# priority: extra s_setprio 0/1 toggle after every 8th MFMA of each 16-MFMA cluster in the GEMM K-loops
# speedup vs baseline: 1.0093x; 1.0093x over previous
; #define PG8_STAGE(bufoff, gbase, voff) do { _Pragma("unroll") for (int _i = 0; _i < 2; ++_i) \
;         __builtin_amdgcn_global_load_lds((const unsigned*)((const char*)(gbase) + (voff)[_i]), (PG8_LAS unsigned*)(lds + (bufoff) + ldsw + _i * 8192), 16, 0, 0); } while (0)
; #define PG8_LDA(dst, b, h) do { _Pragma("unroll") for (int m = 0; m < 4; ++m) _Pragma("unroll") for (int k = 0; k < 2; ++k) dst[m][k] = *(const PG8_LAS bf16x8*)(lds + PG8_SA(b, h) + aoff + m * 2048 + k * 1024); } while (0)
; #define PG8_LDB(dst, b, h) do { _Pragma("unroll") for (int n = 0; n < 2; ++n) _Pragma("unroll") for (int k = 0; k < 2; ++k) dst[n][k] = *(const PG8_LAS bf16x8*)(lds + PG8_SB(b, h) + boff + n * 2048 + k * 1024); } while (0)
; #define PG8_MMA(ai, bj, At, Bt) do { __builtin_amdgcn_s_setprio(1); _Pragma("unroll") for (int m = 0; m < 4; ++m) _Pragma("unroll") for (int n = 0; n < 2; ++n) _Pragma("unroll") for (int k = 0; k < 2; ++k) \
;         acc[ai][bj][m][n] = __builtin_amdgcn_mfma_f32_16x16x32_bf16(Bt[n][k], At[m][k], acc[ai][bj][m][n], 0, 0, 0); __builtin_amdgcn_s_setprio(0); } while (0)
; #define PG8_WAIT_V(n) asm volatile("s_waitcnt vmcnt(" #n ")" ::: "memory")
; #define PG8_WAIT_L(n) asm volatile("s_waitcnt lgkmcnt(" #n ")" ::: "memory")
; #define PG8_BAR __builtin_amdgcn_s_barrier()
; #define PG8_SCHED __builtin_amdgcn_sched_barrier(0)
; template <class Epi, class Sched, bool ALIGN_EPI, bool SP2, int KC>
; __device__ __forceinline__ void gemm_phase(PG8_LAS unsigned char* lds, const Gemm g, const Sched& S, const Epi& E, const int tid) {
;     ...
;             const bool last = (t == nt - 2);
;             const char* a1 = cA + (size_t)(t + 1) * kstep;
;             const char* a2 = last ? nA : cA + (size_t)(t + 2) * kstep; const char* b2 = last ? nB : cB + (size_t)(t + 2) * kstep;
;             const char* a3 = a2 + kstep; const char* b3 = b2 + kstep;
;             if (last && has_next) S.a_ready(nxt);
;             if constexpr (SP2) {
;             PG8_LDB(B0, 0, 0); PG8_LDB(B1, 0, 1); PG8_SCHED; PG8_LDA(At, 0, 0); PG8_STAGE(PG8_SA(1, 1), a1 + hstep, voffA);
;             PG8_WAIT_V(8); PG8_WAIT_L(0); PG8_BAR; PG8_MMA(0, 0, At, B0); PG8_MMA(0, 1, At, B1); PG8_BAR; PG8_SCHED;
;             PG8_LDA(At, 0, 1); PG8_STAGE(PG8_SB(0, 0), b2, voffB); PG8_STAGE(PG8_SB(0, 1), b2 + hstep, voffB); PG8_STAGE(PG8_SA(0, 0), a2, voffA);
.LBB0_44:
	s_add_u32 s24, s22, 0xfffc0080
	s_addc_u32 s25, s23, -1
	s_add_i32 s43, 0, 0x10000
	s_cmp_eq_u32 s42, 12
	s_cselect_b32 s27, s17, s25
	s_cselect_b32 s26, s38, s24
	v_add_u32_e32 v138, s43, v145
	s_cselect_b32 s25, s15, s41
	s_cselect_b32 s24, s39, s40
	s_add_i32 s46, 0, 0x14000
	ds_read_b128 v[148:151], v138
	ds_read_b128 v[152:155], v138 offset:1024
	ds_read_b128 v[156:159], v138 offset:2048
	ds_read_b128 v[160:163], v138 offset:3072
	v_add_u32_e32 v138, s46, v145
	ds_read_b128 v[174:177], v138
	ds_read_b128 v[178:181], v138 offset:1024
	ds_read_b128 v[182:185], v138 offset:2048
	ds_read_b128 v[186:189], v138 offset:3072
	v_lshl_add_u64 v[138:139], s[22:23], 0, v[134:135]
	s_add_i32 m0, s29, 0xc000
	ds_read_b128 v[190:193], v147
	ds_read_b128 v[194:197], v147 offset:1024
	ds_read_b128 v[198:201], v147 offset:2048
	ds_read_b128 v[202:205], v147 offset:3072
	ds_read_b128 v[206:209], v147 offset:4096
	ds_read_b128 v[210:213], v147 offset:5120
	ds_read_b128 v[214:217], v147 offset:6144
	ds_read_b128 v[218:221], v147 offset:7168
	global_load_lds_dwordx4 v[138:139], off
	v_lshl_add_u64 v[138:139], s[22:23], 0, v[136:137]
	s_add_i32 m0, s29, 0xe000
	s_nop 0
	global_load_lds_dwordx4 v[138:139], off
	s_waitcnt vmcnt(8)
	s_waitcnt lgkmcnt(0)
	s_barrier
	s_setprio 1
	s_waitcnt lgkmcnt(0)
	v_mfma_f32_16x16x32_bf16 v[124:127], v[148:151], v[190:193], v[124:127]
	v_mfma_f32_16x16x32_bf16 v[120:123], v[156:159], v[190:193], v[120:123]
	v_mfma_f32_16x16x32_bf16 v[116:119], v[148:151], v[198:201], v[116:119]
	v_mfma_f32_16x16x32_bf16 v[108:111], v[156:159], v[198:201], v[108:111]
	v_mfma_f32_16x16x32_bf16 v[100:103], v[148:151], v[206:209], v[100:103]
	v_mfma_f32_16x16x32_bf16 v[92:95], v[156:159], v[206:209], v[92:95]
	v_mfma_f32_16x16x32_bf16 v[80:83], v[148:151], v[214:217], v[80:83]
	v_mfma_f32_16x16x32_bf16 v[72:75], v[156:159], v[214:217], v[72:75]
	s_setprio 0
	s_setprio 1
	v_mfma_f32_16x16x32_bf16 v[124:127], v[152:155], v[194:197], v[124:127]
	v_mfma_f32_16x16x32_bf16 v[120:123], v[160:163], v[194:197], v[120:123]
	v_mfma_f32_16x16x32_bf16 v[116:119], v[152:155], v[202:205], v[116:119]
	v_mfma_f32_16x16x32_bf16 v[108:111], v[160:163], v[202:205], v[108:111]
	v_mfma_f32_16x16x32_bf16 v[100:103], v[152:155], v[210:213], v[100:103]
	v_mfma_f32_16x16x32_bf16 v[92:95], v[160:163], v[210:213], v[92:95]
	v_mfma_f32_16x16x32_bf16 v[80:83], v[152:155], v[218:221], v[80:83]
	v_mfma_f32_16x16x32_bf16 v[72:75], v[160:163], v[218:221], v[72:75]
	s_setprio 0
	s_setprio 1
	v_mfma_f32_16x16x32_bf16 v[112:115], v[174:177], v[190:193], v[112:115]
	v_mfma_f32_16x16x32_bf16 v[104:107], v[182:185], v[190:193], v[104:107]
	v_mfma_f32_16x16x32_bf16 v[96:99], v[174:177], v[198:201], v[96:99]
	v_mfma_f32_16x16x32_bf16 v[88:91], v[182:185], v[198:201], v[88:91]
	v_mfma_f32_16x16x32_bf16 v[84:87], v[174:177], v[206:209], v[84:87]
	v_mfma_f32_16x16x32_bf16 v[76:79], v[182:185], v[206:209], v[76:79]
	v_mfma_f32_16x16x32_bf16 v[68:71], v[174:177], v[214:217], v[68:71]
	v_mfma_f32_16x16x32_bf16 v[64:67], v[182:185], v[214:217], v[64:67]
	s_setprio 0
	s_setprio 1
	v_mfma_f32_16x16x32_bf16 v[112:115], v[178:181], v[194:197], v[112:115]
	v_mfma_f32_16x16x32_bf16 v[104:107], v[186:189], v[194:197], v[104:107]
	v_mfma_f32_16x16x32_bf16 v[96:99], v[178:181], v[202:205], v[96:99]
	v_mfma_f32_16x16x32_bf16 v[88:91], v[186:189], v[202:205], v[88:91]
	v_mfma_f32_16x16x32_bf16 v[84:87], v[178:181], v[210:213], v[84:87]
	v_mfma_f32_16x16x32_bf16 v[76:79], v[186:189], v[210:213], v[76:79]
	v_mfma_f32_16x16x32_bf16 v[68:71], v[178:181], v[218:221], v[68:71]
	v_mfma_f32_16x16x32_bf16 v[64:67], v[186:189], v[218:221], v[64:67]
	s_setprio 0
	s_barrier
	s_add_i32 s43, s43, s28
	v_lshl_add_u64 v[138:139], s[24:25], 0, v[164:165]
	s_mov_b32 m0, s43
	ds_read_b128 v[190:193], v147 offset:16384
	ds_read_b128 v[194:197], v147 offset:17408
	ds_read_b128 v[198:201], v147 offset:18432
	ds_read_b128 v[202:205], v147 offset:19456
	ds_read_b128 v[206:209], v147 offset:20480
	ds_read_b128 v[210:213], v147 offset:21504
	ds_read_b128 v[214:217], v147 offset:22528
	ds_read_b128 v[218:221], v147 offset:23552
	global_load_lds_dwordx4 v[138:139], off
	s_add_i32 m0, s43, 0x2000
	s_add_u32 s44, s24, 0x40000
	v_lshl_add_u64 v[222:223], s[24:25], 0, v[128:129]
	s_addc_u32 s45, s25, 0
	s_add_i32 s43, s46, s28
	global_load_lds_dwordx4 v[222:223], off
	v_lshl_add_u64 v[234:235], s[44:45], 0, v[164:165]
	s_mov_b32 m0, s43
	v_lshl_add_u64 v[236:237], s[26:27], 0, v[130:131]
	global_load_lds_dwordx4 v[234:235], off
	v_lshl_add_u64 v[234:235], s[44:45], 0, v[128:129]
	s_add_i32 m0, s43, 0x2000
	s_nop 0
	global_load_lds_dwordx4 v[234:235], off
	v_lshl_add_u64 v[234:235], s[26:27], 0, v[132:133]
	s_mov_b32 m0, s29
	s_nop 0
	global_load_lds_dwordx4 v[234:235], off
	s_mov_b32 m0, s30
	s_nop 0
	global_load_lds_dwordx4 v[236:237], off
	s_waitcnt vmcnt(8)
	s_waitcnt lgkmcnt(0)
	s_barrier
; #define PG8_STAGE(bufoff, gbase, voff) do { _Pragma("unroll") for (int _i = 0; _i < 2; ++_i) \
;         __builtin_amdgcn_global_load_lds((const unsigned*)((const char*)(gbase) + (voff)[_i]), (PG8_LAS unsigned*)(lds + (bufoff) + ldsw + _i * 8192), 16, 0, 0); } while (0)
; #define PG8_LDA(dst, b, h) do { _Pragma("unroll") for (int m = 0; m < 4; ++m) _Pragma("unroll") for (int k = 0; k < 2; ++k) dst[m][k] = *(const PG8_LAS bf16x8*)(lds + PG8_SA(b, h) + aoff + m * 2048 + k * 1024); } while (0)
; #define PG8_LDB(dst, b, h) do { _Pragma("unroll") for (int n = 0; n < 2; ++n) _Pragma("unroll") for (int k = 0; k < 2; ++k) dst[n][k] = *(const PG8_LAS bf16x8*)(lds + PG8_SB(b, h) + boff + n * 2048 + k * 1024); } while (0)
; #define PG8_MMA(ai, bj, At, Bt) do { __builtin_amdgcn_s_setprio(1); _Pragma("unroll") for (int m = 0; m < 4; ++m) _Pragma("unroll") for (int n = 0; n < 2; ++n) _Pragma("unroll") for (int k = 0; k < 2; ++k) \
;         acc[ai][bj][m][n] = __builtin_amdgcn_mfma_f32_16x16x32_bf16(Bt[n][k], At[m][k], acc[ai][bj][m][n], 0, 0, 0); __builtin_amdgcn_s_setprio(0); } while (0)
; #define PG8_WAIT_V(n) asm volatile("s_waitcnt vmcnt(" #n ")" ::: "memory")
; #define PG8_WAIT_L(n) asm volatile("s_waitcnt lgkmcnt(" #n ")" ::: "memory")
; #define PG8_BAR __builtin_amdgcn_s_barrier()
; #define PG8_SCHED __builtin_amdgcn_sched_barrier(0)
; template <class Epi, class Sched, bool ALIGN_EPI, bool SP2, int KC>
; __device__ __forceinline__ void gemm_phase(PG8_LAS unsigned char* lds, const Gemm g, const Sched& S, const Epi& E, const int tid) {
;     ...
;             PG8_WAIT_V(8); PG8_WAIT_L(0); PG8_BAR; PG8_MMA(1, 0, At, B0); PG8_MMA(1, 1, At, B1); PG8_BAR; PG8_SCHED;
;             PG8_LDB(B0, 1, 0); PG8_LDB(B1, 1, 1); PG8_SCHED; PG8_LDA(At, 1, 0); PG8_STAGE(PG8_SA(0, 1), a2 + hstep, voffA);
;             PG8_WAIT_V(8); PG8_WAIT_L(0); PG8_BAR; PG8_MMA(0, 0, At, B0); PG8_MMA(0, 1, At, B1); PG8_BAR; PG8_SCHED;
	s_setprio 1
	s_waitcnt lgkmcnt(0)
	v_mfma_f32_16x16x32_bf16 v[60:63], v[148:151], v[190:193], v[60:63]
	v_mfma_f32_16x16x32_bf16 v[56:59], v[156:159], v[190:193], v[56:59]
	v_mfma_f32_16x16x32_bf16 v[52:55], v[148:151], v[198:201], v[52:55]
	v_mfma_f32_16x16x32_bf16 v[44:47], v[156:159], v[198:201], v[44:47]
	v_mfma_f32_16x16x32_bf16 v[36:39], v[148:151], v[206:209], v[36:39]
	v_mfma_f32_16x16x32_bf16 v[28:31], v[156:159], v[206:209], v[28:31]
	v_mfma_f32_16x16x32_bf16 v[20:23], v[148:151], v[214:217], v[20:23]
	v_mfma_f32_16x16x32_bf16 v[12:15], v[156:159], v[214:217], v[12:15]
	s_setprio 0
	s_setprio 1
	v_mfma_f32_16x16x32_bf16 v[60:63], v[152:155], v[194:197], v[60:63]
	v_mfma_f32_16x16x32_bf16 v[56:59], v[160:163], v[194:197], v[56:59]
	v_mfma_f32_16x16x32_bf16 v[52:55], v[152:155], v[202:205], v[52:55]
	v_mfma_f32_16x16x32_bf16 v[44:47], v[160:163], v[202:205], v[44:47]
	v_mfma_f32_16x16x32_bf16 v[36:39], v[152:155], v[210:213], v[36:39]
	v_mfma_f32_16x16x32_bf16 v[28:31], v[160:163], v[210:213], v[28:31]
	v_mfma_f32_16x16x32_bf16 v[20:23], v[152:155], v[218:221], v[20:23]
	v_mfma_f32_16x16x32_bf16 v[12:15], v[160:163], v[218:221], v[12:15]
	s_setprio 0
	s_setprio 1
	v_mfma_f32_16x16x32_bf16 v[48:51], v[174:177], v[190:193], v[48:51]
	v_mfma_f32_16x16x32_bf16 v[40:43], v[182:185], v[190:193], v[40:43]
	v_mfma_f32_16x16x32_bf16 v[32:35], v[174:177], v[198:201], v[32:35]
	v_mfma_f32_16x16x32_bf16 v[24:27], v[182:185], v[198:201], v[24:27]
	v_mfma_f32_16x16x32_bf16 v[16:19], v[174:177], v[206:209], v[16:19]
	v_mfma_f32_16x16x32_bf16 v[8:11], v[182:185], v[206:209], v[8:11]
	v_mfma_f32_16x16x32_bf16 v[4:7], v[174:177], v[214:217], v[4:7]
	v_mfma_f32_16x16x32_bf16 v[0:3], v[182:185], v[214:217], v[0:3]
	s_setprio 0
	s_setprio 1
	v_mfma_f32_16x16x32_bf16 v[48:51], v[178:181], v[194:197], v[48:51]
	v_mfma_f32_16x16x32_bf16 v[40:43], v[186:189], v[194:197], v[40:43]
	v_mfma_f32_16x16x32_bf16 v[32:35], v[178:181], v[202:205], v[32:35]
	v_mfma_f32_16x16x32_bf16 v[24:27], v[186:189], v[202:205], v[24:27]
	v_mfma_f32_16x16x32_bf16 v[16:19], v[178:181], v[210:213], v[16:19]
	v_mfma_f32_16x16x32_bf16 v[8:11], v[186:189], v[210:213], v[8:11]
	v_mfma_f32_16x16x32_bf16 v[4:7], v[178:181], v[218:221], v[4:7]
	v_mfma_f32_16x16x32_bf16 v[0:3], v[186:189], v[218:221], v[0:3]
	s_setprio 0
	s_barrier
	s_add_i32 s43, 0, 0x18000
	s_add_i32 s44, 0, 0x1c000
	v_add_u32_e32 v160, s43, v145
	v_add_u32_e32 v171, s44, v145
	ds_read_b128 v[148:151], v160
	ds_read_b128 v[152:155], v160 offset:1024
	ds_read_b128 v[156:159], v160 offset:2048
	ds_read_b128 v[160:163], v160 offset:3072
	ds_read_b128 v[174:177], v171
	ds_read_b128 v[178:181], v171 offset:1024
	ds_read_b128 v[182:185], v171 offset:2048
	ds_read_b128 v[186:189], v171 offset:3072
	s_add_u32 s26, s26, 0x40000
	s_addc_u32 s27, s27, 0
	s_mov_b32 m0, s31
	v_lshl_add_u64 v[238:239], s[26:27], 0, v[132:133]
	ds_read_b128 v[190:193], v147 offset:32768
	ds_read_b128 v[194:197], v147 offset:33792
	ds_read_b128 v[198:201], v147 offset:34816
	ds_read_b128 v[202:205], v147 offset:35840
	ds_read_b128 v[206:209], v147 offset:36864
	ds_read_b128 v[210:213], v147 offset:37888
	ds_read_b128 v[214:217], v147 offset:38912
	ds_read_b128 v[218:221], v147 offset:39936
	global_load_lds_dwordx4 v[238:239], off
	v_lshl_add_u64 v[238:239], s[26:27], 0, v[130:131]
	s_mov_b32 m0, s34
	s_nop 0
	global_load_lds_dwordx4 v[238:239], off
	s_waitcnt vmcnt(8)
	s_waitcnt lgkmcnt(0)
	s_barrier
	s_setprio 1
	s_waitcnt lgkmcnt(0)
	v_mfma_f32_16x16x32_bf16 v[124:127], v[148:151], v[190:193], v[124:127]
	v_mfma_f32_16x16x32_bf16 v[120:123], v[156:159], v[190:193], v[120:123]
	v_mfma_f32_16x16x32_bf16 v[116:119], v[148:151], v[198:201], v[116:119]
	v_mfma_f32_16x16x32_bf16 v[108:111], v[156:159], v[198:201], v[108:111]
	v_mfma_f32_16x16x32_bf16 v[100:103], v[148:151], v[206:209], v[100:103]
	v_mfma_f32_16x16x32_bf16 v[92:95], v[156:159], v[206:209], v[92:95]
	v_mfma_f32_16x16x32_bf16 v[80:83], v[148:151], v[214:217], v[80:83]
	v_mfma_f32_16x16x32_bf16 v[72:75], v[156:159], v[214:217], v[72:75]
	s_setprio 0
	s_setprio 1
	v_mfma_f32_16x16x32_bf16 v[124:127], v[152:155], v[194:197], v[124:127]
	v_mfma_f32_16x16x32_bf16 v[120:123], v[160:163], v[194:197], v[120:123]
	v_mfma_f32_16x16x32_bf16 v[116:119], v[152:155], v[202:205], v[116:119]
	v_mfma_f32_16x16x32_bf16 v[108:111], v[160:163], v[202:205], v[108:111]
	v_mfma_f32_16x16x32_bf16 v[100:103], v[152:155], v[210:213], v[100:103]
	v_mfma_f32_16x16x32_bf16 v[92:95], v[160:163], v[210:213], v[92:95]
	v_mfma_f32_16x16x32_bf16 v[80:83], v[152:155], v[218:221], v[80:83]
	v_mfma_f32_16x16x32_bf16 v[72:75], v[160:163], v[218:221], v[72:75]
	s_setprio 0
	s_setprio 1
	v_mfma_f32_16x16x32_bf16 v[112:115], v[174:177], v[190:193], v[112:115]
	v_mfma_f32_16x16x32_bf16 v[104:107], v[182:185], v[190:193], v[104:107]
	v_mfma_f32_16x16x32_bf16 v[96:99], v[174:177], v[198:201], v[96:99]
	v_mfma_f32_16x16x32_bf16 v[88:91], v[182:185], v[198:201], v[88:91]
	v_mfma_f32_16x16x32_bf16 v[84:87], v[174:177], v[206:209], v[84:87]
	v_mfma_f32_16x16x32_bf16 v[76:79], v[182:185], v[206:209], v[76:79]
	v_mfma_f32_16x16x32_bf16 v[68:71], v[174:177], v[214:217], v[68:71]
	v_mfma_f32_16x16x32_bf16 v[64:67], v[182:185], v[214:217], v[64:67]
	s_setprio 0
	s_setprio 1
	v_mfma_f32_16x16x32_bf16 v[112:115], v[178:181], v[194:197], v[112:115]
	v_mfma_f32_16x16x32_bf16 v[104:107], v[186:189], v[194:197], v[104:107]
	v_mfma_f32_16x16x32_bf16 v[96:99], v[178:181], v[202:205], v[96:99]
	v_mfma_f32_16x16x32_bf16 v[88:91], v[186:189], v[202:205], v[88:91]
	v_mfma_f32_16x16x32_bf16 v[84:87], v[178:181], v[210:213], v[84:87]
	v_mfma_f32_16x16x32_bf16 v[76:79], v[186:189], v[210:213], v[76:79]
	v_mfma_f32_16x16x32_bf16 v[68:71], v[178:181], v[218:221], v[68:71]
	v_mfma_f32_16x16x32_bf16 v[64:67], v[186:189], v[218:221], v[64:67]
	s_setprio 0
	s_barrier
; #define PG8_STAGE(bufoff, gbase, voff) do { _Pragma("unroll") for (int _i = 0; _i < 2; ++_i) \
;         __builtin_amdgcn_global_load_lds((const unsigned*)((const char*)(gbase) + (voff)[_i]), (PG8_LAS unsigned*)(lds + (bufoff) + ldsw + _i * 8192), 16, 0, 0); } while (0)
; #define PG8_LDA(dst, b, h) do { _Pragma("unroll") for (int m = 0; m < 4; ++m) _Pragma("unroll") for (int k = 0; k < 2; ++k) dst[m][k] = *(const PG8_LAS bf16x8*)(lds + PG8_SA(b, h) + aoff + m * 2048 + k * 1024); } while (0)
; #define PG8_MMA(ai, bj, At, Bt) do { __builtin_amdgcn_s_setprio(1); _Pragma("unroll") for (int m = 0; m < 4; ++m) _Pragma("unroll") for (int n = 0; n < 2; ++n) _Pragma("unroll") for (int k = 0; k < 2; ++k) \
;         acc[ai][bj][m][n] = __builtin_amdgcn_mfma_f32_16x16x32_bf16(Bt[n][k], At[m][k], acc[ai][bj][m][n], 0, 0, 0); __builtin_amdgcn_s_setprio(0); } while (0)
; #define PG8_WAIT_V(n) asm volatile("s_waitcnt vmcnt(" #n ")" ::: "memory")
; #define PG8_WAIT_L(n) asm volatile("s_waitcnt lgkmcnt(" #n ")" ::: "memory")
; #define PG8_BAR __builtin_amdgcn_s_barrier()
; #define PG8_SCHED __builtin_amdgcn_sched_barrier(0)
; template <class Epi, class Sched, bool ALIGN_EPI, bool SP2, int KC>
; __device__ __forceinline__ void gemm_phase(PG8_LAS unsigned char* lds, const Gemm g, const Sched& S, const Epi& E, const int tid) {
;     ...
;             PG8_LDA(At, 1, 1); PG8_STAGE(PG8_SB(1, 0), b3, voffB); PG8_STAGE(PG8_SB(1, 1), b3 + hstep, voffB); PG8_STAGE(PG8_SA(1, 0), a3, voffA);
;             PG8_WAIT_V(8); PG8_WAIT_L(0); PG8_BAR; PG8_MMA(1, 0, At, B0); PG8_MMA(1, 1, At, B1); PG8_BAR; PG8_SCHED;
	s_add_i32 s26, s43, s28
	v_lshl_add_u64 v[138:139], v[138:139], 0, s[86:87]
	s_mov_b32 m0, s26
	ds_read_b128 v[190:193], v147 offset:49152
	ds_read_b128 v[194:197], v147 offset:50176
	ds_read_b128 v[198:201], v147 offset:51200
	ds_read_b128 v[202:205], v147 offset:52224
	ds_read_b128 v[206:209], v147 offset:53248
	ds_read_b128 v[210:213], v147 offset:54272
	ds_read_b128 v[214:217], v147 offset:55296
	ds_read_b128 v[218:221], v147 offset:56320
	global_load_lds_dwordx4 v[138:139], off
	s_add_i32 m0, s26, 0x2000
	s_add_u32 s24, s24, 0x40080
	v_lshl_add_u64 v[138:139], v[222:223], 0, s[86:87]
	s_addc_u32 s25, s25, 0
	s_add_i32 s26, s44, s28
	global_load_lds_dwordx4 v[138:139], off
	v_lshl_add_u64 v[138:139], s[24:25], 0, v[164:165]
	s_mov_b32 m0, s26
	s_nop 0
	global_load_lds_dwordx4 v[138:139], off
	v_lshl_add_u64 v[138:139], s[24:25], 0, v[128:129]
	s_add_i32 m0, s26, 0x2000
	s_nop 0
	global_load_lds_dwordx4 v[138:139], off
	v_lshl_add_u64 v[138:139], v[234:235], 0, s[86:87]
	s_mov_b32 m0, s35
	s_nop 0
	global_load_lds_dwordx4 v[138:139], off
	v_lshl_add_u64 v[138:139], v[236:237], 0, s[86:87]
	s_mov_b32 m0, s36
	s_nop 0
	global_load_lds_dwordx4 v[138:139], off
	s_waitcnt vmcnt(8)
	s_waitcnt lgkmcnt(0)
	s_barrier
	s_setprio 1
	s_waitcnt lgkmcnt(0)
	v_mfma_f32_16x16x32_bf16 v[60:63], v[148:151], v[190:193], v[60:63]
	v_mfma_f32_16x16x32_bf16 v[56:59], v[156:159], v[190:193], v[56:59]
	v_mfma_f32_16x16x32_bf16 v[52:55], v[148:151], v[198:201], v[52:55]
	v_mfma_f32_16x16x32_bf16 v[44:47], v[156:159], v[198:201], v[44:47]
	v_mfma_f32_16x16x32_bf16 v[36:39], v[148:151], v[206:209], v[36:39]
	v_mfma_f32_16x16x32_bf16 v[28:31], v[156:159], v[206:209], v[28:31]
	v_mfma_f32_16x16x32_bf16 v[20:23], v[148:151], v[214:217], v[20:23]
	v_mfma_f32_16x16x32_bf16 v[12:15], v[156:159], v[214:217], v[12:15]
	s_setprio 0
	s_setprio 1
	v_mfma_f32_16x16x32_bf16 v[60:63], v[152:155], v[194:197], v[60:63]
	v_mfma_f32_16x16x32_bf16 v[56:59], v[160:163], v[194:197], v[56:59]
	v_mfma_f32_16x16x32_bf16 v[52:55], v[152:155], v[202:205], v[52:55]
	v_mfma_f32_16x16x32_bf16 v[44:47], v[160:163], v[202:205], v[44:47]
	v_mfma_f32_16x16x32_bf16 v[36:39], v[152:155], v[210:213], v[36:39]
	v_mfma_f32_16x16x32_bf16 v[28:31], v[160:163], v[210:213], v[28:31]
	v_mfma_f32_16x16x32_bf16 v[20:23], v[152:155], v[218:221], v[20:23]
	v_mfma_f32_16x16x32_bf16 v[12:15], v[160:163], v[218:221], v[12:15]
	s_setprio 0
	s_setprio 1
	v_mfma_f32_16x16x32_bf16 v[48:51], v[174:177], v[190:193], v[48:51]
	v_mfma_f32_16x16x32_bf16 v[40:43], v[182:185], v[190:193], v[40:43]
	v_mfma_f32_16x16x32_bf16 v[32:35], v[174:177], v[198:201], v[32:35]
	v_mfma_f32_16x16x32_bf16 v[24:27], v[182:185], v[198:201], v[24:27]
	v_mfma_f32_16x16x32_bf16 v[16:19], v[174:177], v[206:209], v[16:19]
	v_mfma_f32_16x16x32_bf16 v[8:11], v[182:185], v[206:209], v[8:11]
	v_mfma_f32_16x16x32_bf16 v[4:7], v[174:177], v[214:217], v[4:7]
	v_mfma_f32_16x16x32_bf16 v[0:3], v[182:185], v[214:217], v[0:3]
	s_setprio 0
	s_setprio 1
	v_mfma_f32_16x16x32_bf16 v[48:51], v[178:181], v[194:197], v[48:51]
	v_mfma_f32_16x16x32_bf16 v[40:43], v[186:189], v[194:197], v[40:43]
	v_mfma_f32_16x16x32_bf16 v[32:35], v[178:181], v[202:205], v[32:35]
	v_mfma_f32_16x16x32_bf16 v[24:27], v[186:189], v[202:205], v[24:27]
	v_mfma_f32_16x16x32_bf16 v[16:19], v[178:181], v[210:213], v[16:19]
	v_mfma_f32_16x16x32_bf16 v[8:11], v[186:189], v[210:213], v[8:11]
	v_mfma_f32_16x16x32_bf16 v[4:7], v[178:181], v[218:221], v[4:7]
	v_mfma_f32_16x16x32_bf16 v[0:3], v[186:189], v[218:221], v[0:3]
	s_setprio 0
	s_barrier
	s_add_i32 s42, s42, 2
	s_add_u32 s22, s22, 0x100
	s_addc_u32 s23, s23, 0
	s_add_u32 s40, s40, 0x100
	s_addc_u32 s41, s41, 0
	s_cmp_gt_u32 s42, 13
	s_cbranch_scc0 .LBB0_44
	s_and_b64 vcc, exec, s[10:11]
	s_cbranch_vccz .LBB0_47
	s_barrier

; #define PG8_STAGE(bufoff, gbase, voff) do { _Pragma("unroll") for (int _i = 0; _i < 2; ++_i) \
;         __builtin_amdgcn_global_load_lds((const unsigned*)((const char*)(gbase) + (voff)[_i]), (PG8_LAS unsigned*)(lds + (bufoff) + ldsw + _i * 8192), 16, 0, 0); } while (0)
; #define PG8_LDA(dst, b, h) do { _Pragma("unroll") for (int m = 0; m < 4; ++m) _Pragma("unroll") for (int k = 0; k < 2; ++k) dst[m][k] = *(const PG8_LAS bf16x8*)(lds + PG8_SA(b, h) + aoff + m * 2048 + k * 1024); } while (0)
; #define PG8_LDB(dst, b, h) do { _Pragma("unroll") for (int n = 0; n < 2; ++n) _Pragma("unroll") for (int k = 0; k < 2; ++k) dst[n][k] = *(const PG8_LAS bf16x8*)(lds + PG8_SB(b, h) + boff + n * 2048 + k * 1024); } while (0)
; #define PG8_MMA(ai, bj, At, Bt) do { __builtin_amdgcn_s_setprio(1); _Pragma("unroll") for (int m = 0; m < 4; ++m) _Pragma("unroll") for (int n = 0; n < 2; ++n) _Pragma("unroll") for (int k = 0; k < 2; ++k) \
;         acc[ai][bj][m][n] = __builtin_amdgcn_mfma_f32_16x16x32_bf16(Bt[n][k], At[m][k], acc[ai][bj][m][n], 0, 0, 0); __builtin_amdgcn_s_setprio(0); } while (0)
; #define PG8_WAIT_V(n) asm volatile("s_waitcnt vmcnt(" #n ")" ::: "memory")
; #define PG8_WAIT_L(n) asm volatile("s_waitcnt lgkmcnt(" #n ")" ::: "memory")
; #define PG8_BAR __builtin_amdgcn_s_barrier()
; #define PG8_SCHED __builtin_amdgcn_sched_barrier(0)
; template <class Epi, class Sched, bool ALIGN_EPI, bool SP2, int KC>
; __device__ __forceinline__ void gemm_phase(PG8_LAS unsigned char* lds, const Gemm g, const Sched& S, const Epi& E, const int tid) {
;     ...
;             const bool last = (t == nt - 2);
;             const char* a1 = cA + (size_t)(t + 1) * kstep;
;             const char* a2 = last ? nA : cA + (size_t)(t + 2) * kstep; const char* b2 = last ? nB : cB + (size_t)(t + 2) * kstep;
;             const char* a3 = a2 + kstep; const char* b3 = b2 + kstep;
;             if (last && has_next) S.a_ready(nxt);
;             if constexpr (SP2) {
;             PG8_LDB(B0, 0, 0); PG8_LDB(B1, 0, 1); PG8_SCHED; PG8_LDA(At, 0, 0); PG8_STAGE(PG8_SA(1, 1), a1 + hstep, voffA);
;             PG8_WAIT_V(8); PG8_WAIT_L(0); PG8_BAR; PG8_MMA(0, 0, At, B0); PG8_MMA(0, 1, At, B1); PG8_BAR; PG8_SCHED;
;             PG8_LDA(At, 0, 1); PG8_STAGE(PG8_SB(0, 0), b2, voffB); PG8_STAGE(PG8_SB(0, 1), b2 + hstep, voffB); PG8_STAGE(PG8_SA(0, 0), a2, voffA);
.LBB0_66:
	s_add_u32 s24, s22, 0xfffc0080
	s_addc_u32 s25, s23, -1
	s_add_i32 s43, 0, 0x10000
	s_cmp_eq_u32 s42, 12
	s_cselect_b32 s27, s17, s25
	s_cselect_b32 s26, s38, s24
	v_add_u32_e32 v138, s43, v141
	s_cselect_b32 s25, s15, s41
	s_cselect_b32 s24, s39, s40
	s_add_i32 s46, 0, 0x14000
	ds_read_b128 v[146:149], v138
	ds_read_b128 v[150:153], v138 offset:1024
	ds_read_b128 v[154:157], v138 offset:2048
	ds_read_b128 v[158:161], v138 offset:3072
	v_add_u32_e32 v138, s46, v141
	ds_read_b128 v[174:177], v138
	ds_read_b128 v[178:181], v138 offset:1024
	ds_read_b128 v[182:185], v138 offset:2048
	ds_read_b128 v[186:189], v138 offset:3072
	v_lshl_add_u64 v[138:139], s[22:23], 0, v[134:135]
	s_add_i32 m0, s29, 0xc000
	ds_read_b128 v[190:193], v142
	ds_read_b128 v[194:197], v142 offset:1024
	ds_read_b128 v[198:201], v142 offset:2048
	ds_read_b128 v[202:205], v142 offset:3072
	ds_read_b128 v[206:209], v142 offset:4096
	ds_read_b128 v[210:213], v142 offset:5120
	ds_read_b128 v[214:217], v142 offset:6144
	ds_read_b128 v[218:221], v142 offset:7168
	global_load_lds_dwordx4 v[138:139], off
	v_lshl_add_u64 v[138:139], s[22:23], 0, v[136:137]
	s_add_i32 m0, s29, 0xe000
	s_nop 0
	global_load_lds_dwordx4 v[138:139], off
	s_waitcnt vmcnt(8)
	s_waitcnt lgkmcnt(0)
	s_barrier
	s_setprio 1
	s_waitcnt lgkmcnt(0)
	v_mfma_f32_16x16x32_bf16 v[124:127], v[146:149], v[190:193], v[124:127]
	v_mfma_f32_16x16x32_bf16 v[120:123], v[154:157], v[190:193], v[120:123]
	v_mfma_f32_16x16x32_bf16 v[116:119], v[146:149], v[198:201], v[116:119]
	v_mfma_f32_16x16x32_bf16 v[108:111], v[154:157], v[198:201], v[108:111]
	v_mfma_f32_16x16x32_bf16 v[100:103], v[146:149], v[206:209], v[100:103]
	v_mfma_f32_16x16x32_bf16 v[92:95], v[154:157], v[206:209], v[92:95]
	v_mfma_f32_16x16x32_bf16 v[80:83], v[146:149], v[214:217], v[80:83]
	v_mfma_f32_16x16x32_bf16 v[72:75], v[154:157], v[214:217], v[72:75]
	s_setprio 0
	s_setprio 1
	v_mfma_f32_16x16x32_bf16 v[124:127], v[150:153], v[194:197], v[124:127]
	v_mfma_f32_16x16x32_bf16 v[120:123], v[158:161], v[194:197], v[120:123]
	v_mfma_f32_16x16x32_bf16 v[116:119], v[150:153], v[202:205], v[116:119]
	v_mfma_f32_16x16x32_bf16 v[108:111], v[158:161], v[202:205], v[108:111]
	v_mfma_f32_16x16x32_bf16 v[100:103], v[150:153], v[210:213], v[100:103]
	v_mfma_f32_16x16x32_bf16 v[92:95], v[158:161], v[210:213], v[92:95]
	v_mfma_f32_16x16x32_bf16 v[80:83], v[150:153], v[218:221], v[80:83]
	v_mfma_f32_16x16x32_bf16 v[72:75], v[158:161], v[218:221], v[72:75]
	s_setprio 0
	s_setprio 1
	v_mfma_f32_16x16x32_bf16 v[112:115], v[174:177], v[190:193], v[112:115]
	v_mfma_f32_16x16x32_bf16 v[104:107], v[182:185], v[190:193], v[104:107]
	v_mfma_f32_16x16x32_bf16 v[96:99], v[174:177], v[198:201], v[96:99]
	v_mfma_f32_16x16x32_bf16 v[88:91], v[182:185], v[198:201], v[88:91]
	v_mfma_f32_16x16x32_bf16 v[84:87], v[174:177], v[206:209], v[84:87]
	v_mfma_f32_16x16x32_bf16 v[76:79], v[182:185], v[206:209], v[76:79]
	v_mfma_f32_16x16x32_bf16 v[68:71], v[174:177], v[214:217], v[68:71]
	v_mfma_f32_16x16x32_bf16 v[64:67], v[182:185], v[214:217], v[64:67]
	s_setprio 0
	s_setprio 1
	v_mfma_f32_16x16x32_bf16 v[112:115], v[178:181], v[194:197], v[112:115]
	v_mfma_f32_16x16x32_bf16 v[104:107], v[186:189], v[194:197], v[104:107]
	v_mfma_f32_16x16x32_bf16 v[96:99], v[178:181], v[202:205], v[96:99]
	v_mfma_f32_16x16x32_bf16 v[88:91], v[186:189], v[202:205], v[88:91]
	v_mfma_f32_16x16x32_bf16 v[84:87], v[178:181], v[210:213], v[84:87]
	v_mfma_f32_16x16x32_bf16 v[76:79], v[186:189], v[210:213], v[76:79]
	v_mfma_f32_16x16x32_bf16 v[68:71], v[178:181], v[218:221], v[68:71]
	v_mfma_f32_16x16x32_bf16 v[64:67], v[186:189], v[218:221], v[64:67]
	s_setprio 0
	s_barrier
	s_add_i32 s43, s43, s28
	v_lshl_add_u64 v[138:139], s[24:25], 0, v[164:165]
	s_mov_b32 m0, s43
	ds_read_b128 v[190:193], v142 offset:16384
	ds_read_b128 v[194:197], v142 offset:17408
	ds_read_b128 v[198:201], v142 offset:18432
	ds_read_b128 v[202:205], v142 offset:19456
	ds_read_b128 v[206:209], v142 offset:20480
	ds_read_b128 v[210:213], v142 offset:21504
	ds_read_b128 v[214:217], v142 offset:22528
	ds_read_b128 v[218:221], v142 offset:23552
	global_load_lds_dwordx4 v[138:139], off
	s_add_i32 m0, s43, 0x2000
	s_add_u32 s44, s24, 0x40000
	v_lshl_add_u64 v[162:163], s[24:25], 0, v[128:129]
	s_addc_u32 s45, s25, 0
	s_add_i32 s43, s46, s28
	global_load_lds_dwordx4 v[162:163], off
	v_lshl_add_u64 v[222:223], s[44:45], 0, v[164:165]
	s_mov_b32 m0, s43
	v_lshl_add_u64 v[234:235], s[26:27], 0, v[130:131]
	global_load_lds_dwordx4 v[222:223], off
	v_lshl_add_u64 v[222:223], s[44:45], 0, v[128:129]
	s_add_i32 m0, s43, 0x2000
	s_nop 0
	global_load_lds_dwordx4 v[222:223], off
	v_lshl_add_u64 v[222:223], s[26:27], 0, v[132:133]
	s_mov_b32 m0, s29
	s_nop 0
	global_load_lds_dwordx4 v[222:223], off
	s_mov_b32 m0, s30
	s_nop 0
	global_load_lds_dwordx4 v[234:235], off
	s_waitcnt vmcnt(8)
	s_waitcnt lgkmcnt(0)
	s_barrier
; #define PG8_STAGE(bufoff, gbase, voff) do { _Pragma("unroll") for (int _i = 0; _i < 2; ++_i) \
;         __builtin_amdgcn_global_load_lds((const unsigned*)((const char*)(gbase) + (voff)[_i]), (PG8_LAS unsigned*)(lds + (bufoff) + ldsw + _i * 8192), 16, 0, 0); } while (0)
; #define PG8_LDA(dst, b, h) do { _Pragma("unroll") for (int m = 0; m < 4; ++m) _Pragma("unroll") for (int k = 0; k < 2; ++k) dst[m][k] = *(const PG8_LAS bf16x8*)(lds + PG8_SA(b, h) + aoff + m * 2048 + k * 1024); } while (0)
; #define PG8_LDB(dst, b, h) do { _Pragma("unroll") for (int n = 0; n < 2; ++n) _Pragma("unroll") for (int k = 0; k < 2; ++k) dst[n][k] = *(const PG8_LAS bf16x8*)(lds + PG8_SB(b, h) + boff + n * 2048 + k * 1024); } while (0)
; #define PG8_MMA(ai, bj, At, Bt) do { __builtin_amdgcn_s_setprio(1); _Pragma("unroll") for (int m = 0; m < 4; ++m) _Pragma("unroll") for (int n = 0; n < 2; ++n) _Pragma("unroll") for (int k = 0; k < 2; ++k) \
;         acc[ai][bj][m][n] = __builtin_amdgcn_mfma_f32_16x16x32_bf16(Bt[n][k], At[m][k], acc[ai][bj][m][n], 0, 0, 0); __builtin_amdgcn_s_setprio(0); } while (0)
; #define PG8_WAIT_V(n) asm volatile("s_waitcnt vmcnt(" #n ")" ::: "memory")
; #define PG8_WAIT_L(n) asm volatile("s_waitcnt lgkmcnt(" #n ")" ::: "memory")
; #define PG8_BAR __builtin_amdgcn_s_barrier()
; #define PG8_SCHED __builtin_amdgcn_sched_barrier(0)
; template <class Epi, class Sched, bool ALIGN_EPI, bool SP2, int KC>
; __device__ __forceinline__ void gemm_phase(PG8_LAS unsigned char* lds, const Gemm g, const Sched& S, const Epi& E, const int tid) {
;     ...
;             PG8_WAIT_V(8); PG8_WAIT_L(0); PG8_BAR; PG8_MMA(1, 0, At, B0); PG8_MMA(1, 1, At, B1); PG8_BAR; PG8_SCHED;
;             PG8_LDB(B0, 1, 0); PG8_LDB(B1, 1, 1); PG8_SCHED; PG8_LDA(At, 1, 0); PG8_STAGE(PG8_SA(0, 1), a2 + hstep, voffA);
;             PG8_WAIT_V(8); PG8_WAIT_L(0); PG8_BAR; PG8_MMA(0, 0, At, B0); PG8_MMA(0, 1, At, B1); PG8_BAR; PG8_SCHED;
	s_setprio 1
	s_waitcnt lgkmcnt(0)
	v_mfma_f32_16x16x32_bf16 v[60:63], v[146:149], v[190:193], v[60:63]
	v_mfma_f32_16x16x32_bf16 v[56:59], v[154:157], v[190:193], v[56:59]
	v_mfma_f32_16x16x32_bf16 v[52:55], v[146:149], v[198:201], v[52:55]
	v_mfma_f32_16x16x32_bf16 v[44:47], v[154:157], v[198:201], v[44:47]
	v_mfma_f32_16x16x32_bf16 v[36:39], v[146:149], v[206:209], v[36:39]
	v_mfma_f32_16x16x32_bf16 v[28:31], v[154:157], v[206:209], v[28:31]
	v_mfma_f32_16x16x32_bf16 v[20:23], v[146:149], v[214:217], v[20:23]
	v_mfma_f32_16x16x32_bf16 v[12:15], v[154:157], v[214:217], v[12:15]
	s_setprio 0
	s_setprio 1
	v_mfma_f32_16x16x32_bf16 v[60:63], v[150:153], v[194:197], v[60:63]
	v_mfma_f32_16x16x32_bf16 v[56:59], v[158:161], v[194:197], v[56:59]
	v_mfma_f32_16x16x32_bf16 v[52:55], v[150:153], v[202:205], v[52:55]
	v_mfma_f32_16x16x32_bf16 v[44:47], v[158:161], v[202:205], v[44:47]
	v_mfma_f32_16x16x32_bf16 v[36:39], v[150:153], v[210:213], v[36:39]
	v_mfma_f32_16x16x32_bf16 v[28:31], v[158:161], v[210:213], v[28:31]
	v_mfma_f32_16x16x32_bf16 v[20:23], v[150:153], v[218:221], v[20:23]
	v_mfma_f32_16x16x32_bf16 v[12:15], v[158:161], v[218:221], v[12:15]
	s_setprio 0
	s_setprio 1
	v_mfma_f32_16x16x32_bf16 v[48:51], v[174:177], v[190:193], v[48:51]
	v_mfma_f32_16x16x32_bf16 v[40:43], v[182:185], v[190:193], v[40:43]
	v_mfma_f32_16x16x32_bf16 v[32:35], v[174:177], v[198:201], v[32:35]
	v_mfma_f32_16x16x32_bf16 v[24:27], v[182:185], v[198:201], v[24:27]
	v_mfma_f32_16x16x32_bf16 v[16:19], v[174:177], v[206:209], v[16:19]
	v_mfma_f32_16x16x32_bf16 v[8:11], v[182:185], v[206:209], v[8:11]
	v_mfma_f32_16x16x32_bf16 v[4:7], v[174:177], v[214:217], v[4:7]
	v_mfma_f32_16x16x32_bf16 v[0:3], v[182:185], v[214:217], v[0:3]
	s_setprio 0
	s_setprio 1
	v_mfma_f32_16x16x32_bf16 v[48:51], v[178:181], v[194:197], v[48:51]
	v_mfma_f32_16x16x32_bf16 v[40:43], v[186:189], v[194:197], v[40:43]
	v_mfma_f32_16x16x32_bf16 v[32:35], v[178:181], v[202:205], v[32:35]
	v_mfma_f32_16x16x32_bf16 v[24:27], v[186:189], v[202:205], v[24:27]
	v_mfma_f32_16x16x32_bf16 v[16:19], v[178:181], v[210:213], v[16:19]
	v_mfma_f32_16x16x32_bf16 v[8:11], v[186:189], v[210:213], v[8:11]
	v_mfma_f32_16x16x32_bf16 v[4:7], v[178:181], v[218:221], v[4:7]
	v_mfma_f32_16x16x32_bf16 v[0:3], v[186:189], v[218:221], v[0:3]
	s_setprio 0
	s_barrier
	s_add_i32 s43, 0, 0x18000
	v_add_u32_e32 v143, s43, v141
	s_add_i32 s44, 0, 0x1c000
	ds_read_b128 v[146:149], v143
	ds_read_b128 v[150:153], v143 offset:1024
	ds_read_b128 v[154:157], v143 offset:2048
	ds_read_b128 v[158:161], v143 offset:3072
	v_add_u32_e32 v143, s44, v141
	ds_read_b128 v[174:177], v143
	ds_read_b128 v[178:181], v143 offset:1024
	ds_read_b128 v[182:185], v143 offset:2048
	ds_read_b128 v[186:189], v143 offset:3072
	s_add_u32 s26, s26, 0x40000
	s_addc_u32 s27, s27, 0
	s_mov_b32 m0, s31
	v_lshl_add_u64 v[236:237], s[26:27], 0, v[132:133]
	ds_read_b128 v[190:193], v142 offset:32768
	ds_read_b128 v[194:197], v142 offset:33792
	ds_read_b128 v[198:201], v142 offset:34816
	ds_read_b128 v[202:205], v142 offset:35840
	ds_read_b128 v[206:209], v142 offset:36864
	ds_read_b128 v[210:213], v142 offset:37888
	ds_read_b128 v[214:217], v142 offset:38912
	ds_read_b128 v[218:221], v142 offset:39936
	global_load_lds_dwordx4 v[236:237], off
	v_lshl_add_u64 v[236:237], s[26:27], 0, v[130:131]
	s_mov_b32 m0, s34
	s_nop 0
	global_load_lds_dwordx4 v[236:237], off
	s_waitcnt vmcnt(8)
	s_waitcnt lgkmcnt(0)
	s_barrier
	s_setprio 1
	s_waitcnt lgkmcnt(0)
	v_mfma_f32_16x16x32_bf16 v[124:127], v[146:149], v[190:193], v[124:127]
	v_mfma_f32_16x16x32_bf16 v[120:123], v[154:157], v[190:193], v[120:123]
	v_mfma_f32_16x16x32_bf16 v[116:119], v[146:149], v[198:201], v[116:119]
	v_mfma_f32_16x16x32_bf16 v[108:111], v[154:157], v[198:201], v[108:111]
	v_mfma_f32_16x16x32_bf16 v[100:103], v[146:149], v[206:209], v[100:103]
	v_mfma_f32_16x16x32_bf16 v[92:95], v[154:157], v[206:209], v[92:95]
	v_mfma_f32_16x16x32_bf16 v[80:83], v[146:149], v[214:217], v[80:83]
	v_mfma_f32_16x16x32_bf16 v[72:75], v[154:157], v[214:217], v[72:75]
	s_setprio 0
	s_setprio 1
	v_mfma_f32_16x16x32_bf16 v[124:127], v[150:153], v[194:197], v[124:127]
	v_mfma_f32_16x16x32_bf16 v[120:123], v[158:161], v[194:197], v[120:123]
	v_mfma_f32_16x16x32_bf16 v[116:119], v[150:153], v[202:205], v[116:119]
	v_mfma_f32_16x16x32_bf16 v[108:111], v[158:161], v[202:205], v[108:111]
	v_mfma_f32_16x16x32_bf16 v[100:103], v[150:153], v[210:213], v[100:103]
	v_mfma_f32_16x16x32_bf16 v[92:95], v[158:161], v[210:213], v[92:95]
	v_mfma_f32_16x16x32_bf16 v[80:83], v[150:153], v[218:221], v[80:83]
	v_mfma_f32_16x16x32_bf16 v[72:75], v[158:161], v[218:221], v[72:75]
	s_setprio 0
	s_setprio 1
	v_mfma_f32_16x16x32_bf16 v[112:115], v[174:177], v[190:193], v[112:115]
	v_mfma_f32_16x16x32_bf16 v[104:107], v[182:185], v[190:193], v[104:107]
	v_mfma_f32_16x16x32_bf16 v[96:99], v[174:177], v[198:201], v[96:99]
	v_mfma_f32_16x16x32_bf16 v[88:91], v[182:185], v[198:201], v[88:91]
	v_mfma_f32_16x16x32_bf16 v[84:87], v[174:177], v[206:209], v[84:87]
	v_mfma_f32_16x16x32_bf16 v[76:79], v[182:185], v[206:209], v[76:79]
	v_mfma_f32_16x16x32_bf16 v[68:71], v[174:177], v[214:217], v[68:71]
	v_mfma_f32_16x16x32_bf16 v[64:67], v[182:185], v[214:217], v[64:67]
	s_setprio 0
	s_setprio 1
	v_mfma_f32_16x16x32_bf16 v[112:115], v[178:181], v[194:197], v[112:115]
	v_mfma_f32_16x16x32_bf16 v[104:107], v[186:189], v[194:197], v[104:107]
	v_mfma_f32_16x16x32_bf16 v[96:99], v[178:181], v[202:205], v[96:99]
	v_mfma_f32_16x16x32_bf16 v[88:91], v[186:189], v[202:205], v[88:91]
	v_mfma_f32_16x16x32_bf16 v[84:87], v[178:181], v[210:213], v[84:87]
	v_mfma_f32_16x16x32_bf16 v[76:79], v[186:189], v[210:213], v[76:79]
	v_mfma_f32_16x16x32_bf16 v[68:71], v[178:181], v[218:221], v[68:71]
	v_mfma_f32_16x16x32_bf16 v[64:67], v[186:189], v[218:221], v[64:67]
	s_setprio 0
	s_barrier
; #define PG8_STAGE(bufoff, gbase, voff) do { _Pragma("unroll") for (int _i = 0; _i < 2; ++_i) \
;         __builtin_amdgcn_global_load_lds((const unsigned*)((const char*)(gbase) + (voff)[_i]), (PG8_LAS unsigned*)(lds + (bufoff) + ldsw + _i * 8192), 16, 0, 0); } while (0)
; #define PG8_LDA(dst, b, h) do { _Pragma("unroll") for (int m = 0; m < 4; ++m) _Pragma("unroll") for (int k = 0; k < 2; ++k) dst[m][k] = *(const PG8_LAS bf16x8*)(lds + PG8_SA(b, h) + aoff + m * 2048 + k * 1024); } while (0)
; #define PG8_MMA(ai, bj, At, Bt) do { __builtin_amdgcn_s_setprio(1); _Pragma("unroll") for (int m = 0; m < 4; ++m) _Pragma("unroll") for (int n = 0; n < 2; ++n) _Pragma("unroll") for (int k = 0; k < 2; ++k) \
;         acc[ai][bj][m][n] = __builtin_amdgcn_mfma_f32_16x16x32_bf16(Bt[n][k], At[m][k], acc[ai][bj][m][n], 0, 0, 0); __builtin_amdgcn_s_setprio(0); } while (0)
; #define PG8_WAIT_V(n) asm volatile("s_waitcnt vmcnt(" #n ")" ::: "memory")
; #define PG8_WAIT_L(n) asm volatile("s_waitcnt lgkmcnt(" #n ")" ::: "memory")
; #define PG8_BAR __builtin_amdgcn_s_barrier()
; #define PG8_SCHED __builtin_amdgcn_sched_barrier(0)
; template <class Epi, class Sched, bool ALIGN_EPI, bool SP2, int KC>
; __device__ __forceinline__ void gemm_phase(PG8_LAS unsigned char* lds, const Gemm g, const Sched& S, const Epi& E, const int tid) {
;     ...
;             PG8_LDA(At, 1, 1); PG8_STAGE(PG8_SB(1, 0), b3, voffB); PG8_STAGE(PG8_SB(1, 1), b3 + hstep, voffB); PG8_STAGE(PG8_SA(1, 0), a3, voffA);
;             PG8_WAIT_V(8); PG8_WAIT_L(0); PG8_BAR; PG8_MMA(1, 0, At, B0); PG8_MMA(1, 1, At, B1); PG8_BAR; PG8_SCHED;
;     ...
;         if constexpr (ALIGN_EPI) { if (wr == 0) PG8_BAR; }
	s_add_i32 s26, s43, s28
	v_lshl_add_u64 v[138:139], v[138:139], 0, s[86:87]
	s_mov_b32 m0, s26
	ds_read_b128 v[190:193], v142 offset:49152
	ds_read_b128 v[194:197], v142 offset:50176
	ds_read_b128 v[198:201], v142 offset:51200
	ds_read_b128 v[202:205], v142 offset:52224
	ds_read_b128 v[206:209], v142 offset:53248
	ds_read_b128 v[210:213], v142 offset:54272
	ds_read_b128 v[214:217], v142 offset:55296
	ds_read_b128 v[218:221], v142 offset:56320
	global_load_lds_dwordx4 v[138:139], off
	s_add_i32 m0, s26, 0x2000
	s_add_u32 s24, s24, 0x40080
	v_lshl_add_u64 v[138:139], v[162:163], 0, s[86:87]
	s_addc_u32 s25, s25, 0
	s_add_i32 s26, s44, s28
	global_load_lds_dwordx4 v[138:139], off
	v_lshl_add_u64 v[138:139], s[24:25], 0, v[164:165]
	s_mov_b32 m0, s26
	s_nop 0
	global_load_lds_dwordx4 v[138:139], off
	v_lshl_add_u64 v[138:139], s[24:25], 0, v[128:129]
	s_add_i32 m0, s26, 0x2000
	s_nop 0
	global_load_lds_dwordx4 v[138:139], off
	v_lshl_add_u64 v[138:139], v[222:223], 0, s[86:87]
	s_mov_b32 m0, s35
	s_nop 0
	global_load_lds_dwordx4 v[138:139], off
	v_lshl_add_u64 v[138:139], v[234:235], 0, s[86:87]
	s_mov_b32 m0, s36
	s_nop 0
	global_load_lds_dwordx4 v[138:139], off
	s_waitcnt vmcnt(8)
	s_waitcnt lgkmcnt(0)
	s_barrier
	s_setprio 1
	s_waitcnt lgkmcnt(0)
	v_mfma_f32_16x16x32_bf16 v[60:63], v[146:149], v[190:193], v[60:63]
	v_mfma_f32_16x16x32_bf16 v[56:59], v[154:157], v[190:193], v[56:59]
	v_mfma_f32_16x16x32_bf16 v[52:55], v[146:149], v[198:201], v[52:55]
	v_mfma_f32_16x16x32_bf16 v[44:47], v[154:157], v[198:201], v[44:47]
	v_mfma_f32_16x16x32_bf16 v[36:39], v[146:149], v[206:209], v[36:39]
	v_mfma_f32_16x16x32_bf16 v[28:31], v[154:157], v[206:209], v[28:31]
	v_mfma_f32_16x16x32_bf16 v[20:23], v[146:149], v[214:217], v[20:23]
	v_mfma_f32_16x16x32_bf16 v[12:15], v[154:157], v[214:217], v[12:15]
	s_setprio 0
	s_setprio 1
	v_mfma_f32_16x16x32_bf16 v[60:63], v[150:153], v[194:197], v[60:63]
	v_mfma_f32_16x16x32_bf16 v[56:59], v[158:161], v[194:197], v[56:59]
	v_mfma_f32_16x16x32_bf16 v[52:55], v[150:153], v[202:205], v[52:55]
	v_mfma_f32_16x16x32_bf16 v[44:47], v[158:161], v[202:205], v[44:47]
	v_mfma_f32_16x16x32_bf16 v[36:39], v[150:153], v[210:213], v[36:39]
	v_mfma_f32_16x16x32_bf16 v[28:31], v[158:161], v[210:213], v[28:31]
	v_mfma_f32_16x16x32_bf16 v[20:23], v[150:153], v[218:221], v[20:23]
	v_mfma_f32_16x16x32_bf16 v[12:15], v[158:161], v[218:221], v[12:15]
	s_setprio 0
	s_setprio 1
	v_mfma_f32_16x16x32_bf16 v[48:51], v[174:177], v[190:193], v[48:51]
	v_mfma_f32_16x16x32_bf16 v[40:43], v[182:185], v[190:193], v[40:43]
	v_mfma_f32_16x16x32_bf16 v[32:35], v[174:177], v[198:201], v[32:35]
	v_mfma_f32_16x16x32_bf16 v[24:27], v[182:185], v[198:201], v[24:27]
	v_mfma_f32_16x16x32_bf16 v[16:19], v[174:177], v[206:209], v[16:19]
	v_mfma_f32_16x16x32_bf16 v[8:11], v[182:185], v[206:209], v[8:11]
	v_mfma_f32_16x16x32_bf16 v[4:7], v[174:177], v[214:217], v[4:7]
	v_mfma_f32_16x16x32_bf16 v[0:3], v[182:185], v[214:217], v[0:3]
	s_setprio 0
	s_setprio 1
	v_mfma_f32_16x16x32_bf16 v[48:51], v[178:181], v[194:197], v[48:51]
	v_mfma_f32_16x16x32_bf16 v[40:43], v[186:189], v[194:197], v[40:43]
	v_mfma_f32_16x16x32_bf16 v[32:35], v[178:181], v[202:205], v[32:35]
	v_mfma_f32_16x16x32_bf16 v[24:27], v[186:189], v[202:205], v[24:27]
	v_mfma_f32_16x16x32_bf16 v[16:19], v[178:181], v[210:213], v[16:19]
	v_mfma_f32_16x16x32_bf16 v[8:11], v[186:189], v[210:213], v[8:11]
	v_mfma_f32_16x16x32_bf16 v[4:7], v[178:181], v[218:221], v[4:7]
	v_mfma_f32_16x16x32_bf16 v[0:3], v[186:189], v[218:221], v[0:3]
	s_setprio 0
	s_barrier
	s_add_i32 s42, s42, 2
	s_add_u32 s22, s22, 0x100
	s_addc_u32 s23, s23, 0
	s_add_u32 s40, s40, 0x100
	s_addc_u32 s41, s41, 0
	s_cmp_gt_u32 s42, 13
	s_cbranch_scc0 .LBB0_66
	s_and_b64 vcc, exec, s[10:11]
	s_cbranch_vccz .LBB0_69
	s_barrier

; #define PG8_STAGE(bufoff, gbase, voff) do { _Pragma("unroll") for (int _i = 0; _i < 2; ++_i) \
;         __builtin_amdgcn_global_load_lds((const unsigned*)((const char*)(gbase) + (voff)[_i]), (PG8_LAS unsigned*)(lds + (bufoff) + ldsw + _i * 8192), 16, 0, 0); } while (0)
; #define PG8_LDA(dst, b, h) do { _Pragma("unroll") for (int m = 0; m < 4; ++m) _Pragma("unroll") for (int k = 0; k < 2; ++k) dst[m][k] = *(const PG8_LAS bf16x8*)(lds + PG8_SA(b, h) + aoff + m * 2048 + k * 1024); } while (0)
; #define PG8_LDB(dst, b, h) do { _Pragma("unroll") for (int n = 0; n < 2; ++n) _Pragma("unroll") for (int k = 0; k < 2; ++k) dst[n][k] = *(const PG8_LAS bf16x8*)(lds + PG8_SB(b, h) + boff + n * 2048 + k * 1024); } while (0)
; #define PG8_MMA(ai, bj, At, Bt) do { __builtin_amdgcn_s_setprio(1); _Pragma("unroll") for (int m = 0; m < 4; ++m) _Pragma("unroll") for (int n = 0; n < 2; ++n) _Pragma("unroll") for (int k = 0; k < 2; ++k) \
;         acc[ai][bj][m][n] = __builtin_amdgcn_mfma_f32_16x16x32_bf16(Bt[n][k], At[m][k], acc[ai][bj][m][n], 0, 0, 0); __builtin_amdgcn_s_setprio(0); } while (0)
; #define PG8_WAIT_V(n) asm volatile("s_waitcnt vmcnt(" #n ")" ::: "memory")
; #define PG8_WAIT_L(n) asm volatile("s_waitcnt lgkmcnt(" #n ")" ::: "memory")
; template <class Epi, class Sched, bool ALIGN_EPI, bool SP2, int KC>
; __device__ __forceinline__ void gemm_phase(PG8_LAS unsigned char* lds, const Gemm g, const Sched& S, const Epi& E, const int tid) {
;     ...
;             const bool last = (t == nt - 2);
;             const char* a1 = cA + (size_t)(t + 1) * kstep;
;             const char* a2 = last ? nA : cA + (size_t)(t + 2) * kstep; const char* b2 = last ? nB : cB + (size_t)(t + 2) * kstep;
;             const char* a3 = a2 + kstep; const char* b3 = b2 + kstep;
;             if (last && has_next) S.a_ready(nxt);
;             if constexpr (SP2) {
;             PG8_LDB(B0, 0, 0); PG8_LDB(B1, 0, 1); PG8_SCHED; PG8_LDA(At, 0, 0); PG8_STAGE(PG8_SA(1, 1), a1 + hstep, voffA);
;             PG8_WAIT_V(8); PG8_WAIT_L(0); PG8_BAR; PG8_MMA(0, 0, At, B0); PG8_MMA(0, 1, At, B1); PG8_BAR; PG8_SCHED;
;             PG8_LDA(At, 0, 1); PG8_STAGE(PG8_SB(0, 0), b2, voffB); PG8_STAGE(PG8_SB(0, 1), b2 + hstep, voffB); PG8_STAGE(PG8_SA(0, 0), a2, voffA);
;             PG8_WAIT_V(8); PG8_WAIT_L(0); PG8_BAR; PG8_MMA(1, 0, At, B0); PG8_MMA(1, 1, At, B1); PG8_BAR; PG8_SCHED;
.LBB0_92:
	s_add_u32 s26, s4, 0xfffc0080
	s_addc_u32 s27, s5, -1
	s_add_i32 s45, 0, 0x10000
	s_cmp_eq_u32 s44, 12
	s_cselect_b32 s29, s19, s27
	s_cselect_b32 s28, s40, s26
	s_cselect_b32 s27, s17, s43
	s_cselect_b32 s26, s41, s42
	s_add_i32 s48, 0, 0x14000
	v_add_u32_e32 v76, s45, v222
	v_add_u32_e32 v156, s48, v222
	ds_read_b128 v[64:67], v76
	ds_read_b128 v[68:71], v76 offset:1024
	ds_read_b128 v[72:75], v76 offset:2048
	ds_read_b128 v[76:79], v76 offset:3072
	ds_read_b128 v[144:147], v156
	ds_read_b128 v[148:151], v156 offset:1024
	ds_read_b128 v[152:155], v156 offset:2048
	ds_read_b128 v[156:159], v156 offset:3072
	v_lshl_add_u64 v[212:213], s[4:5], 0, v[176:177]
	s_add_i32 m0, s7, 0xc000
	ds_read_b128 v[180:183], v233
	ds_read_b128 v[184:187], v233 offset:1024
	ds_read_b128 v[188:191], v233 offset:2048
	ds_read_b128 v[192:195], v233 offset:3072
	ds_read_b128 v[196:199], v233 offset:4096
	ds_read_b128 v[200:203], v233 offset:5120
	ds_read_b128 v[204:207], v233 offset:6144
	ds_read_b128 v[208:211], v233 offset:7168
	global_load_lds_dwordx4 v[212:213], off
	v_lshl_add_u64 v[212:213], s[4:5], 0, v[178:179]
	s_add_i32 m0, s7, 0xe000
	s_nop 0
	global_load_lds_dwordx4 v[212:213], off
	s_waitcnt vmcnt(8)
	s_waitcnt lgkmcnt(0)
	s_barrier
	s_setprio 1
	s_waitcnt lgkmcnt(0)
	v_mfma_f32_16x16x32_bf16 v[140:143], v[64:67], v[180:183], v[140:143]
	v_mfma_f32_16x16x32_bf16 v[132:135], v[72:75], v[180:183], v[132:135]
	v_mfma_f32_16x16x32_bf16 v[124:127], v[64:67], v[188:191], v[124:127]
	v_mfma_f32_16x16x32_bf16 v[116:119], v[72:75], v[188:191], v[116:119]
	v_mfma_f32_16x16x32_bf16 v[108:111], v[64:67], v[196:199], v[108:111]
	v_mfma_f32_16x16x32_bf16 v[100:103], v[72:75], v[196:199], v[100:103]
	v_mfma_f32_16x16x32_bf16 v[92:95], v[64:67], v[204:207], v[92:95]
	v_mfma_f32_16x16x32_bf16 v[84:87], v[72:75], v[204:207], v[84:87]
	s_setprio 0
	s_setprio 1
	v_mfma_f32_16x16x32_bf16 v[140:143], v[68:71], v[184:187], v[140:143]
	v_mfma_f32_16x16x32_bf16 v[132:135], v[76:79], v[184:187], v[132:135]
	v_mfma_f32_16x16x32_bf16 v[124:127], v[68:71], v[192:195], v[124:127]
	v_mfma_f32_16x16x32_bf16 v[116:119], v[76:79], v[192:195], v[116:119]
	v_mfma_f32_16x16x32_bf16 v[108:111], v[68:71], v[200:203], v[108:111]
	v_mfma_f32_16x16x32_bf16 v[100:103], v[76:79], v[200:203], v[100:103]
	v_mfma_f32_16x16x32_bf16 v[92:95], v[68:71], v[208:211], v[92:95]
	v_mfma_f32_16x16x32_bf16 v[84:87], v[76:79], v[208:211], v[84:87]
	s_setprio 0
	s_setprio 1
	v_mfma_f32_16x16x32_bf16 v[136:139], v[144:147], v[180:183], v[136:139]
	v_mfma_f32_16x16x32_bf16 v[128:131], v[152:155], v[180:183], v[128:131]
	v_mfma_f32_16x16x32_bf16 v[120:123], v[144:147], v[188:191], v[120:123]
	v_mfma_f32_16x16x32_bf16 v[112:115], v[152:155], v[188:191], v[112:115]
	v_mfma_f32_16x16x32_bf16 v[104:107], v[144:147], v[196:199], v[104:107]
	v_mfma_f32_16x16x32_bf16 v[96:99], v[152:155], v[196:199], v[96:99]
	v_mfma_f32_16x16x32_bf16 v[88:91], v[144:147], v[204:207], v[88:91]
	v_mfma_f32_16x16x32_bf16 v[80:83], v[152:155], v[204:207], v[80:83]
	s_setprio 0
	s_setprio 1
	v_mfma_f32_16x16x32_bf16 v[136:139], v[148:151], v[184:187], v[136:139]
	v_mfma_f32_16x16x32_bf16 v[128:131], v[156:159], v[184:187], v[128:131]
	v_mfma_f32_16x16x32_bf16 v[120:123], v[148:151], v[192:195], v[120:123]
	v_mfma_f32_16x16x32_bf16 v[112:115], v[156:159], v[192:195], v[112:115]
	v_mfma_f32_16x16x32_bf16 v[104:107], v[148:151], v[200:203], v[104:107]
	v_mfma_f32_16x16x32_bf16 v[96:99], v[156:159], v[200:203], v[96:99]
	v_mfma_f32_16x16x32_bf16 v[88:91], v[148:151], v[208:211], v[88:91]
	v_mfma_f32_16x16x32_bf16 v[80:83], v[156:159], v[208:211], v[80:83]
	s_setprio 0
	s_barrier
	s_add_i32 s45, s45, s6
	v_lshl_add_u64 v[212:213], s[26:27], 0, v[164:165]
	s_mov_b32 m0, s45
	ds_read_b128 v[180:183], v233 offset:16384
	ds_read_b128 v[184:187], v233 offset:17408
	ds_read_b128 v[188:191], v233 offset:18432
	ds_read_b128 v[192:195], v233 offset:19456
	ds_read_b128 v[196:199], v233 offset:20480
	ds_read_b128 v[200:203], v233 offset:21504
	ds_read_b128 v[204:207], v233 offset:22528
	ds_read_b128 v[208:211], v233 offset:23552
	global_load_lds_dwordx4 v[212:213], off
	s_add_i32 m0, s45, 0x2000
	s_add_u32 s46, s26, 0x40000
	v_lshl_add_u64 v[214:215], s[26:27], 0, v[160:161]
	s_addc_u32 s47, s27, 0
	s_add_i32 s45, s48, s6
	global_load_lds_dwordx4 v[214:215], off
	v_lshl_add_u64 v[216:217], s[46:47], 0, v[164:165]
	s_mov_b32 m0, s45
	v_lshl_add_u64 v[218:219], s[28:29], 0, v[162:163]
	global_load_lds_dwordx4 v[216:217], off
	v_lshl_add_u64 v[216:217], s[46:47], 0, v[160:161]
	s_add_i32 m0, s45, 0x2000
	s_nop 0
	global_load_lds_dwordx4 v[216:217], off
	v_lshl_add_u64 v[216:217], s[28:29], 0, v[174:175]
	s_mov_b32 m0, s7
	s_nop 0
	global_load_lds_dwordx4 v[216:217], off
	s_mov_b32 m0, s30
	s_nop 0
	global_load_lds_dwordx4 v[218:219], off
	s_waitcnt vmcnt(8)
	s_waitcnt lgkmcnt(0)
	s_barrier
; #define PG8_STAGE(bufoff, gbase, voff) do { _Pragma("unroll") for (int _i = 0; _i < 2; ++_i) \
;         __builtin_amdgcn_global_load_lds((const unsigned*)((const char*)(gbase) + (voff)[_i]), (PG8_LAS unsigned*)(lds + (bufoff) + ldsw + _i * 8192), 16, 0, 0); } while (0)
; #define PG8_LDA(dst, b, h) do { _Pragma("unroll") for (int m = 0; m < 4; ++m) _Pragma("unroll") for (int k = 0; k < 2; ++k) dst[m][k] = *(const PG8_LAS bf16x8*)(lds + PG8_SA(b, h) + aoff + m * 2048 + k * 1024); } while (0)
; #define PG8_LDB(dst, b, h) do { _Pragma("unroll") for (int n = 0; n < 2; ++n) _Pragma("unroll") for (int k = 0; k < 2; ++k) dst[n][k] = *(const PG8_LAS bf16x8*)(lds + PG8_SB(b, h) + boff + n * 2048 + k * 1024); } while (0)
; #define PG8_MMA(ai, bj, At, Bt) do { __builtin_amdgcn_s_setprio(1); _Pragma("unroll") for (int m = 0; m < 4; ++m) _Pragma("unroll") for (int n = 0; n < 2; ++n) _Pragma("unroll") for (int k = 0; k < 2; ++k) \
;         acc[ai][bj][m][n] = __builtin_amdgcn_mfma_f32_16x16x32_bf16(Bt[n][k], At[m][k], acc[ai][bj][m][n], 0, 0, 0); __builtin_amdgcn_s_setprio(0); } while (0)
; #define PG8_WAIT_V(n) asm volatile("s_waitcnt vmcnt(" #n ")" ::: "memory")
; #define PG8_WAIT_L(n) asm volatile("s_waitcnt lgkmcnt(" #n ")" ::: "memory")
; #define PG8_BAR __builtin_amdgcn_s_barrier()
; #define PG8_SCHED __builtin_amdgcn_sched_barrier(0)
; template <class Epi, class Sched, bool ALIGN_EPI, bool SP2, int KC>
; __device__ __forceinline__ void gemm_phase(PG8_LAS unsigned char* lds, const Gemm g, const Sched& S, const Epi& E, const int tid) {
;     ...
;             PG8_WAIT_V(8); PG8_WAIT_L(0); PG8_BAR; PG8_MMA(1, 0, At, B0); PG8_MMA(1, 1, At, B1); PG8_BAR; PG8_SCHED;
;             PG8_LDB(B0, 1, 0); PG8_LDB(B1, 1, 1); PG8_SCHED; PG8_LDA(At, 1, 0); PG8_STAGE(PG8_SA(0, 1), a2 + hstep, voffA);
;             PG8_WAIT_V(8); PG8_WAIT_L(0); PG8_BAR; PG8_MMA(0, 0, At, B0); PG8_MMA(0, 1, At, B1); PG8_BAR; PG8_SCHED;
	s_setprio 1
	s_waitcnt lgkmcnt(0)
	v_mfma_f32_16x16x32_bf16 v[60:63], v[64:67], v[180:183], v[60:63]
	v_mfma_f32_16x16x32_bf16 v[52:55], v[72:75], v[180:183], v[52:55]
	v_mfma_f32_16x16x32_bf16 v[44:47], v[64:67], v[188:191], v[44:47]
	v_mfma_f32_16x16x32_bf16 v[36:39], v[72:75], v[188:191], v[36:39]
	v_mfma_f32_16x16x32_bf16 v[28:31], v[64:67], v[196:199], v[28:31]
	v_mfma_f32_16x16x32_bf16 v[20:23], v[72:75], v[196:199], v[20:23]
	v_mfma_f32_16x16x32_bf16 v[12:15], v[64:67], v[204:207], v[12:15]
	v_mfma_f32_16x16x32_bf16 v[4:7], v[72:75], v[204:207], v[4:7]
	s_setprio 0
	s_setprio 1
	v_mfma_f32_16x16x32_bf16 v[60:63], v[68:71], v[184:187], v[60:63]
	v_mfma_f32_16x16x32_bf16 v[52:55], v[76:79], v[184:187], v[52:55]
	v_mfma_f32_16x16x32_bf16 v[44:47], v[68:71], v[192:195], v[44:47]
	v_mfma_f32_16x16x32_bf16 v[36:39], v[76:79], v[192:195], v[36:39]
	v_mfma_f32_16x16x32_bf16 v[28:31], v[68:71], v[200:203], v[28:31]
	v_mfma_f32_16x16x32_bf16 v[20:23], v[76:79], v[200:203], v[20:23]
	v_mfma_f32_16x16x32_bf16 v[12:15], v[68:71], v[208:211], v[12:15]
	v_mfma_f32_16x16x32_bf16 v[4:7], v[76:79], v[208:211], v[4:7]
	s_setprio 0
	s_setprio 1
	v_mfma_f32_16x16x32_bf16 v[56:59], v[144:147], v[180:183], v[56:59]
	v_mfma_f32_16x16x32_bf16 v[48:51], v[152:155], v[180:183], v[48:51]
	v_mfma_f32_16x16x32_bf16 v[40:43], v[144:147], v[188:191], v[40:43]
	v_mfma_f32_16x16x32_bf16 v[32:35], v[152:155], v[188:191], v[32:35]
	v_mfma_f32_16x16x32_bf16 v[24:27], v[144:147], v[196:199], v[24:27]
	v_mfma_f32_16x16x32_bf16 v[16:19], v[152:155], v[196:199], v[16:19]
	v_mfma_f32_16x16x32_bf16 v[8:11], v[144:147], v[204:207], v[8:11]
	v_mfma_f32_16x16x32_bf16 v[0:3], v[152:155], v[204:207], v[0:3]
	s_setprio 0
	s_setprio 1
	v_mfma_f32_16x16x32_bf16 v[56:59], v[148:151], v[184:187], v[56:59]
	v_mfma_f32_16x16x32_bf16 v[48:51], v[156:159], v[184:187], v[48:51]
	v_mfma_f32_16x16x32_bf16 v[40:43], v[148:151], v[192:195], v[40:43]
	v_mfma_f32_16x16x32_bf16 v[32:35], v[156:159], v[192:195], v[32:35]
	v_mfma_f32_16x16x32_bf16 v[24:27], v[148:151], v[200:203], v[24:27]
	v_mfma_f32_16x16x32_bf16 v[16:19], v[156:159], v[200:203], v[16:19]
	v_mfma_f32_16x16x32_bf16 v[8:11], v[148:151], v[208:211], v[8:11]
	v_mfma_f32_16x16x32_bf16 v[0:3], v[156:159], v[208:211], v[0:3]
	s_setprio 0
	s_barrier
	s_add_i32 s45, 0, 0x18000
	s_add_i32 s46, 0, 0x1c000
	v_add_u32_e32 v76, s45, v222
	v_add_u32_e32 v156, s46, v222
	ds_read_b128 v[64:67], v76
	ds_read_b128 v[68:71], v76 offset:1024
	ds_read_b128 v[72:75], v76 offset:2048
	ds_read_b128 v[76:79], v76 offset:3072
	ds_read_b128 v[144:147], v156
	ds_read_b128 v[148:151], v156 offset:1024
	ds_read_b128 v[152:155], v156 offset:2048
	ds_read_b128 v[156:159], v156 offset:3072
	s_add_u32 s28, s28, 0x40000
	s_addc_u32 s29, s29, 0
	s_mov_b32 m0, s31
	v_lshl_add_u64 v[220:221], s[28:29], 0, v[174:175]
	ds_read_b128 v[180:183], v233 offset:32768
	ds_read_b128 v[184:187], v233 offset:33792
	ds_read_b128 v[188:191], v233 offset:34816
	ds_read_b128 v[192:195], v233 offset:35840
	ds_read_b128 v[196:199], v233 offset:36864
	ds_read_b128 v[200:203], v233 offset:37888
	ds_read_b128 v[204:207], v233 offset:38912
	ds_read_b128 v[208:211], v233 offset:39936
	global_load_lds_dwordx4 v[220:221], off
	v_lshl_add_u64 v[220:221], s[28:29], 0, v[162:163]
	s_mov_b32 m0, s34
	s_nop 0
	global_load_lds_dwordx4 v[220:221], off
	s_waitcnt vmcnt(8)
	s_waitcnt lgkmcnt(0)
	s_barrier
	s_setprio 1
	s_waitcnt lgkmcnt(0)
	v_mfma_f32_16x16x32_bf16 v[140:143], v[64:67], v[180:183], v[140:143]
	v_mfma_f32_16x16x32_bf16 v[132:135], v[72:75], v[180:183], v[132:135]
	v_mfma_f32_16x16x32_bf16 v[124:127], v[64:67], v[188:191], v[124:127]
	v_mfma_f32_16x16x32_bf16 v[116:119], v[72:75], v[188:191], v[116:119]
	v_mfma_f32_16x16x32_bf16 v[108:111], v[64:67], v[196:199], v[108:111]
	v_mfma_f32_16x16x32_bf16 v[100:103], v[72:75], v[196:199], v[100:103]
	v_mfma_f32_16x16x32_bf16 v[92:95], v[64:67], v[204:207], v[92:95]
	v_mfma_f32_16x16x32_bf16 v[84:87], v[72:75], v[204:207], v[84:87]
	s_setprio 0
	s_setprio 1
	v_mfma_f32_16x16x32_bf16 v[140:143], v[68:71], v[184:187], v[140:143]
	v_mfma_f32_16x16x32_bf16 v[132:135], v[76:79], v[184:187], v[132:135]
	v_mfma_f32_16x16x32_bf16 v[124:127], v[68:71], v[192:195], v[124:127]
	v_mfma_f32_16x16x32_bf16 v[116:119], v[76:79], v[192:195], v[116:119]
	v_mfma_f32_16x16x32_bf16 v[108:111], v[68:71], v[200:203], v[108:111]
	v_mfma_f32_16x16x32_bf16 v[100:103], v[76:79], v[200:203], v[100:103]
	v_mfma_f32_16x16x32_bf16 v[92:95], v[68:71], v[208:211], v[92:95]
	v_mfma_f32_16x16x32_bf16 v[84:87], v[76:79], v[208:211], v[84:87]
	s_setprio 0
	s_setprio 1
	v_mfma_f32_16x16x32_bf16 v[136:139], v[144:147], v[180:183], v[136:139]
	v_mfma_f32_16x16x32_bf16 v[128:131], v[152:155], v[180:183], v[128:131]
	v_mfma_f32_16x16x32_bf16 v[120:123], v[144:147], v[188:191], v[120:123]
	v_mfma_f32_16x16x32_bf16 v[112:115], v[152:155], v[188:191], v[112:115]
	v_mfma_f32_16x16x32_bf16 v[104:107], v[144:147], v[196:199], v[104:107]
	v_mfma_f32_16x16x32_bf16 v[96:99], v[152:155], v[196:199], v[96:99]
	v_mfma_f32_16x16x32_bf16 v[88:91], v[144:147], v[204:207], v[88:91]
	v_mfma_f32_16x16x32_bf16 v[80:83], v[152:155], v[204:207], v[80:83]
	s_setprio 0
	s_setprio 1
	v_mfma_f32_16x16x32_bf16 v[136:139], v[148:151], v[184:187], v[136:139]
	v_mfma_f32_16x16x32_bf16 v[128:131], v[156:159], v[184:187], v[128:131]
	v_mfma_f32_16x16x32_bf16 v[120:123], v[148:151], v[192:195], v[120:123]
	v_mfma_f32_16x16x32_bf16 v[112:115], v[156:159], v[192:195], v[112:115]
	v_mfma_f32_16x16x32_bf16 v[104:107], v[148:151], v[200:203], v[104:107]
	v_mfma_f32_16x16x32_bf16 v[96:99], v[156:159], v[200:203], v[96:99]
	v_mfma_f32_16x16x32_bf16 v[88:91], v[148:151], v[208:211], v[88:91]
	v_mfma_f32_16x16x32_bf16 v[80:83], v[156:159], v[208:211], v[80:83]
	s_setprio 0
	s_barrier
; #define PG8_STAGE(bufoff, gbase, voff) do { _Pragma("unroll") for (int _i = 0; _i < 2; ++_i) \
;         __builtin_amdgcn_global_load_lds((const unsigned*)((const char*)(gbase) + (voff)[_i]), (PG8_LAS unsigned*)(lds + (bufoff) + ldsw + _i * 8192), 16, 0, 0); } while (0)
; #define PG8_LDA(dst, b, h) do { _Pragma("unroll") for (int m = 0; m < 4; ++m) _Pragma("unroll") for (int k = 0; k < 2; ++k) dst[m][k] = *(const PG8_LAS bf16x8*)(lds + PG8_SA(b, h) + aoff + m * 2048 + k * 1024); } while (0)
; #define PG8_MMA(ai, bj, At, Bt) do { __builtin_amdgcn_s_setprio(1); _Pragma("unroll") for (int m = 0; m < 4; ++m) _Pragma("unroll") for (int n = 0; n < 2; ++n) _Pragma("unroll") for (int k = 0; k < 2; ++k) \
;         acc[ai][bj][m][n] = __builtin_amdgcn_mfma_f32_16x16x32_bf16(Bt[n][k], At[m][k], acc[ai][bj][m][n], 0, 0, 0); __builtin_amdgcn_s_setprio(0); } while (0)
; #define PG8_WAIT_V(n) asm volatile("s_waitcnt vmcnt(" #n ")" ::: "memory")
; #define PG8_WAIT_L(n) asm volatile("s_waitcnt lgkmcnt(" #n ")" ::: "memory")
; #define PG8_BAR __builtin_amdgcn_s_barrier()
; #define PG8_SCHED __builtin_amdgcn_sched_barrier(0)
; template <class Epi, class Sched, bool ALIGN_EPI, bool SP2, int KC>
; __device__ __forceinline__ void gemm_phase(PG8_LAS unsigned char* lds, const Gemm g, const Sched& S, const Epi& E, const int tid) {
;     ...
;             PG8_LDA(At, 1, 1); PG8_STAGE(PG8_SB(1, 0), b3, voffB); PG8_STAGE(PG8_SB(1, 1), b3 + hstep, voffB); PG8_STAGE(PG8_SA(1, 0), a3, voffA);
;             PG8_WAIT_V(8); PG8_WAIT_L(0); PG8_BAR; PG8_MMA(1, 0, At, B0); PG8_MMA(1, 1, At, B1); PG8_BAR; PG8_SCHED;
;     ...
;         if constexpr (ALIGN_EPI) { if (wr == 0) PG8_BAR; }
	s_add_i32 s28, s45, s6
	v_lshl_add_u64 v[212:213], v[212:213], 0, s[86:87]
	s_mov_b32 m0, s28
	ds_read_b128 v[180:183], v233 offset:49152
	ds_read_b128 v[184:187], v233 offset:50176
	ds_read_b128 v[188:191], v233 offset:51200
	ds_read_b128 v[192:195], v233 offset:52224
	ds_read_b128 v[196:199], v233 offset:53248
	ds_read_b128 v[200:203], v233 offset:54272
	ds_read_b128 v[204:207], v233 offset:55296
	ds_read_b128 v[208:211], v233 offset:56320
	global_load_lds_dwordx4 v[212:213], off
	s_add_i32 m0, s28, 0x2000
	s_add_u32 s26, s26, 0x40080
	v_lshl_add_u64 v[212:213], v[214:215], 0, s[86:87]
	s_addc_u32 s27, s27, 0
	s_add_i32 s28, s46, s6
	global_load_lds_dwordx4 v[212:213], off
	v_lshl_add_u64 v[212:213], s[26:27], 0, v[164:165]
	s_mov_b32 m0, s28
	s_nop 0
	global_load_lds_dwordx4 v[212:213], off
	v_lshl_add_u64 v[212:213], s[26:27], 0, v[160:161]
	s_add_i32 m0, s28, 0x2000
	s_nop 0
	global_load_lds_dwordx4 v[212:213], off
	v_lshl_add_u64 v[212:213], v[216:217], 0, s[86:87]
	s_mov_b32 m0, s35
	s_nop 0
	global_load_lds_dwordx4 v[212:213], off
	v_lshl_add_u64 v[212:213], v[218:219], 0, s[86:87]
	s_mov_b32 m0, s36
	s_nop 0
	global_load_lds_dwordx4 v[212:213], off
	s_waitcnt vmcnt(8)
	s_waitcnt lgkmcnt(0)
	s_barrier
	s_setprio 1
	s_waitcnt lgkmcnt(0)
	v_mfma_f32_16x16x32_bf16 v[60:63], v[64:67], v[180:183], v[60:63]
	v_mfma_f32_16x16x32_bf16 v[52:55], v[72:75], v[180:183], v[52:55]
	v_mfma_f32_16x16x32_bf16 v[44:47], v[64:67], v[188:191], v[44:47]
	v_mfma_f32_16x16x32_bf16 v[36:39], v[72:75], v[188:191], v[36:39]
	v_mfma_f32_16x16x32_bf16 v[28:31], v[64:67], v[196:199], v[28:31]
	v_mfma_f32_16x16x32_bf16 v[20:23], v[72:75], v[196:199], v[20:23]
	v_mfma_f32_16x16x32_bf16 v[12:15], v[64:67], v[204:207], v[12:15]
	v_mfma_f32_16x16x32_bf16 v[4:7], v[72:75], v[204:207], v[4:7]
	s_setprio 0
	s_setprio 1
	v_mfma_f32_16x16x32_bf16 v[60:63], v[68:71], v[184:187], v[60:63]
	v_mfma_f32_16x16x32_bf16 v[52:55], v[76:79], v[184:187], v[52:55]
	v_mfma_f32_16x16x32_bf16 v[44:47], v[68:71], v[192:195], v[44:47]
	v_mfma_f32_16x16x32_bf16 v[36:39], v[76:79], v[192:195], v[36:39]
	v_mfma_f32_16x16x32_bf16 v[28:31], v[68:71], v[200:203], v[28:31]
	v_mfma_f32_16x16x32_bf16 v[20:23], v[76:79], v[200:203], v[20:23]
	v_mfma_f32_16x16x32_bf16 v[12:15], v[68:71], v[208:211], v[12:15]
	v_mfma_f32_16x16x32_bf16 v[4:7], v[76:79], v[208:211], v[4:7]
	s_setprio 0
	s_setprio 1
	v_mfma_f32_16x16x32_bf16 v[56:59], v[144:147], v[180:183], v[56:59]
	v_mfma_f32_16x16x32_bf16 v[48:51], v[152:155], v[180:183], v[48:51]
	v_mfma_f32_16x16x32_bf16 v[40:43], v[144:147], v[188:191], v[40:43]
	v_mfma_f32_16x16x32_bf16 v[32:35], v[152:155], v[188:191], v[32:35]
	v_mfma_f32_16x16x32_bf16 v[24:27], v[144:147], v[196:199], v[24:27]
	v_mfma_f32_16x16x32_bf16 v[16:19], v[152:155], v[196:199], v[16:19]
	v_mfma_f32_16x16x32_bf16 v[8:11], v[144:147], v[204:207], v[8:11]
	v_mfma_f32_16x16x32_bf16 v[0:3], v[152:155], v[204:207], v[0:3]
	s_setprio 0
	s_setprio 1
	v_mfma_f32_16x16x32_bf16 v[56:59], v[148:151], v[184:187], v[56:59]
	v_mfma_f32_16x16x32_bf16 v[48:51], v[156:159], v[184:187], v[48:51]
	v_mfma_f32_16x16x32_bf16 v[40:43], v[148:151], v[192:195], v[40:43]
	v_mfma_f32_16x16x32_bf16 v[32:35], v[156:159], v[192:195], v[32:35]
	v_mfma_f32_16x16x32_bf16 v[24:27], v[148:151], v[200:203], v[24:27]
	v_mfma_f32_16x16x32_bf16 v[16:19], v[156:159], v[200:203], v[16:19]
	v_mfma_f32_16x16x32_bf16 v[8:11], v[148:151], v[208:211], v[8:11]
	v_mfma_f32_16x16x32_bf16 v[0:3], v[156:159], v[208:211], v[0:3]
	s_setprio 0
	s_barrier
	s_add_i32 s44, s44, 2
	s_add_u32 s4, s4, 0x100
	s_addc_u32 s5, s5, 0
	s_add_u32 s42, s42, 0x100
	s_addc_u32 s43, s43, 0
	s_cmp_gt_u32 s44, 13
	s_cbranch_scc0 .LBB0_92
	s_and_b64 vcc, exec, s[14:15]
	s_cbranch_vccz .LBB0_95
	s_barrier

; #define PG8_STAGE(bufoff, gbase, voff) do { _Pragma("unroll") for (int _i = 0; _i < 2; ++_i) \
;         __builtin_amdgcn_global_load_lds((const unsigned*)((const char*)(gbase) + (voff)[_i]), (PG8_LAS unsigned*)(lds + (bufoff) + ldsw + _i * 8192), 16, 0, 0); } while (0)
; #define PG8_LDA(dst, b, h) do { _Pragma("unroll") for (int m = 0; m < 4; ++m) _Pragma("unroll") for (int k = 0; k < 2; ++k) dst[m][k] = *(const PG8_LAS bf16x8*)(lds + PG8_SA(b, h) + aoff + m * 2048 + k * 1024); } while (0)
; #define PG8_LDB(dst, b, h) do { _Pragma("unroll") for (int n = 0; n < 2; ++n) _Pragma("unroll") for (int k = 0; k < 2; ++k) dst[n][k] = *(const PG8_LAS bf16x8*)(lds + PG8_SB(b, h) + boff + n * 2048 + k * 1024); } while (0)
; #define PG8_MMA(ai, bj, At, Bt) do { __builtin_amdgcn_s_setprio(1); _Pragma("unroll") for (int m = 0; m < 4; ++m) _Pragma("unroll") for (int n = 0; n < 2; ++n) _Pragma("unroll") for (int k = 0; k < 2; ++k) \
;         acc[ai][bj][m][n] = __builtin_amdgcn_mfma_f32_16x16x32_bf16(Bt[n][k], At[m][k], acc[ai][bj][m][n], 0, 0, 0); __builtin_amdgcn_s_setprio(0); } while (0)
; #define PG8_WAIT_V(n) asm volatile("s_waitcnt vmcnt(" #n ")" ::: "memory")
; #define PG8_WAIT_L(n) asm volatile("s_waitcnt lgkmcnt(" #n ")" ::: "memory")
; template <class Epi, class Sched, bool ALIGN_EPI, bool SP2, int KC>
; __device__ __forceinline__ void gemm_phase(PG8_LAS unsigned char* lds, const Gemm g, const Sched& S, const Epi& E, const int tid) {
;     ...
;             const bool last = (t == nt - 2);
;             const char* a1 = cA + (size_t)(t + 1) * kstep;
;             const char* a2 = last ? nA : cA + (size_t)(t + 2) * kstep; const char* b2 = last ? nB : cB + (size_t)(t + 2) * kstep;
;             const char* a3 = a2 + kstep; const char* b3 = b2 + kstep;
;             if (last && has_next) S.a_ready(nxt);
;             if constexpr (SP2) {
;             PG8_LDB(B0, 0, 0); PG8_LDB(B1, 0, 1); PG8_SCHED; PG8_LDA(At, 0, 0); PG8_STAGE(PG8_SA(1, 1), a1 + hstep, voffA);
;             PG8_WAIT_V(8); PG8_WAIT_L(0); PG8_BAR; PG8_MMA(0, 0, At, B0); PG8_MMA(0, 1, At, B1); PG8_BAR; PG8_SCHED;
;             PG8_LDA(At, 0, 1); PG8_STAGE(PG8_SB(0, 0), b2, voffB); PG8_STAGE(PG8_SB(0, 1), b2 + hstep, voffB); PG8_STAGE(PG8_SA(0, 0), a2, voffA);
;             PG8_WAIT_V(8); PG8_WAIT_L(0); PG8_BAR; PG8_MMA(1, 0, At, B0); PG8_MMA(1, 1, At, B1); PG8_BAR; PG8_SCHED;
.LBB0_116:
	s_add_u32 s24, s22, 0xfffc0080
	s_addc_u32 s25, s23, -1
	s_add_i32 s43, 0, 0x10000
	s_cmp_eq_u32 s42, 12
	s_cselect_b32 s27, s15, s25
	s_cselect_b32 s26, s38, s24
	s_cselect_b32 s25, s13, s41
	s_cselect_b32 s24, s39, s40
	s_add_i32 s46, 0, 0x14000
	v_add_u32_e32 v140, s43, v196
	v_add_u32_e32 v162, s46, v196
	ds_read_b128 v[128:131], v140
	ds_read_b128 v[132:135], v140 offset:1024
	ds_read_b128 v[136:139], v140 offset:2048
	ds_read_b128 v[140:143], v140 offset:3072
	ds_read_b128 v[154:157], v162
	ds_read_b128 v[158:161], v162 offset:1024
	ds_read_b128 v[174:177], v162 offset:2048
	ds_read_b128 v[178:181], v162 offset:3072
	v_lshl_add_u64 v[162:163], s[22:23], 0, v[150:151]
	s_add_i32 m0, s29, 0xc000
	ds_read_b128 v[182:185], v198
	ds_read_b128 v[186:189], v198 offset:1024
	ds_read_b128 v[190:193], v198 offset:2048
	ds_read_b128 v[200:203], v198 offset:3072
	ds_read_b128 v[204:207], v198 offset:4096
	ds_read_b128 v[208:211], v198 offset:5120
	ds_read_b128 v[212:215], v198 offset:6144
	ds_read_b128 v[216:219], v198 offset:7168
	global_load_lds_dwordx4 v[162:163], off
	v_lshl_add_u64 v[162:163], s[22:23], 0, v[152:153]
	s_add_i32 m0, s29, 0xe000
	s_nop 0
	global_load_lds_dwordx4 v[162:163], off
	s_waitcnt vmcnt(8)
	s_waitcnt lgkmcnt(0)
	s_barrier
	s_setprio 1
	s_waitcnt lgkmcnt(0)
	v_mfma_f32_16x16x32_bf16 v[124:127], v[128:131], v[182:185], v[124:127]
	v_mfma_f32_16x16x32_bf16 v[120:123], v[136:139], v[182:185], v[120:123]
	v_mfma_f32_16x16x32_bf16 v[116:119], v[128:131], v[190:193], v[116:119]
	v_mfma_f32_16x16x32_bf16 v[112:115], v[136:139], v[190:193], v[112:115]
	v_mfma_f32_16x16x32_bf16 v[108:111], v[128:131], v[204:207], v[108:111]
	v_mfma_f32_16x16x32_bf16 v[104:107], v[136:139], v[204:207], v[104:107]
	v_mfma_f32_16x16x32_bf16 v[100:103], v[128:131], v[212:215], v[100:103]
	v_mfma_f32_16x16x32_bf16 v[96:99], v[136:139], v[212:215], v[96:99]
	s_setprio 0
	s_setprio 1
	v_mfma_f32_16x16x32_bf16 v[124:127], v[132:135], v[186:189], v[124:127]
	v_mfma_f32_16x16x32_bf16 v[120:123], v[140:143], v[186:189], v[120:123]
	v_mfma_f32_16x16x32_bf16 v[116:119], v[132:135], v[200:203], v[116:119]
	v_mfma_f32_16x16x32_bf16 v[112:115], v[140:143], v[200:203], v[112:115]
	v_mfma_f32_16x16x32_bf16 v[108:111], v[132:135], v[208:211], v[108:111]
	v_mfma_f32_16x16x32_bf16 v[104:107], v[140:143], v[208:211], v[104:107]
	v_mfma_f32_16x16x32_bf16 v[100:103], v[132:135], v[216:219], v[100:103]
	v_mfma_f32_16x16x32_bf16 v[96:99], v[140:143], v[216:219], v[96:99]
	s_setprio 0
	s_setprio 1
	v_mfma_f32_16x16x32_bf16 v[68:71], v[154:157], v[182:185], v[68:71]
	v_mfma_f32_16x16x32_bf16 v[64:67], v[174:177], v[182:185], v[64:67]
	v_mfma_f32_16x16x32_bf16 v[52:55], v[154:157], v[190:193], v[52:55]
	v_mfma_f32_16x16x32_bf16 v[48:51], v[174:177], v[190:193], v[48:51]
	v_mfma_f32_16x16x32_bf16 v[44:47], v[154:157], v[204:207], v[44:47]
	v_mfma_f32_16x16x32_bf16 v[40:43], v[174:177], v[204:207], v[40:43]
	v_mfma_f32_16x16x32_bf16 v[36:39], v[154:157], v[212:215], v[36:39]
	v_mfma_f32_16x16x32_bf16 v[32:35], v[174:177], v[212:215], v[32:35]
	s_setprio 0
	s_setprio 1
	v_mfma_f32_16x16x32_bf16 v[68:71], v[158:161], v[186:189], v[68:71]
	v_mfma_f32_16x16x32_bf16 v[64:67], v[178:181], v[186:189], v[64:67]
	v_mfma_f32_16x16x32_bf16 v[52:55], v[158:161], v[200:203], v[52:55]
	v_mfma_f32_16x16x32_bf16 v[48:51], v[178:181], v[200:203], v[48:51]
	v_mfma_f32_16x16x32_bf16 v[44:47], v[158:161], v[208:211], v[44:47]
	v_mfma_f32_16x16x32_bf16 v[40:43], v[178:181], v[208:211], v[40:43]
	v_mfma_f32_16x16x32_bf16 v[36:39], v[158:161], v[216:219], v[36:39]
	v_mfma_f32_16x16x32_bf16 v[32:35], v[178:181], v[216:219], v[32:35]
	s_setprio 0
	s_barrier
	s_add_i32 s43, s43, s28
	v_lshl_add_u64 v[162:163], s[24:25], 0, v[164:165]
	s_mov_b32 m0, s43
	ds_read_b128 v[182:185], v198 offset:16384
	ds_read_b128 v[186:189], v198 offset:17408
	ds_read_b128 v[190:193], v198 offset:18432
	ds_read_b128 v[200:203], v198 offset:19456
	ds_read_b128 v[204:207], v198 offset:20480
	ds_read_b128 v[208:211], v198 offset:21504
	ds_read_b128 v[212:215], v198 offset:22528
	ds_read_b128 v[216:219], v198 offset:23552
	global_load_lds_dwordx4 v[162:163], off
	s_add_i32 m0, s43, 0x2000
	s_add_u32 s44, s24, 0x40000
	v_lshl_add_u64 v[194:195], s[24:25], 0, v[144:145]
	s_addc_u32 s45, s25, 0
	s_add_i32 s43, s46, s28
	global_load_lds_dwordx4 v[194:195], off
	v_lshl_add_u64 v[220:221], s[44:45], 0, v[164:165]
	s_mov_b32 m0, s43
	v_lshl_add_u64 v[222:223], s[26:27], 0, v[146:147]
	global_load_lds_dwordx4 v[220:221], off
	v_lshl_add_u64 v[220:221], s[44:45], 0, v[144:145]
	s_add_i32 m0, s43, 0x2000
	s_nop 0
	global_load_lds_dwordx4 v[220:221], off
	v_lshl_add_u64 v[220:221], s[26:27], 0, v[148:149]
	s_mov_b32 m0, s29
	s_nop 0
	global_load_lds_dwordx4 v[220:221], off
	s_mov_b32 m0, s30
	s_nop 0
	global_load_lds_dwordx4 v[222:223], off
	s_waitcnt vmcnt(8)
	s_waitcnt lgkmcnt(0)
	s_barrier
; #define PG8_STAGE(bufoff, gbase, voff) do { _Pragma("unroll") for (int _i = 0; _i < 2; ++_i) \
;         __builtin_amdgcn_global_load_lds((const unsigned*)((const char*)(gbase) + (voff)[_i]), (PG8_LAS unsigned*)(lds + (bufoff) + ldsw + _i * 8192), 16, 0, 0); } while (0)
; #define PG8_LDA(dst, b, h) do { _Pragma("unroll") for (int m = 0; m < 4; ++m) _Pragma("unroll") for (int k = 0; k < 2; ++k) dst[m][k] = *(const PG8_LAS bf16x8*)(lds + PG8_SA(b, h) + aoff + m * 2048 + k * 1024); } while (0)
; #define PG8_LDB(dst, b, h) do { _Pragma("unroll") for (int n = 0; n < 2; ++n) _Pragma("unroll") for (int k = 0; k < 2; ++k) dst[n][k] = *(const PG8_LAS bf16x8*)(lds + PG8_SB(b, h) + boff + n * 2048 + k * 1024); } while (0)
; #define PG8_MMA(ai, bj, At, Bt) do { __builtin_amdgcn_s_setprio(1); _Pragma("unroll") for (int m = 0; m < 4; ++m) _Pragma("unroll") for (int n = 0; n < 2; ++n) _Pragma("unroll") for (int k = 0; k < 2; ++k) \
;         acc[ai][bj][m][n] = __builtin_amdgcn_mfma_f32_16x16x32_bf16(Bt[n][k], At[m][k], acc[ai][bj][m][n], 0, 0, 0); __builtin_amdgcn_s_setprio(0); } while (0)
; #define PG8_WAIT_V(n) asm volatile("s_waitcnt vmcnt(" #n ")" ::: "memory")
; #define PG8_WAIT_L(n) asm volatile("s_waitcnt lgkmcnt(" #n ")" ::: "memory")
; #define PG8_BAR __builtin_amdgcn_s_barrier()
; #define PG8_SCHED __builtin_amdgcn_sched_barrier(0)
; template <class Epi, class Sched, bool ALIGN_EPI, bool SP2, int KC>
; __device__ __forceinline__ void gemm_phase(PG8_LAS unsigned char* lds, const Gemm g, const Sched& S, const Epi& E, const int tid) {
;     ...
;             PG8_WAIT_V(8); PG8_WAIT_L(0); PG8_BAR; PG8_MMA(1, 0, At, B0); PG8_MMA(1, 1, At, B1); PG8_BAR; PG8_SCHED;
;             PG8_LDB(B0, 1, 0); PG8_LDB(B1, 1, 1); PG8_SCHED; PG8_LDA(At, 1, 0); PG8_STAGE(PG8_SA(0, 1), a2 + hstep, voffA);
;             PG8_WAIT_V(8); PG8_WAIT_L(0); PG8_BAR; PG8_MMA(0, 0, At, B0); PG8_MMA(0, 1, At, B1); PG8_BAR; PG8_SCHED;
	s_setprio 1
	s_waitcnt lgkmcnt(0)
	v_mfma_f32_16x16x32_bf16 v[92:95], v[128:131], v[182:185], v[92:95]
	v_mfma_f32_16x16x32_bf16 v[88:91], v[136:139], v[182:185], v[88:91]
	v_mfma_f32_16x16x32_bf16 v[84:87], v[128:131], v[190:193], v[84:87]
	v_mfma_f32_16x16x32_bf16 v[80:83], v[136:139], v[190:193], v[80:83]
	v_mfma_f32_16x16x32_bf16 v[76:79], v[128:131], v[204:207], v[76:79]
	v_mfma_f32_16x16x32_bf16 v[72:75], v[136:139], v[204:207], v[72:75]
	v_mfma_f32_16x16x32_bf16 v[60:63], v[128:131], v[212:215], v[60:63]
	v_mfma_f32_16x16x32_bf16 v[56:59], v[136:139], v[212:215], v[56:59]
	s_setprio 0
	s_setprio 1
	v_mfma_f32_16x16x32_bf16 v[92:95], v[132:135], v[186:189], v[92:95]
	v_mfma_f32_16x16x32_bf16 v[88:91], v[140:143], v[186:189], v[88:91]
	v_mfma_f32_16x16x32_bf16 v[84:87], v[132:135], v[200:203], v[84:87]
	v_mfma_f32_16x16x32_bf16 v[80:83], v[140:143], v[200:203], v[80:83]
	v_mfma_f32_16x16x32_bf16 v[76:79], v[132:135], v[208:211], v[76:79]
	v_mfma_f32_16x16x32_bf16 v[72:75], v[140:143], v[208:211], v[72:75]
	v_mfma_f32_16x16x32_bf16 v[60:63], v[132:135], v[216:219], v[60:63]
	v_mfma_f32_16x16x32_bf16 v[56:59], v[140:143], v[216:219], v[56:59]
	s_setprio 0
	s_setprio 1
	v_mfma_f32_16x16x32_bf16 v[28:31], v[154:157], v[182:185], v[28:31]
	v_mfma_f32_16x16x32_bf16 v[24:27], v[174:177], v[182:185], v[24:27]
	v_mfma_f32_16x16x32_bf16 v[20:23], v[154:157], v[190:193], v[20:23]
	v_mfma_f32_16x16x32_bf16 v[16:19], v[174:177], v[190:193], v[16:19]
	v_mfma_f32_16x16x32_bf16 v[12:15], v[154:157], v[204:207], v[12:15]
	v_mfma_f32_16x16x32_bf16 v[8:11], v[174:177], v[204:207], v[8:11]
	v_mfma_f32_16x16x32_bf16 v[4:7], v[154:157], v[212:215], v[4:7]
	v_mfma_f32_16x16x32_bf16 v[0:3], v[174:177], v[212:215], v[0:3]
	s_setprio 0
	s_setprio 1
	v_mfma_f32_16x16x32_bf16 v[28:31], v[158:161], v[186:189], v[28:31]
	v_mfma_f32_16x16x32_bf16 v[24:27], v[178:181], v[186:189], v[24:27]
	v_mfma_f32_16x16x32_bf16 v[20:23], v[158:161], v[200:203], v[20:23]
	v_mfma_f32_16x16x32_bf16 v[16:19], v[178:181], v[200:203], v[16:19]
	v_mfma_f32_16x16x32_bf16 v[12:15], v[158:161], v[208:211], v[12:15]
	v_mfma_f32_16x16x32_bf16 v[8:11], v[178:181], v[208:211], v[8:11]
	v_mfma_f32_16x16x32_bf16 v[4:7], v[158:161], v[216:219], v[4:7]
	v_mfma_f32_16x16x32_bf16 v[0:3], v[178:181], v[216:219], v[0:3]
	s_setprio 0
	s_barrier
	s_add_i32 s43, 0, 0x18000
	s_add_i32 s44, 0, 0x1c000
	v_add_u32_e32 v140, s43, v196
	v_add_u32_e32 v178, s44, v196
	ds_read_b128 v[128:131], v140
	ds_read_b128 v[132:135], v140 offset:1024
	ds_read_b128 v[136:139], v140 offset:2048
	ds_read_b128 v[140:143], v140 offset:3072
	ds_read_b128 v[154:157], v178
	ds_read_b128 v[158:161], v178 offset:1024
	ds_read_b128 v[174:177], v178 offset:2048
	ds_read_b128 v[178:181], v178 offset:3072
	s_add_u32 s26, s26, 0x40000
	s_addc_u32 s27, s27, 0
	s_mov_b32 m0, s31
	v_lshl_add_u64 v[234:235], s[26:27], 0, v[148:149]
	ds_read_b128 v[182:185], v198 offset:32768
	ds_read_b128 v[186:189], v198 offset:33792
	ds_read_b128 v[190:193], v198 offset:34816
	ds_read_b128 v[200:203], v198 offset:35840
	ds_read_b128 v[204:207], v198 offset:36864
	ds_read_b128 v[208:211], v198 offset:37888
	ds_read_b128 v[212:215], v198 offset:38912
	ds_read_b128 v[216:219], v198 offset:39936
	global_load_lds_dwordx4 v[234:235], off
	v_lshl_add_u64 v[234:235], s[26:27], 0, v[146:147]
	s_mov_b32 m0, s34
	s_nop 0
	global_load_lds_dwordx4 v[234:235], off
	s_waitcnt vmcnt(8)
	s_waitcnt lgkmcnt(0)
	s_barrier
	s_setprio 1
	s_waitcnt lgkmcnt(0)
	v_mfma_f32_16x16x32_bf16 v[124:127], v[128:131], v[182:185], v[124:127]
	v_mfma_f32_16x16x32_bf16 v[120:123], v[136:139], v[182:185], v[120:123]
	v_mfma_f32_16x16x32_bf16 v[116:119], v[128:131], v[190:193], v[116:119]
	v_mfma_f32_16x16x32_bf16 v[112:115], v[136:139], v[190:193], v[112:115]
	v_mfma_f32_16x16x32_bf16 v[108:111], v[128:131], v[204:207], v[108:111]
	v_mfma_f32_16x16x32_bf16 v[104:107], v[136:139], v[204:207], v[104:107]
	v_mfma_f32_16x16x32_bf16 v[100:103], v[128:131], v[212:215], v[100:103]
	v_mfma_f32_16x16x32_bf16 v[96:99], v[136:139], v[212:215], v[96:99]
	s_setprio 0
	s_setprio 1
	v_mfma_f32_16x16x32_bf16 v[124:127], v[132:135], v[186:189], v[124:127]
	v_mfma_f32_16x16x32_bf16 v[120:123], v[140:143], v[186:189], v[120:123]
	v_mfma_f32_16x16x32_bf16 v[116:119], v[132:135], v[200:203], v[116:119]
	v_mfma_f32_16x16x32_bf16 v[112:115], v[140:143], v[200:203], v[112:115]
	v_mfma_f32_16x16x32_bf16 v[108:111], v[132:135], v[208:211], v[108:111]
	v_mfma_f32_16x16x32_bf16 v[104:107], v[140:143], v[208:211], v[104:107]
	v_mfma_f32_16x16x32_bf16 v[100:103], v[132:135], v[216:219], v[100:103]
	v_mfma_f32_16x16x32_bf16 v[96:99], v[140:143], v[216:219], v[96:99]
	s_setprio 0
	s_setprio 1
	v_mfma_f32_16x16x32_bf16 v[68:71], v[154:157], v[182:185], v[68:71]
	v_mfma_f32_16x16x32_bf16 v[64:67], v[174:177], v[182:185], v[64:67]
	v_mfma_f32_16x16x32_bf16 v[52:55], v[154:157], v[190:193], v[52:55]
	v_mfma_f32_16x16x32_bf16 v[48:51], v[174:177], v[190:193], v[48:51]
	v_mfma_f32_16x16x32_bf16 v[44:47], v[154:157], v[204:207], v[44:47]
	v_mfma_f32_16x16x32_bf16 v[40:43], v[174:177], v[204:207], v[40:43]
	v_mfma_f32_16x16x32_bf16 v[36:39], v[154:157], v[212:215], v[36:39]
	v_mfma_f32_16x16x32_bf16 v[32:35], v[174:177], v[212:215], v[32:35]
	s_setprio 0
	s_setprio 1
	v_mfma_f32_16x16x32_bf16 v[68:71], v[158:161], v[186:189], v[68:71]
	v_mfma_f32_16x16x32_bf16 v[64:67], v[178:181], v[186:189], v[64:67]
	v_mfma_f32_16x16x32_bf16 v[52:55], v[158:161], v[200:203], v[52:55]
	v_mfma_f32_16x16x32_bf16 v[48:51], v[178:181], v[200:203], v[48:51]
	v_mfma_f32_16x16x32_bf16 v[44:47], v[158:161], v[208:211], v[44:47]
	v_mfma_f32_16x16x32_bf16 v[40:43], v[178:181], v[208:211], v[40:43]
	v_mfma_f32_16x16x32_bf16 v[36:39], v[158:161], v[216:219], v[36:39]
	v_mfma_f32_16x16x32_bf16 v[32:35], v[178:181], v[216:219], v[32:35]
	s_setprio 0
	s_barrier
; #define PG8_STAGE(bufoff, gbase, voff) do { _Pragma("unroll") for (int _i = 0; _i < 2; ++_i) \
;         __builtin_amdgcn_global_load_lds((const unsigned*)((const char*)(gbase) + (voff)[_i]), (PG8_LAS unsigned*)(lds + (bufoff) + ldsw + _i * 8192), 16, 0, 0); } while (0)
; #define PG8_LDA(dst, b, h) do { _Pragma("unroll") for (int m = 0; m < 4; ++m) _Pragma("unroll") for (int k = 0; k < 2; ++k) dst[m][k] = *(const PG8_LAS bf16x8*)(lds + PG8_SA(b, h) + aoff + m * 2048 + k * 1024); } while (0)
; #define PG8_MMA(ai, bj, At, Bt) do { __builtin_amdgcn_s_setprio(1); _Pragma("unroll") for (int m = 0; m < 4; ++m) _Pragma("unroll") for (int n = 0; n < 2; ++n) _Pragma("unroll") for (int k = 0; k < 2; ++k) \
;         acc[ai][bj][m][n] = __builtin_amdgcn_mfma_f32_16x16x32_bf16(Bt[n][k], At[m][k], acc[ai][bj][m][n], 0, 0, 0); __builtin_amdgcn_s_setprio(0); } while (0)
; #define PG8_WAIT_V(n) asm volatile("s_waitcnt vmcnt(" #n ")" ::: "memory")
; #define PG8_WAIT_L(n) asm volatile("s_waitcnt lgkmcnt(" #n ")" ::: "memory")
; #define PG8_BAR __builtin_amdgcn_s_barrier()
; #define PG8_SCHED __builtin_amdgcn_sched_barrier(0)
; template <class Epi, class Sched, bool ALIGN_EPI, bool SP2, int KC>
; __device__ __forceinline__ void gemm_phase(PG8_LAS unsigned char* lds, const Gemm g, const Sched& S, const Epi& E, const int tid) {
;     ...
;             PG8_LDA(At, 1, 1); PG8_STAGE(PG8_SB(1, 0), b3, voffB); PG8_STAGE(PG8_SB(1, 1), b3 + hstep, voffB); PG8_STAGE(PG8_SA(1, 0), a3, voffA);
;             PG8_WAIT_V(8); PG8_WAIT_L(0); PG8_BAR; PG8_MMA(1, 0, At, B0); PG8_MMA(1, 1, At, B1); PG8_BAR; PG8_SCHED;
;     ...
;         if constexpr (ALIGN_EPI) { if (wr == 0) PG8_BAR; }
	s_add_i32 s26, s43, s28
	v_lshl_add_u64 v[162:163], v[162:163], 0, s[86:87]
	s_mov_b32 m0, s26
	ds_read_b128 v[182:185], v198 offset:49152
	ds_read_b128 v[186:189], v198 offset:50176
	ds_read_b128 v[190:193], v198 offset:51200
	ds_read_b128 v[200:203], v198 offset:52224
	ds_read_b128 v[204:207], v198 offset:53248
	ds_read_b128 v[208:211], v198 offset:54272
	ds_read_b128 v[212:215], v198 offset:55296
	ds_read_b128 v[216:219], v198 offset:56320
	global_load_lds_dwordx4 v[162:163], off
	s_add_i32 m0, s26, 0x2000
	s_add_u32 s24, s24, 0x40080
	v_lshl_add_u64 v[162:163], v[194:195], 0, s[86:87]
	s_addc_u32 s25, s25, 0
	s_add_i32 s26, s44, s28
	global_load_lds_dwordx4 v[162:163], off
	v_lshl_add_u64 v[162:163], s[24:25], 0, v[164:165]
	s_mov_b32 m0, s26
	s_nop 0
	global_load_lds_dwordx4 v[162:163], off
	v_lshl_add_u64 v[162:163], s[24:25], 0, v[144:145]
	s_add_i32 m0, s26, 0x2000
	s_nop 0
	global_load_lds_dwordx4 v[162:163], off
	v_lshl_add_u64 v[162:163], v[220:221], 0, s[86:87]
	s_mov_b32 m0, s35
	s_nop 0
	global_load_lds_dwordx4 v[162:163], off
	v_lshl_add_u64 v[162:163], v[222:223], 0, s[86:87]
	s_mov_b32 m0, s36
	s_nop 0
	global_load_lds_dwordx4 v[162:163], off
	s_waitcnt vmcnt(8)
	s_waitcnt lgkmcnt(0)
	s_barrier
	s_setprio 1
	s_waitcnt lgkmcnt(0)
	v_mfma_f32_16x16x32_bf16 v[92:95], v[128:131], v[182:185], v[92:95]
	v_mfma_f32_16x16x32_bf16 v[88:91], v[136:139], v[182:185], v[88:91]
	v_mfma_f32_16x16x32_bf16 v[84:87], v[128:131], v[190:193], v[84:87]
	v_mfma_f32_16x16x32_bf16 v[80:83], v[136:139], v[190:193], v[80:83]
	v_mfma_f32_16x16x32_bf16 v[76:79], v[128:131], v[204:207], v[76:79]
	v_mfma_f32_16x16x32_bf16 v[72:75], v[136:139], v[204:207], v[72:75]
	v_mfma_f32_16x16x32_bf16 v[60:63], v[128:131], v[212:215], v[60:63]
	v_mfma_f32_16x16x32_bf16 v[56:59], v[136:139], v[212:215], v[56:59]
	s_setprio 0
	s_setprio 1
	v_mfma_f32_16x16x32_bf16 v[92:95], v[132:135], v[186:189], v[92:95]
	v_mfma_f32_16x16x32_bf16 v[88:91], v[140:143], v[186:189], v[88:91]
	v_mfma_f32_16x16x32_bf16 v[84:87], v[132:135], v[200:203], v[84:87]
	v_mfma_f32_16x16x32_bf16 v[80:83], v[140:143], v[200:203], v[80:83]
	v_mfma_f32_16x16x32_bf16 v[76:79], v[132:135], v[208:211], v[76:79]
	v_mfma_f32_16x16x32_bf16 v[72:75], v[140:143], v[208:211], v[72:75]
	v_mfma_f32_16x16x32_bf16 v[60:63], v[132:135], v[216:219], v[60:63]
	v_mfma_f32_16x16x32_bf16 v[56:59], v[140:143], v[216:219], v[56:59]
	s_setprio 0
	s_setprio 1
	v_mfma_f32_16x16x32_bf16 v[28:31], v[154:157], v[182:185], v[28:31]
	v_mfma_f32_16x16x32_bf16 v[24:27], v[174:177], v[182:185], v[24:27]
	v_mfma_f32_16x16x32_bf16 v[20:23], v[154:157], v[190:193], v[20:23]
	v_mfma_f32_16x16x32_bf16 v[16:19], v[174:177], v[190:193], v[16:19]
	v_mfma_f32_16x16x32_bf16 v[12:15], v[154:157], v[204:207], v[12:15]
	v_mfma_f32_16x16x32_bf16 v[8:11], v[174:177], v[204:207], v[8:11]
	v_mfma_f32_16x16x32_bf16 v[4:7], v[154:157], v[212:215], v[4:7]
	v_mfma_f32_16x16x32_bf16 v[0:3], v[174:177], v[212:215], v[0:3]
	s_setprio 0
	s_setprio 1
	v_mfma_f32_16x16x32_bf16 v[28:31], v[158:161], v[186:189], v[28:31]
	v_mfma_f32_16x16x32_bf16 v[24:27], v[178:181], v[186:189], v[24:27]
	v_mfma_f32_16x16x32_bf16 v[20:23], v[158:161], v[200:203], v[20:23]
	v_mfma_f32_16x16x32_bf16 v[16:19], v[178:181], v[200:203], v[16:19]
	v_mfma_f32_16x16x32_bf16 v[12:15], v[158:161], v[208:211], v[12:15]
	v_mfma_f32_16x16x32_bf16 v[8:11], v[178:181], v[208:211], v[8:11]
	v_mfma_f32_16x16x32_bf16 v[4:7], v[158:161], v[216:219], v[4:7]
	v_mfma_f32_16x16x32_bf16 v[0:3], v[178:181], v[216:219], v[0:3]
	s_setprio 0
	s_barrier
	s_add_i32 s42, s42, 2
	s_add_u32 s22, s22, 0x100
	s_addc_u32 s23, s23, 0
	s_add_u32 s40, s40, 0x100
	s_addc_u32 s41, s41, 0
	s_cmp_gt_u32 s42, 13
	s_cbranch_scc0 .LBB0_116
	s_and_b64 vcc, exec, s[10:11]
	s_cbranch_vccz .LBB0_119
	s_barrier

; #define PG8_STAGE(bufoff, gbase, voff) do { _Pragma("unroll") for (int _i = 0; _i < 2; ++_i) \
;         __builtin_amdgcn_global_load_lds((const unsigned*)((const char*)(gbase) + (voff)[_i]), (PG8_LAS unsigned*)(lds + (bufoff) + ldsw + _i * 8192), 16, 0, 0); } while (0)
; #define PG8_LDA(dst, b, h) do { _Pragma("unroll") for (int m = 0; m < 4; ++m) _Pragma("unroll") for (int k = 0; k < 2; ++k) dst[m][k] = *(const PG8_LAS bf16x8*)(lds + PG8_SA(b, h) + aoff + m * 2048 + k * 1024); } while (0)
; #define PG8_LDB(dst, b, h) do { _Pragma("unroll") for (int n = 0; n < 2; ++n) _Pragma("unroll") for (int k = 0; k < 2; ++k) dst[n][k] = *(const PG8_LAS bf16x8*)(lds + PG8_SB(b, h) + boff + n * 2048 + k * 1024); } while (0)
; #define PG8_MMA(ai, bj, At, Bt) do { __builtin_amdgcn_s_setprio(1); _Pragma("unroll") for (int m = 0; m < 4; ++m) _Pragma("unroll") for (int n = 0; n < 2; ++n) _Pragma("unroll") for (int k = 0; k < 2; ++k) \
;         acc[ai][bj][m][n] = __builtin_amdgcn_mfma_f32_16x16x32_bf16(Bt[n][k], At[m][k], acc[ai][bj][m][n], 0, 0, 0); __builtin_amdgcn_s_setprio(0); } while (0)
; #define PG8_WAIT_V(n) asm volatile("s_waitcnt vmcnt(" #n ")" ::: "memory")
; #define PG8_WAIT_L(n) asm volatile("s_waitcnt lgkmcnt(" #n ")" ::: "memory")
; template <class Epi, class Sched, bool ALIGN_EPI, bool SP2, int KC>
; __device__ __forceinline__ void gemm_phase(PG8_LAS unsigned char* lds, const Gemm g, const Sched& S, const Epi& E, const int tid) {
;     ...
;             const bool last = (t == nt - 2);
;             const char* a1 = cA + (size_t)(t + 1) * kstep;
;             const char* a2 = last ? nA : cA + (size_t)(t + 2) * kstep; const char* b2 = last ? nB : cB + (size_t)(t + 2) * kstep;
;             const char* a3 = a2 + kstep; const char* b3 = b2 + kstep;
;             if (last && has_next) S.a_ready(nxt);
;             if constexpr (SP2) {
;             PG8_LDB(B0, 0, 0); PG8_LDB(B1, 0, 1); PG8_SCHED; PG8_LDA(At, 0, 0); PG8_STAGE(PG8_SA(1, 1), a1 + hstep, voffA);
;             PG8_WAIT_V(8); PG8_WAIT_L(0); PG8_BAR; PG8_MMA(0, 0, At, B0); PG8_MMA(0, 1, At, B1); PG8_BAR; PG8_SCHED;
;             PG8_LDA(At, 0, 1); PG8_STAGE(PG8_SB(0, 0), b2, voffB); PG8_STAGE(PG8_SB(0, 1), b2 + hstep, voffB); PG8_STAGE(PG8_SA(0, 0), a2, voffA);
;             PG8_WAIT_V(8); PG8_WAIT_L(0); PG8_BAR; PG8_MMA(1, 0, At, B0); PG8_MMA(1, 1, At, B1); PG8_BAR; PG8_SCHED;
.LBB0_162:
	s_add_u32 s16, s4, 0xfffc0080
	s_addc_u32 s17, s5, -1
	s_add_i32 s71, 0, 0x10000
	s_cmp_eq_u32 s70, 12
	s_cselect_b32 s19, s41, s17
	s_cselect_b32 s18, s47, s16
	s_cselect_b32 s17, s39, s65
	s_cselect_b32 s16, s49, s64
	s_add_i32 s79, 0, 0x14000
	v_add_u32_e32 v146, s71, v245
	v_add_u32_e32 v162, s79, v245
	ds_read_b128 v[128:131], v146
	ds_read_b128 v[132:135], v146 offset:1024
	ds_read_b128 v[136:139], v146 offset:2048
	ds_read_b128 v[146:149], v146 offset:3072
	ds_read_b128 v[150:153], v162
	ds_read_b128 v[154:157], v162 offset:1024
	ds_read_b128 v[158:161], v162 offset:2048
	ds_read_b128 v[174:177], v162 offset:3072
	v_lshl_add_u64 v[162:163], s[4:5], 0, v[142:143]
	s_add_i32 m0, s7, 0xc000
	ds_read_b128 v[178:181], v249
	ds_read_b128 v[182:185], v249 offset:1024
	ds_read_b128 v[186:189], v249 offset:2048
	ds_read_b128 v[190:193], v249 offset:3072
	ds_read_b128 v[194:197], v249 offset:4096
	ds_read_b128 v[198:201], v249 offset:5120
	ds_read_b128 v[202:205], v249 offset:6144
	ds_read_b128 v[206:209], v249 offset:7168
	global_load_lds_dwordx4 v[162:163], off
	v_lshl_add_u64 v[162:163], s[4:5], 0, v[144:145]
	s_add_i32 m0, s7, 0xe000
	s_nop 0
	global_load_lds_dwordx4 v[162:163], off
	s_waitcnt vmcnt(8)
	s_waitcnt lgkmcnt(0)
	s_barrier
	s_setprio 1
	s_waitcnt lgkmcnt(0)
	v_mfma_f32_16x16x32_bf16 v[124:127], v[128:131], v[178:181], v[124:127]
	v_mfma_f32_16x16x32_bf16 v[108:111], v[136:139], v[178:181], v[108:111]
	v_mfma_f32_16x16x32_bf16 v[120:123], v[128:131], v[186:189], v[120:123]
	v_mfma_f32_16x16x32_bf16 v[104:107], v[136:139], v[186:189], v[104:107]
	v_mfma_f32_16x16x32_bf16 v[116:119], v[128:131], v[194:197], v[116:119]
	v_mfma_f32_16x16x32_bf16 v[100:103], v[136:139], v[194:197], v[100:103]
	v_mfma_f32_16x16x32_bf16 v[112:115], v[128:131], v[202:205], v[112:115]
	v_mfma_f32_16x16x32_bf16 v[96:99], v[136:139], v[202:205], v[96:99]
	s_setprio 0
	s_setprio 1
	v_mfma_f32_16x16x32_bf16 v[124:127], v[132:135], v[182:185], v[124:127]
	v_mfma_f32_16x16x32_bf16 v[108:111], v[146:149], v[182:185], v[108:111]
	v_mfma_f32_16x16x32_bf16 v[120:123], v[132:135], v[190:193], v[120:123]
	v_mfma_f32_16x16x32_bf16 v[104:107], v[146:149], v[190:193], v[104:107]
	v_mfma_f32_16x16x32_bf16 v[116:119], v[132:135], v[198:201], v[116:119]
	v_mfma_f32_16x16x32_bf16 v[100:103], v[146:149], v[198:201], v[100:103]
	v_mfma_f32_16x16x32_bf16 v[112:115], v[132:135], v[206:209], v[112:115]
	v_mfma_f32_16x16x32_bf16 v[96:99], v[146:149], v[206:209], v[96:99]
	s_setprio 0
	s_setprio 1
	v_mfma_f32_16x16x32_bf16 v[92:95], v[150:153], v[178:181], v[92:95]
	v_mfma_f32_16x16x32_bf16 v[76:79], v[158:161], v[178:181], v[76:79]
	v_mfma_f32_16x16x32_bf16 v[88:91], v[150:153], v[186:189], v[88:91]
	v_mfma_f32_16x16x32_bf16 v[72:75], v[158:161], v[186:189], v[72:75]
	v_mfma_f32_16x16x32_bf16 v[84:87], v[150:153], v[194:197], v[84:87]
	v_mfma_f32_16x16x32_bf16 v[68:71], v[158:161], v[194:197], v[68:71]
	v_mfma_f32_16x16x32_bf16 v[80:83], v[150:153], v[202:205], v[80:83]
	v_mfma_f32_16x16x32_bf16 v[64:67], v[158:161], v[202:205], v[64:67]
	s_setprio 0
	s_setprio 1
	v_mfma_f32_16x16x32_bf16 v[92:95], v[154:157], v[182:185], v[92:95]
	v_mfma_f32_16x16x32_bf16 v[76:79], v[174:177], v[182:185], v[76:79]
	v_mfma_f32_16x16x32_bf16 v[88:91], v[154:157], v[190:193], v[88:91]
	v_mfma_f32_16x16x32_bf16 v[72:75], v[174:177], v[190:193], v[72:75]
	v_mfma_f32_16x16x32_bf16 v[84:87], v[154:157], v[198:201], v[84:87]
	v_mfma_f32_16x16x32_bf16 v[68:71], v[174:177], v[198:201], v[68:71]
	v_mfma_f32_16x16x32_bf16 v[80:83], v[154:157], v[206:209], v[80:83]
	v_mfma_f32_16x16x32_bf16 v[64:67], v[174:177], v[206:209], v[64:67]
	s_setprio 0
	s_barrier
	s_add_i32 s71, s71, s6
	v_lshl_add_u64 v[162:163], s[16:17], 0, v[164:165]
	s_mov_b32 m0, s71
	ds_read_b128 v[178:181], v249 offset:16384
	ds_read_b128 v[182:185], v249 offset:17408
	ds_read_b128 v[186:189], v249 offset:18432
	ds_read_b128 v[190:193], v249 offset:19456
	ds_read_b128 v[194:197], v249 offset:20480
	ds_read_b128 v[198:201], v249 offset:21504
	ds_read_b128 v[202:205], v249 offset:22528
	ds_read_b128 v[206:209], v249 offset:23552
	global_load_lds_dwordx4 v[162:163], off
	s_add_i32 m0, s71, 0x2000
	s_add_u32 s92, s16, 0x40000
	v_lshl_add_u64 v[210:211], s[16:17], 0, v[140:141]
	s_addc_u32 s93, s17, 0
	s_add_i32 s71, s79, s6
	global_load_lds_dwordx4 v[210:211], off
	v_lshl_add_u64 v[212:213], s[92:93], 0, v[164:165]
	s_mov_b32 m0, s71
	v_lshl_add_u64 v[214:215], s[18:19], 0, v[140:141]
	global_load_lds_dwordx4 v[212:213], off
	v_lshl_add_u64 v[212:213], s[92:93], 0, v[140:141]
	s_add_i32 m0, s71, 0x2000
	s_nop 0
	global_load_lds_dwordx4 v[212:213], off
	v_lshl_add_u64 v[212:213], s[18:19], 0, v[164:165]
	s_mov_b32 m0, s7
	s_nop 0
	global_load_lds_dwordx4 v[212:213], off
	s_mov_b32 m0, s58
	s_nop 0
	global_load_lds_dwordx4 v[214:215], off
	s_waitcnt vmcnt(8)
	s_waitcnt lgkmcnt(0)
	s_barrier
; #define PG8_STAGE(bufoff, gbase, voff) do { _Pragma("unroll") for (int _i = 0; _i < 2; ++_i) \
;         __builtin_amdgcn_global_load_lds((const unsigned*)((const char*)(gbase) + (voff)[_i]), (PG8_LAS unsigned*)(lds + (bufoff) + ldsw + _i * 8192), 16, 0, 0); } while (0)
; #define PG8_LDA(dst, b, h) do { _Pragma("unroll") for (int m = 0; m < 4; ++m) _Pragma("unroll") for (int k = 0; k < 2; ++k) dst[m][k] = *(const PG8_LAS bf16x8*)(lds + PG8_SA(b, h) + aoff + m * 2048 + k * 1024); } while (0)
; #define PG8_LDB(dst, b, h) do { _Pragma("unroll") for (int n = 0; n < 2; ++n) _Pragma("unroll") for (int k = 0; k < 2; ++k) dst[n][k] = *(const PG8_LAS bf16x8*)(lds + PG8_SB(b, h) + boff + n * 2048 + k * 1024); } while (0)
; #define PG8_MMA(ai, bj, At, Bt) do { __builtin_amdgcn_s_setprio(1); _Pragma("unroll") for (int m = 0; m < 4; ++m) _Pragma("unroll") for (int n = 0; n < 2; ++n) _Pragma("unroll") for (int k = 0; k < 2; ++k) \
;         acc[ai][bj][m][n] = __builtin_amdgcn_mfma_f32_16x16x32_bf16(Bt[n][k], At[m][k], acc[ai][bj][m][n], 0, 0, 0); __builtin_amdgcn_s_setprio(0); } while (0)
; #define PG8_WAIT_V(n) asm volatile("s_waitcnt vmcnt(" #n ")" ::: "memory")
; #define PG8_WAIT_L(n) asm volatile("s_waitcnt lgkmcnt(" #n ")" ::: "memory")
; #define PG8_BAR __builtin_amdgcn_s_barrier()
; #define PG8_SCHED __builtin_amdgcn_sched_barrier(0)
; template <class Epi, class Sched, bool ALIGN_EPI, bool SP2, int KC>
; __device__ __forceinline__ void gemm_phase(PG8_LAS unsigned char* lds, const Gemm g, const Sched& S, const Epi& E, const int tid) {
;     ...
;             PG8_WAIT_V(8); PG8_WAIT_L(0); PG8_BAR; PG8_MMA(1, 0, At, B0); PG8_MMA(1, 1, At, B1); PG8_BAR; PG8_SCHED;
;             PG8_LDB(B0, 1, 0); PG8_LDB(B1, 1, 1); PG8_SCHED; PG8_LDA(At, 1, 0); PG8_STAGE(PG8_SA(0, 1), a2 + hstep, voffA);
;             PG8_WAIT_V(8); PG8_WAIT_L(0); PG8_BAR; PG8_MMA(0, 0, At, B0); PG8_MMA(0, 1, At, B1); PG8_BAR; PG8_SCHED;
	s_setprio 1
	s_waitcnt lgkmcnt(0)
	v_mfma_f32_16x16x32_bf16 v[60:63], v[128:131], v[178:181], v[60:63]
	v_mfma_f32_16x16x32_bf16 v[44:47], v[136:139], v[178:181], v[44:47]
	v_mfma_f32_16x16x32_bf16 v[56:59], v[128:131], v[186:189], v[56:59]
	v_mfma_f32_16x16x32_bf16 v[40:43], v[136:139], v[186:189], v[40:43]
	v_mfma_f32_16x16x32_bf16 v[52:55], v[128:131], v[194:197], v[52:55]
	v_mfma_f32_16x16x32_bf16 v[36:39], v[136:139], v[194:197], v[36:39]
	v_mfma_f32_16x16x32_bf16 v[48:51], v[128:131], v[202:205], v[48:51]
	v_mfma_f32_16x16x32_bf16 v[32:35], v[136:139], v[202:205], v[32:35]
	s_setprio 0
	s_setprio 1
	v_mfma_f32_16x16x32_bf16 v[60:63], v[132:135], v[182:185], v[60:63]
	v_mfma_f32_16x16x32_bf16 v[44:47], v[146:149], v[182:185], v[44:47]
	v_mfma_f32_16x16x32_bf16 v[56:59], v[132:135], v[190:193], v[56:59]
	v_mfma_f32_16x16x32_bf16 v[40:43], v[146:149], v[190:193], v[40:43]
	v_mfma_f32_16x16x32_bf16 v[52:55], v[132:135], v[198:201], v[52:55]
	v_mfma_f32_16x16x32_bf16 v[36:39], v[146:149], v[198:201], v[36:39]
	v_mfma_f32_16x16x32_bf16 v[48:51], v[132:135], v[206:209], v[48:51]
	v_mfma_f32_16x16x32_bf16 v[32:35], v[146:149], v[206:209], v[32:35]
	s_setprio 0
	s_setprio 1
	v_mfma_f32_16x16x32_bf16 v[28:31], v[150:153], v[178:181], v[28:31]
	v_mfma_f32_16x16x32_bf16 v[12:15], v[158:161], v[178:181], v[12:15]
	v_mfma_f32_16x16x32_bf16 v[24:27], v[150:153], v[186:189], v[24:27]
	v_mfma_f32_16x16x32_bf16 v[8:11], v[158:161], v[186:189], v[8:11]
	v_mfma_f32_16x16x32_bf16 v[20:23], v[150:153], v[194:197], v[20:23]
	v_mfma_f32_16x16x32_bf16 v[4:7], v[158:161], v[194:197], v[4:7]
	v_mfma_f32_16x16x32_bf16 v[16:19], v[150:153], v[202:205], v[16:19]
	v_mfma_f32_16x16x32_bf16 v[0:3], v[158:161], v[202:205], v[0:3]
	s_setprio 0
	s_setprio 1
	v_mfma_f32_16x16x32_bf16 v[28:31], v[154:157], v[182:185], v[28:31]
	v_mfma_f32_16x16x32_bf16 v[12:15], v[174:177], v[182:185], v[12:15]
	v_mfma_f32_16x16x32_bf16 v[24:27], v[154:157], v[190:193], v[24:27]
	v_mfma_f32_16x16x32_bf16 v[8:11], v[174:177], v[190:193], v[8:11]
	v_mfma_f32_16x16x32_bf16 v[20:23], v[154:157], v[198:201], v[20:23]
	v_mfma_f32_16x16x32_bf16 v[4:7], v[174:177], v[198:201], v[4:7]
	v_mfma_f32_16x16x32_bf16 v[16:19], v[154:157], v[206:209], v[16:19]
	v_mfma_f32_16x16x32_bf16 v[0:3], v[174:177], v[206:209], v[0:3]
	s_setprio 0
	s_barrier
	s_add_i32 s71, 0, 0x18000
	s_add_i32 s79, 0, 0x1c000
	v_add_u32_e32 v146, s71, v245
	v_add_u32_e32 v174, s79, v245
	ds_read_b128 v[128:131], v146
	ds_read_b128 v[132:135], v146 offset:1024
	ds_read_b128 v[136:139], v146 offset:2048
	ds_read_b128 v[146:149], v146 offset:3072
	ds_read_b128 v[150:153], v174
	ds_read_b128 v[154:157], v174 offset:1024
	ds_read_b128 v[158:161], v174 offset:2048
	ds_read_b128 v[174:177], v174 offset:3072
	s_add_u32 s18, s18, 0x40000
	s_addc_u32 s19, s19, 0
	s_mov_b32 m0, s59
	v_lshl_add_u64 v[216:217], s[18:19], 0, v[164:165]
	ds_read_b128 v[178:181], v249 offset:32768
	ds_read_b128 v[182:185], v249 offset:33792
	ds_read_b128 v[186:189], v249 offset:34816
	ds_read_b128 v[190:193], v249 offset:35840
	ds_read_b128 v[194:197], v249 offset:36864
	ds_read_b128 v[198:201], v249 offset:37888
	ds_read_b128 v[202:205], v249 offset:38912
	ds_read_b128 v[206:209], v249 offset:39936
	global_load_lds_dwordx4 v[216:217], off
	v_lshl_add_u64 v[216:217], s[18:19], 0, v[140:141]
	s_mov_b32 m0, s74
	s_nop 0
	global_load_lds_dwordx4 v[216:217], off
	s_waitcnt vmcnt(8)
	s_waitcnt lgkmcnt(0)
	s_barrier
	s_setprio 1
	s_waitcnt lgkmcnt(0)
	v_mfma_f32_16x16x32_bf16 v[124:127], v[128:131], v[178:181], v[124:127]
	v_mfma_f32_16x16x32_bf16 v[108:111], v[136:139], v[178:181], v[108:111]
	v_mfma_f32_16x16x32_bf16 v[120:123], v[128:131], v[186:189], v[120:123]
	v_mfma_f32_16x16x32_bf16 v[104:107], v[136:139], v[186:189], v[104:107]
	v_mfma_f32_16x16x32_bf16 v[116:119], v[128:131], v[194:197], v[116:119]
	v_mfma_f32_16x16x32_bf16 v[100:103], v[136:139], v[194:197], v[100:103]
	v_mfma_f32_16x16x32_bf16 v[112:115], v[128:131], v[202:205], v[112:115]
	v_mfma_f32_16x16x32_bf16 v[96:99], v[136:139], v[202:205], v[96:99]
	s_setprio 0
	s_setprio 1
	v_mfma_f32_16x16x32_bf16 v[124:127], v[132:135], v[182:185], v[124:127]
	v_mfma_f32_16x16x32_bf16 v[108:111], v[146:149], v[182:185], v[108:111]
	v_mfma_f32_16x16x32_bf16 v[120:123], v[132:135], v[190:193], v[120:123]
	v_mfma_f32_16x16x32_bf16 v[104:107], v[146:149], v[190:193], v[104:107]
	v_mfma_f32_16x16x32_bf16 v[116:119], v[132:135], v[198:201], v[116:119]
	v_mfma_f32_16x16x32_bf16 v[100:103], v[146:149], v[198:201], v[100:103]
	v_mfma_f32_16x16x32_bf16 v[112:115], v[132:135], v[206:209], v[112:115]
	v_mfma_f32_16x16x32_bf16 v[96:99], v[146:149], v[206:209], v[96:99]
	s_setprio 0
	s_setprio 1
	v_mfma_f32_16x16x32_bf16 v[92:95], v[150:153], v[178:181], v[92:95]
	v_mfma_f32_16x16x32_bf16 v[76:79], v[158:161], v[178:181], v[76:79]
	v_mfma_f32_16x16x32_bf16 v[88:91], v[150:153], v[186:189], v[88:91]
	v_mfma_f32_16x16x32_bf16 v[72:75], v[158:161], v[186:189], v[72:75]
	v_mfma_f32_16x16x32_bf16 v[84:87], v[150:153], v[194:197], v[84:87]
	v_mfma_f32_16x16x32_bf16 v[68:71], v[158:161], v[194:197], v[68:71]
	v_mfma_f32_16x16x32_bf16 v[80:83], v[150:153], v[202:205], v[80:83]
	v_mfma_f32_16x16x32_bf16 v[64:67], v[158:161], v[202:205], v[64:67]
	s_setprio 0
	s_setprio 1
	v_mfma_f32_16x16x32_bf16 v[92:95], v[154:157], v[182:185], v[92:95]
	v_mfma_f32_16x16x32_bf16 v[76:79], v[174:177], v[182:185], v[76:79]
	v_mfma_f32_16x16x32_bf16 v[88:91], v[154:157], v[190:193], v[88:91]
	v_mfma_f32_16x16x32_bf16 v[72:75], v[174:177], v[190:193], v[72:75]
	v_mfma_f32_16x16x32_bf16 v[84:87], v[154:157], v[198:201], v[84:87]
	v_mfma_f32_16x16x32_bf16 v[68:71], v[174:177], v[198:201], v[68:71]
	v_mfma_f32_16x16x32_bf16 v[80:83], v[154:157], v[206:209], v[80:83]
	v_mfma_f32_16x16x32_bf16 v[64:67], v[174:177], v[206:209], v[64:67]
	s_setprio 0
	s_barrier
; #define PG8_STAGE(bufoff, gbase, voff) do { _Pragma("unroll") for (int _i = 0; _i < 2; ++_i) \
;         __builtin_amdgcn_global_load_lds((const unsigned*)((const char*)(gbase) + (voff)[_i]), (PG8_LAS unsigned*)(lds + (bufoff) + ldsw + _i * 8192), 16, 0, 0); } while (0)
; #define PG8_LDA(dst, b, h) do { _Pragma("unroll") for (int m = 0; m < 4; ++m) _Pragma("unroll") for (int k = 0; k < 2; ++k) dst[m][k] = *(const PG8_LAS bf16x8*)(lds + PG8_SA(b, h) + aoff + m * 2048 + k * 1024); } while (0)
; #define PG8_MMA(ai, bj, At, Bt) do { __builtin_amdgcn_s_setprio(1); _Pragma("unroll") for (int m = 0; m < 4; ++m) _Pragma("unroll") for (int n = 0; n < 2; ++n) _Pragma("unroll") for (int k = 0; k < 2; ++k) \
;         acc[ai][bj][m][n] = __builtin_amdgcn_mfma_f32_16x16x32_bf16(Bt[n][k], At[m][k], acc[ai][bj][m][n], 0, 0, 0); __builtin_amdgcn_s_setprio(0); } while (0)
; #define PG8_WAIT_V(n) asm volatile("s_waitcnt vmcnt(" #n ")" ::: "memory")
; #define PG8_WAIT_L(n) asm volatile("s_waitcnt lgkmcnt(" #n ")" ::: "memory")
; #define PG8_BAR __builtin_amdgcn_s_barrier()
; #define PG8_SCHED __builtin_amdgcn_sched_barrier(0)
; template <class Epi, class Sched, bool ALIGN_EPI, bool SP2, int KC>
; __device__ __forceinline__ void gemm_phase(PG8_LAS unsigned char* lds, const Gemm g, const Sched& S, const Epi& E, const int tid) {
;     ...
;             PG8_LDA(At, 1, 1); PG8_STAGE(PG8_SB(1, 0), b3, voffB); PG8_STAGE(PG8_SB(1, 1), b3 + hstep, voffB); PG8_STAGE(PG8_SA(1, 0), a3, voffA);
;             PG8_WAIT_V(8); PG8_WAIT_L(0); PG8_BAR; PG8_MMA(1, 0, At, B0); PG8_MMA(1, 1, At, B1); PG8_BAR; PG8_SCHED;
;     ...
;         if constexpr (ALIGN_EPI) { if (wr == 0) PG8_BAR; }
	s_add_i32 s18, s71, s6
	v_lshl_add_u64 v[162:163], v[162:163], 0, s[86:87]
	s_mov_b32 m0, s18
	ds_read_b128 v[178:181], v249 offset:49152
	ds_read_b128 v[182:185], v249 offset:50176
	ds_read_b128 v[186:189], v249 offset:51200
	ds_read_b128 v[190:193], v249 offset:52224
	ds_read_b128 v[194:197], v249 offset:53248
	ds_read_b128 v[198:201], v249 offset:54272
	ds_read_b128 v[202:205], v249 offset:55296
	ds_read_b128 v[206:209], v249 offset:56320
	global_load_lds_dwordx4 v[162:163], off
	s_add_i32 m0, s18, 0x2000
	s_add_u32 s16, s16, 0x40080
	v_lshl_add_u64 v[162:163], v[210:211], 0, s[86:87]
	s_addc_u32 s17, s17, 0
	s_add_i32 s18, s79, s6
	global_load_lds_dwordx4 v[162:163], off
	v_lshl_add_u64 v[162:163], s[16:17], 0, v[164:165]
	s_mov_b32 m0, s18
	s_nop 0
	global_load_lds_dwordx4 v[162:163], off
	v_lshl_add_u64 v[162:163], s[16:17], 0, v[140:141]
	s_add_i32 m0, s18, 0x2000
	s_nop 0
	global_load_lds_dwordx4 v[162:163], off
	v_lshl_add_u64 v[162:163], v[212:213], 0, s[86:87]
	s_mov_b32 m0, s76
	s_nop 0
	global_load_lds_dwordx4 v[162:163], off
	v_lshl_add_u64 v[162:163], v[214:215], 0, s[86:87]
	s_mov_b32 m0, s77
	s_nop 0
	global_load_lds_dwordx4 v[162:163], off
	s_waitcnt vmcnt(8)
	s_waitcnt lgkmcnt(0)
	s_barrier
	s_setprio 1
	s_waitcnt lgkmcnt(0)
	v_mfma_f32_16x16x32_bf16 v[60:63], v[128:131], v[178:181], v[60:63]
	v_mfma_f32_16x16x32_bf16 v[44:47], v[136:139], v[178:181], v[44:47]
	v_mfma_f32_16x16x32_bf16 v[56:59], v[128:131], v[186:189], v[56:59]
	v_mfma_f32_16x16x32_bf16 v[40:43], v[136:139], v[186:189], v[40:43]
	v_mfma_f32_16x16x32_bf16 v[52:55], v[128:131], v[194:197], v[52:55]
	v_mfma_f32_16x16x32_bf16 v[36:39], v[136:139], v[194:197], v[36:39]
	v_mfma_f32_16x16x32_bf16 v[48:51], v[128:131], v[202:205], v[48:51]
	v_mfma_f32_16x16x32_bf16 v[32:35], v[136:139], v[202:205], v[32:35]
	s_setprio 0
	s_setprio 1
	v_mfma_f32_16x16x32_bf16 v[60:63], v[132:135], v[182:185], v[60:63]
	v_mfma_f32_16x16x32_bf16 v[44:47], v[146:149], v[182:185], v[44:47]
	v_mfma_f32_16x16x32_bf16 v[56:59], v[132:135], v[190:193], v[56:59]
	v_mfma_f32_16x16x32_bf16 v[40:43], v[146:149], v[190:193], v[40:43]
	v_mfma_f32_16x16x32_bf16 v[52:55], v[132:135], v[198:201], v[52:55]
	v_mfma_f32_16x16x32_bf16 v[36:39], v[146:149], v[198:201], v[36:39]
	v_mfma_f32_16x16x32_bf16 v[48:51], v[132:135], v[206:209], v[48:51]
	v_mfma_f32_16x16x32_bf16 v[32:35], v[146:149], v[206:209], v[32:35]
	s_setprio 0
	s_setprio 1
	v_mfma_f32_16x16x32_bf16 v[28:31], v[150:153], v[178:181], v[28:31]
	v_mfma_f32_16x16x32_bf16 v[12:15], v[158:161], v[178:181], v[12:15]
	v_mfma_f32_16x16x32_bf16 v[24:27], v[150:153], v[186:189], v[24:27]
	v_mfma_f32_16x16x32_bf16 v[8:11], v[158:161], v[186:189], v[8:11]
	v_mfma_f32_16x16x32_bf16 v[20:23], v[150:153], v[194:197], v[20:23]
	v_mfma_f32_16x16x32_bf16 v[4:7], v[158:161], v[194:197], v[4:7]
	v_mfma_f32_16x16x32_bf16 v[16:19], v[150:153], v[202:205], v[16:19]
	v_mfma_f32_16x16x32_bf16 v[0:3], v[158:161], v[202:205], v[0:3]
	s_setprio 0
	s_setprio 1
	v_mfma_f32_16x16x32_bf16 v[28:31], v[154:157], v[182:185], v[28:31]
	v_mfma_f32_16x16x32_bf16 v[12:15], v[174:177], v[182:185], v[12:15]
	v_mfma_f32_16x16x32_bf16 v[24:27], v[154:157], v[190:193], v[24:27]
	v_mfma_f32_16x16x32_bf16 v[8:11], v[174:177], v[190:193], v[8:11]
	v_mfma_f32_16x16x32_bf16 v[20:23], v[154:157], v[198:201], v[20:23]
	v_mfma_f32_16x16x32_bf16 v[4:7], v[174:177], v[198:201], v[4:7]
	v_mfma_f32_16x16x32_bf16 v[16:19], v[154:157], v[206:209], v[16:19]
	v_mfma_f32_16x16x32_bf16 v[0:3], v[174:177], v[206:209], v[0:3]
	s_setprio 0
	s_barrier
	s_add_i32 s70, s70, 2
	s_add_u32 s4, s4, 0x100
	s_addc_u32 s5, s5, 0
	s_add_u32 s64, s64, 0x100
	s_addc_u32 s65, s65, 0
	s_cmp_gt_u32 s70, 13
	s_cbranch_scc0 .LBB0_162
	s_and_b64 vcc, exec, s[30:31]
	s_cbranch_vccz .LBB0_165
	s_barrier

; #define PG8_STAGE(bufoff, gbase, voff) do { _Pragma("unroll") for (int _i = 0; _i < 2; ++_i) \
;         __builtin_amdgcn_global_load_lds((const unsigned*)((const char*)(gbase) + (voff)[_i]), (PG8_LAS unsigned*)(lds + (bufoff) + ldsw + _i * 8192), 16, 0, 0); } while (0)
; #define PG8_LDA(dst, b, h) do { _Pragma("unroll") for (int m = 0; m < 4; ++m) _Pragma("unroll") for (int k = 0; k < 2; ++k) dst[m][k] = *(const PG8_LAS bf16x8*)(lds + PG8_SA(b, h) + aoff + m * 2048 + k * 1024); } while (0)
; #define PG8_LDB(dst, b, h) do { _Pragma("unroll") for (int n = 0; n < 2; ++n) _Pragma("unroll") for (int k = 0; k < 2; ++k) dst[n][k] = *(const PG8_LAS bf16x8*)(lds + PG8_SB(b, h) + boff + n * 2048 + k * 1024); } while (0)
; #define PG8_MMA(ai, bj, At, Bt) do { __builtin_amdgcn_s_setprio(1); _Pragma("unroll") for (int m = 0; m < 4; ++m) _Pragma("unroll") for (int n = 0; n < 2; ++n) _Pragma("unroll") for (int k = 0; k < 2; ++k) \
;         acc[ai][bj][m][n] = __builtin_amdgcn_mfma_f32_16x16x32_bf16(Bt[n][k], At[m][k], acc[ai][bj][m][n], 0, 0, 0); __builtin_amdgcn_s_setprio(0); } while (0)
; #define PG8_WAIT_V(n) asm volatile("s_waitcnt vmcnt(" #n ")" ::: "memory")
; #define PG8_WAIT_L(n) asm volatile("s_waitcnt lgkmcnt(" #n ")" ::: "memory")
; template <class Epi, class Sched, bool ALIGN_EPI, bool SP2, int KC>
; __device__ __forceinline__ void gemm_phase(PG8_LAS unsigned char* lds, const Gemm g, const Sched& S, const Epi& E, const int tid) {
;     ...
;             const bool last = (t == nt - 2);
;             const char* a1 = cA + (size_t)(t + 1) * kstep;
;             const char* a2 = last ? nA : cA + (size_t)(t + 2) * kstep; const char* b2 = last ? nB : cB + (size_t)(t + 2) * kstep;
;             const char* a3 = a2 + kstep; const char* b3 = b2 + kstep;
;             if (last && has_next) S.a_ready(nxt);
;             if constexpr (SP2) {
;             PG8_LDB(B0, 0, 0); PG8_LDB(B1, 0, 1); PG8_SCHED; PG8_LDA(At, 0, 0); PG8_STAGE(PG8_SA(1, 1), a1 + hstep, voffA);
;             PG8_WAIT_V(8); PG8_WAIT_L(0); PG8_BAR; PG8_MMA(0, 0, At, B0); PG8_MMA(0, 1, At, B1); PG8_BAR; PG8_SCHED;
;             PG8_LDA(At, 0, 1); PG8_STAGE(PG8_SB(0, 0), b2, voffB); PG8_STAGE(PG8_SB(0, 1), b2 + hstep, voffB); PG8_STAGE(PG8_SA(0, 0), a2, voffA);
;             PG8_WAIT_V(8); PG8_WAIT_L(0); PG8_BAR; PG8_MMA(1, 0, At, B0); PG8_MMA(1, 1, At, B1); PG8_BAR; PG8_SCHED;
.LBB0_560:
	s_add_u32 s16, s4, 0x100
	s_addc_u32 s17, s5, 0
	s_add_i32 s49, 0, 0x10000
	s_cmp_eq_u32 s48, 40
	s_cselect_b32 s39, s27, s17
	s_cselect_b32 s38, s26, s16
	s_cselect_b32 s37, s29, s35
	s_cselect_b32 s36, s28, s31
	s_add_i32 s58, 0, 0x14000
	v_add_u32_e32 v146, s49, v212
	v_add_u32_e32 v162, s58, v212
	ds_read_b128 v[128:131], v146
	ds_read_b128 v[132:135], v146 offset:1024
	ds_read_b128 v[142:145], v146 offset:2048
	ds_read_b128 v[146:149], v146 offset:3072
	ds_read_b128 v[150:153], v162
	ds_read_b128 v[154:157], v162 offset:1024
	ds_read_b128 v[158:161], v162 offset:2048
	ds_read_b128 v[174:177], v162 offset:3072
	v_lshl_add_u64 v[162:163], s[4:5], 0, v[138:139]
	s_add_i32 m0, s7, 0xc000
	ds_read_b128 v[178:181], v216
	ds_read_b128 v[182:185], v216 offset:1024
	ds_read_b128 v[186:189], v216 offset:2048
	ds_read_b128 v[190:193], v216 offset:3072
	ds_read_b128 v[194:197], v216 offset:4096
	ds_read_b128 v[198:201], v216 offset:5120
	ds_read_b128 v[202:205], v216 offset:6144
	ds_read_b128 v[206:209], v216 offset:7168
	global_load_lds_dwordx4 v[162:163], off
	v_lshl_add_u64 v[162:163], s[4:5], 0, v[140:141]
	s_add_i32 m0, s7, 0xe000
	s_nop 0
	global_load_lds_dwordx4 v[162:163], off
	s_waitcnt vmcnt(8)
	s_waitcnt lgkmcnt(0)
	s_barrier
	s_setprio 1
	s_waitcnt lgkmcnt(0)
	v_mfma_f32_16x16x32_bf16 v[60:63], v[128:131], v[178:181], v[60:63]
	v_mfma_f32_16x16x32_bf16 v[92:95], v[142:145], v[178:181], v[92:95]
	v_mfma_f32_16x16x32_bf16 v[56:59], v[128:131], v[186:189], v[56:59]
	v_mfma_f32_16x16x32_bf16 v[84:87], v[142:145], v[186:189], v[84:87]
	v_mfma_f32_16x16x32_bf16 v[48:51], v[128:131], v[194:197], v[48:51]
	v_mfma_f32_16x16x32_bf16 v[80:83], v[142:145], v[194:197], v[80:83]
	v_mfma_f32_16x16x32_bf16 v[40:43], v[128:131], v[202:205], v[40:43]
	v_mfma_f32_16x16x32_bf16 v[72:75], v[142:145], v[202:205], v[72:75]
	s_setprio 0
	s_setprio 1
	v_mfma_f32_16x16x32_bf16 v[60:63], v[132:135], v[182:185], v[60:63]
	v_mfma_f32_16x16x32_bf16 v[92:95], v[146:149], v[182:185], v[92:95]
	v_mfma_f32_16x16x32_bf16 v[56:59], v[132:135], v[190:193], v[56:59]
	v_mfma_f32_16x16x32_bf16 v[84:87], v[146:149], v[190:193], v[84:87]
	v_mfma_f32_16x16x32_bf16 v[48:51], v[132:135], v[198:201], v[48:51]
	v_mfma_f32_16x16x32_bf16 v[80:83], v[146:149], v[198:201], v[80:83]
	v_mfma_f32_16x16x32_bf16 v[40:43], v[132:135], v[206:209], v[40:43]
	v_mfma_f32_16x16x32_bf16 v[72:75], v[146:149], v[206:209], v[72:75]
	s_setprio 0
	s_setprio 1
	v_mfma_f32_16x16x32_bf16 v[120:123], v[150:153], v[178:181], v[120:123]
	v_mfma_f32_16x16x32_bf16 v[124:127], v[158:161], v[178:181], v[124:127]
	v_mfma_f32_16x16x32_bf16 v[112:115], v[150:153], v[186:189], v[112:115]
	v_mfma_f32_16x16x32_bf16 v[116:119], v[158:161], v[186:189], v[116:119]
	v_mfma_f32_16x16x32_bf16 v[108:111], v[150:153], v[194:197], v[108:111]
	v_mfma_f32_16x16x32_bf16 v[104:107], v[158:161], v[194:197], v[104:107]
	v_mfma_f32_16x16x32_bf16 v[100:103], v[150:153], v[202:205], v[100:103]
	v_mfma_f32_16x16x32_bf16 v[96:99], v[158:161], v[202:205], v[96:99]
	s_setprio 0
	s_setprio 1
	v_mfma_f32_16x16x32_bf16 v[120:123], v[154:157], v[182:185], v[120:123]
	v_mfma_f32_16x16x32_bf16 v[124:127], v[174:177], v[182:185], v[124:127]
	v_mfma_f32_16x16x32_bf16 v[112:115], v[154:157], v[190:193], v[112:115]
	v_mfma_f32_16x16x32_bf16 v[116:119], v[174:177], v[190:193], v[116:119]
	v_mfma_f32_16x16x32_bf16 v[108:111], v[154:157], v[198:201], v[108:111]
	v_mfma_f32_16x16x32_bf16 v[104:107], v[174:177], v[198:201], v[104:107]
	v_mfma_f32_16x16x32_bf16 v[100:103], v[154:157], v[206:209], v[100:103]
	v_mfma_f32_16x16x32_bf16 v[96:99], v[174:177], v[206:209], v[96:99]
	s_setprio 0
	s_barrier
	s_add_i32 s4, s49, s6
	v_lshl_add_u64 v[162:163], s[36:37], 0, v[164:165]
	s_mov_b32 m0, s4
	ds_read_b128 v[178:181], v216 offset:16384
	ds_read_b128 v[182:185], v216 offset:17408
	ds_read_b128 v[186:189], v216 offset:18432
	ds_read_b128 v[190:193], v216 offset:19456
	ds_read_b128 v[194:197], v216 offset:20480
	ds_read_b128 v[198:201], v216 offset:21504
	ds_read_b128 v[202:205], v216 offset:22528
	ds_read_b128 v[206:209], v216 offset:23552
	global_load_lds_dwordx4 v[162:163], off
	s_add_i32 m0, s4, 0x2000
	s_add_u32 s4, s36, 0xb0000
	v_lshl_add_u64 v[210:211], s[36:37], 0, v[136:137]
	s_addc_u32 s5, s37, 0
	s_add_i32 s49, s58, s6
	global_load_lds_dwordx4 v[210:211], off
	v_lshl_add_u64 v[220:221], s[4:5], 0, v[164:165]
	s_mov_b32 m0, s49
	v_lshl_add_u64 v[222:223], s[38:39], 0, v[136:137]
	global_load_lds_dwordx4 v[220:221], off
	v_lshl_add_u64 v[220:221], s[4:5], 0, v[136:137]
	s_add_i32 m0, s49, 0x2000
	s_nop 0
	global_load_lds_dwordx4 v[220:221], off
	v_lshl_add_u64 v[220:221], s[38:39], 0, v[164:165]
	s_mov_b32 m0, s7
	s_nop 0
	global_load_lds_dwordx4 v[220:221], off
	s_mov_b32 m0, s40
	s_nop 0
	global_load_lds_dwordx4 v[222:223], off
	s_waitcnt vmcnt(8)
	s_waitcnt lgkmcnt(0)
	s_barrier
; #define PG8_STAGE(bufoff, gbase, voff) do { _Pragma("unroll") for (int _i = 0; _i < 2; ++_i) \
;         __builtin_amdgcn_global_load_lds((const unsigned*)((const char*)(gbase) + (voff)[_i]), (PG8_LAS unsigned*)(lds + (bufoff) + ldsw + _i * 8192), 16, 0, 0); } while (0)
; #define PG8_LDA(dst, b, h) do { _Pragma("unroll") for (int m = 0; m < 4; ++m) _Pragma("unroll") for (int k = 0; k < 2; ++k) dst[m][k] = *(const PG8_LAS bf16x8*)(lds + PG8_SA(b, h) + aoff + m * 2048 + k * 1024); } while (0)
; #define PG8_LDB(dst, b, h) do { _Pragma("unroll") for (int n = 0; n < 2; ++n) _Pragma("unroll") for (int k = 0; k < 2; ++k) dst[n][k] = *(const PG8_LAS bf16x8*)(lds + PG8_SB(b, h) + boff + n * 2048 + k * 1024); } while (0)
; #define PG8_MMA(ai, bj, At, Bt) do { __builtin_amdgcn_s_setprio(1); _Pragma("unroll") for (int m = 0; m < 4; ++m) _Pragma("unroll") for (int n = 0; n < 2; ++n) _Pragma("unroll") for (int k = 0; k < 2; ++k) \
;         acc[ai][bj][m][n] = __builtin_amdgcn_mfma_f32_16x16x32_bf16(Bt[n][k], At[m][k], acc[ai][bj][m][n], 0, 0, 0); __builtin_amdgcn_s_setprio(0); } while (0)
; #define PG8_WAIT_V(n) asm volatile("s_waitcnt vmcnt(" #n ")" ::: "memory")
; #define PG8_WAIT_L(n) asm volatile("s_waitcnt lgkmcnt(" #n ")" ::: "memory")
; #define PG8_BAR __builtin_amdgcn_s_barrier()
; #define PG8_SCHED __builtin_amdgcn_sched_barrier(0)
; template <class Epi, class Sched, bool ALIGN_EPI, bool SP2, int KC>
; __device__ __forceinline__ void gemm_phase(PG8_LAS unsigned char* lds, const Gemm g, const Sched& S, const Epi& E, const int tid) {
;     ...
;             PG8_WAIT_V(8); PG8_WAIT_L(0); PG8_BAR; PG8_MMA(1, 0, At, B0); PG8_MMA(1, 1, At, B1); PG8_BAR; PG8_SCHED;
;             PG8_LDB(B0, 1, 0); PG8_LDB(B1, 1, 1); PG8_SCHED; PG8_LDA(At, 1, 0); PG8_STAGE(PG8_SA(0, 1), a2 + hstep, voffA);
;             PG8_WAIT_V(8); PG8_WAIT_L(0); PG8_BAR; PG8_MMA(0, 0, At, B0); PG8_MMA(0, 1, At, B1); PG8_BAR; PG8_SCHED;
	s_setprio 1
	s_waitcnt lgkmcnt(0)
	v_mfma_f32_16x16x32_bf16 v[88:91], v[128:131], v[178:181], v[88:91]
	v_mfma_f32_16x16x32_bf16 v[52:55], v[142:145], v[178:181], v[52:55]
	v_mfma_f32_16x16x32_bf16 v[76:79], v[128:131], v[186:189], v[76:79]
	v_mfma_f32_16x16x32_bf16 v[44:47], v[142:145], v[186:189], v[44:47]
	v_mfma_f32_16x16x32_bf16 v[68:71], v[128:131], v[194:197], v[68:71]
	v_mfma_f32_16x16x32_bf16 v[36:39], v[142:145], v[194:197], v[36:39]
	v_mfma_f32_16x16x32_bf16 v[64:67], v[128:131], v[202:205], v[64:67]
	v_mfma_f32_16x16x32_bf16 v[32:35], v[142:145], v[202:205], v[32:35]
	s_setprio 0
	s_setprio 1
	v_mfma_f32_16x16x32_bf16 v[88:91], v[132:135], v[182:185], v[88:91]
	v_mfma_f32_16x16x32_bf16 v[52:55], v[146:149], v[182:185], v[52:55]
	v_mfma_f32_16x16x32_bf16 v[76:79], v[132:135], v[190:193], v[76:79]
	v_mfma_f32_16x16x32_bf16 v[44:47], v[146:149], v[190:193], v[44:47]
	v_mfma_f32_16x16x32_bf16 v[68:71], v[132:135], v[198:201], v[68:71]
	v_mfma_f32_16x16x32_bf16 v[36:39], v[146:149], v[198:201], v[36:39]
	v_mfma_f32_16x16x32_bf16 v[64:67], v[132:135], v[206:209], v[64:67]
	v_mfma_f32_16x16x32_bf16 v[32:35], v[146:149], v[206:209], v[32:35]
	s_setprio 0
	s_setprio 1
	v_mfma_f32_16x16x32_bf16 v[28:31], v[150:153], v[178:181], v[28:31]
	v_mfma_f32_16x16x32_bf16 v[12:15], v[158:161], v[178:181], v[12:15]
	v_mfma_f32_16x16x32_bf16 v[24:27], v[150:153], v[186:189], v[24:27]
	v_mfma_f32_16x16x32_bf16 v[8:11], v[158:161], v[186:189], v[8:11]
	v_mfma_f32_16x16x32_bf16 v[20:23], v[150:153], v[194:197], v[20:23]
	v_mfma_f32_16x16x32_bf16 v[4:7], v[158:161], v[194:197], v[4:7]
	v_mfma_f32_16x16x32_bf16 v[16:19], v[150:153], v[202:205], v[16:19]
	v_mfma_f32_16x16x32_bf16 v[0:3], v[158:161], v[202:205], v[0:3]
	s_setprio 0
	s_setprio 1
	v_mfma_f32_16x16x32_bf16 v[28:31], v[154:157], v[182:185], v[28:31]
	v_mfma_f32_16x16x32_bf16 v[12:15], v[174:177], v[182:185], v[12:15]
	v_mfma_f32_16x16x32_bf16 v[24:27], v[154:157], v[190:193], v[24:27]
	v_mfma_f32_16x16x32_bf16 v[8:11], v[174:177], v[190:193], v[8:11]
	v_mfma_f32_16x16x32_bf16 v[20:23], v[154:157], v[198:201], v[20:23]
	v_mfma_f32_16x16x32_bf16 v[4:7], v[174:177], v[198:201], v[4:7]
	v_mfma_f32_16x16x32_bf16 v[16:19], v[154:157], v[206:209], v[16:19]
	v_mfma_f32_16x16x32_bf16 v[0:3], v[174:177], v[206:209], v[0:3]
	s_setprio 0
	s_barrier
	s_add_i32 s49, 0, 0x18000
	s_add_i32 s58, 0, 0x1c000
	v_add_u32_e32 v146, s49, v212
	v_add_u32_e32 v174, s58, v212
	ds_read_b128 v[128:131], v146
	ds_read_b128 v[132:135], v146 offset:1024
	ds_read_b128 v[142:145], v146 offset:2048
	ds_read_b128 v[146:149], v146 offset:3072
	ds_read_b128 v[150:153], v174
	ds_read_b128 v[154:157], v174 offset:1024
	ds_read_b128 v[158:161], v174 offset:2048
	ds_read_b128 v[174:177], v174 offset:3072
	s_add_u32 s4, s38, 0xb0000
	s_addc_u32 s5, s39, 0
	s_mov_b32 m0, s41
	v_lshl_add_u64 v[234:235], s[4:5], 0, v[164:165]
	ds_read_b128 v[178:181], v216 offset:32768
	ds_read_b128 v[182:185], v216 offset:33792
	ds_read_b128 v[186:189], v216 offset:34816
	ds_read_b128 v[190:193], v216 offset:35840
	ds_read_b128 v[194:197], v216 offset:36864
	ds_read_b128 v[198:201], v216 offset:37888
	ds_read_b128 v[202:205], v216 offset:38912
	ds_read_b128 v[206:209], v216 offset:39936
	global_load_lds_dwordx4 v[234:235], off
	v_lshl_add_u64 v[234:235], s[4:5], 0, v[136:137]
	s_mov_b32 m0, s42
	s_nop 0
	global_load_lds_dwordx4 v[234:235], off
	s_waitcnt vmcnt(8)
	s_waitcnt lgkmcnt(0)
	s_barrier
	s_setprio 1
	s_waitcnt lgkmcnt(0)
	v_mfma_f32_16x16x32_bf16 v[60:63], v[128:131], v[178:181], v[60:63]
	v_mfma_f32_16x16x32_bf16 v[92:95], v[142:145], v[178:181], v[92:95]
	v_mfma_f32_16x16x32_bf16 v[56:59], v[128:131], v[186:189], v[56:59]
	v_mfma_f32_16x16x32_bf16 v[84:87], v[142:145], v[186:189], v[84:87]
	v_mfma_f32_16x16x32_bf16 v[48:51], v[128:131], v[194:197], v[48:51]
	v_mfma_f32_16x16x32_bf16 v[80:83], v[142:145], v[194:197], v[80:83]
	v_mfma_f32_16x16x32_bf16 v[40:43], v[128:131], v[202:205], v[40:43]
	v_mfma_f32_16x16x32_bf16 v[72:75], v[142:145], v[202:205], v[72:75]
	s_setprio 0
	s_setprio 1
	v_mfma_f32_16x16x32_bf16 v[60:63], v[132:135], v[182:185], v[60:63]
	v_mfma_f32_16x16x32_bf16 v[92:95], v[146:149], v[182:185], v[92:95]
	v_mfma_f32_16x16x32_bf16 v[56:59], v[132:135], v[190:193], v[56:59]
	v_mfma_f32_16x16x32_bf16 v[84:87], v[146:149], v[190:193], v[84:87]
	v_mfma_f32_16x16x32_bf16 v[48:51], v[132:135], v[198:201], v[48:51]
	v_mfma_f32_16x16x32_bf16 v[80:83], v[146:149], v[198:201], v[80:83]
	v_mfma_f32_16x16x32_bf16 v[40:43], v[132:135], v[206:209], v[40:43]
	v_mfma_f32_16x16x32_bf16 v[72:75], v[146:149], v[206:209], v[72:75]
	s_setprio 0
	s_setprio 1
	v_mfma_f32_16x16x32_bf16 v[120:123], v[150:153], v[178:181], v[120:123]
	v_mfma_f32_16x16x32_bf16 v[124:127], v[158:161], v[178:181], v[124:127]
	v_mfma_f32_16x16x32_bf16 v[112:115], v[150:153], v[186:189], v[112:115]
	v_mfma_f32_16x16x32_bf16 v[116:119], v[158:161], v[186:189], v[116:119]
	v_mfma_f32_16x16x32_bf16 v[108:111], v[150:153], v[194:197], v[108:111]
	v_mfma_f32_16x16x32_bf16 v[104:107], v[158:161], v[194:197], v[104:107]
	v_mfma_f32_16x16x32_bf16 v[100:103], v[150:153], v[202:205], v[100:103]
	v_mfma_f32_16x16x32_bf16 v[96:99], v[158:161], v[202:205], v[96:99]
	s_setprio 0
	s_setprio 1
	v_mfma_f32_16x16x32_bf16 v[120:123], v[154:157], v[182:185], v[120:123]
	v_mfma_f32_16x16x32_bf16 v[124:127], v[174:177], v[182:185], v[124:127]
	v_mfma_f32_16x16x32_bf16 v[112:115], v[154:157], v[190:193], v[112:115]
	v_mfma_f32_16x16x32_bf16 v[116:119], v[174:177], v[190:193], v[116:119]
	v_mfma_f32_16x16x32_bf16 v[108:111], v[154:157], v[198:201], v[108:111]
	v_mfma_f32_16x16x32_bf16 v[104:107], v[174:177], v[198:201], v[104:107]
	v_mfma_f32_16x16x32_bf16 v[100:103], v[154:157], v[206:209], v[100:103]
	v_mfma_f32_16x16x32_bf16 v[96:99], v[174:177], v[206:209], v[96:99]
	s_setprio 0
	s_barrier
; #define PG8_STAGE(bufoff, gbase, voff) do { _Pragma("unroll") for (int _i = 0; _i < 2; ++_i) \
;         __builtin_amdgcn_global_load_lds((const unsigned*)((const char*)(gbase) + (voff)[_i]), (PG8_LAS unsigned*)(lds + (bufoff) + ldsw + _i * 8192), 16, 0, 0); } while (0)
; #define PG8_LDA(dst, b, h) do { _Pragma("unroll") for (int m = 0; m < 4; ++m) _Pragma("unroll") for (int k = 0; k < 2; ++k) dst[m][k] = *(const PG8_LAS bf16x8*)(lds + PG8_SA(b, h) + aoff + m * 2048 + k * 1024); } while (0)
; #define PG8_MMA(ai, bj, At, Bt) do { __builtin_amdgcn_s_setprio(1); _Pragma("unroll") for (int m = 0; m < 4; ++m) _Pragma("unroll") for (int n = 0; n < 2; ++n) _Pragma("unroll") for (int k = 0; k < 2; ++k) \
;         acc[ai][bj][m][n] = __builtin_amdgcn_mfma_f32_16x16x32_bf16(Bt[n][k], At[m][k], acc[ai][bj][m][n], 0, 0, 0); __builtin_amdgcn_s_setprio(0); } while (0)
; #define PG8_WAIT_V(n) asm volatile("s_waitcnt vmcnt(" #n ")" ::: "memory")
; #define PG8_WAIT_L(n) asm volatile("s_waitcnt lgkmcnt(" #n ")" ::: "memory")
; #define PG8_BAR __builtin_amdgcn_s_barrier()
; #define PG8_SCHED __builtin_amdgcn_sched_barrier(0)
; template <class Epi, class Sched, bool ALIGN_EPI, bool SP2, int KC>
; __device__ __forceinline__ void gemm_phase(PG8_LAS unsigned char* lds, const Gemm g, const Sched& S, const Epi& E, const int tid) {
;     ...
;             PG8_LDA(At, 1, 1); PG8_STAGE(PG8_SB(1, 0), b3, voffB); PG8_STAGE(PG8_SB(1, 1), b3 + hstep, voffB); PG8_STAGE(PG8_SA(1, 0), a3, voffA);
;             PG8_WAIT_V(8); PG8_WAIT_L(0); PG8_BAR; PG8_MMA(1, 0, At, B0); PG8_MMA(1, 1, At, B1); PG8_BAR; PG8_SCHED;
;     ...
;         if constexpr (ALIGN_EPI) { if (wr == 0) PG8_BAR; }
	s_add_i32 s4, s49, s6
	v_lshl_add_u64 v[162:163], v[162:163], 0, s[86:87]
	s_mov_b32 m0, s4
	ds_read_b128 v[178:181], v216 offset:49152
	ds_read_b128 v[182:185], v216 offset:50176
	ds_read_b128 v[186:189], v216 offset:51200
	ds_read_b128 v[190:193], v216 offset:52224
	ds_read_b128 v[194:197], v216 offset:53248
	ds_read_b128 v[198:201], v216 offset:54272
	ds_read_b128 v[202:205], v216 offset:55296
	ds_read_b128 v[206:209], v216 offset:56320
	global_load_lds_dwordx4 v[162:163], off
	s_add_i32 m0, s4, 0x2000
	s_add_u32 s4, s36, 0xb0080
	v_lshl_add_u64 v[162:163], v[210:211], 0, s[86:87]
	s_addc_u32 s5, s37, 0
	s_add_i32 s36, s58, s6
	global_load_lds_dwordx4 v[162:163], off
	v_lshl_add_u64 v[162:163], s[4:5], 0, v[164:165]
	s_mov_b32 m0, s36
	s_nop 0
	global_load_lds_dwordx4 v[162:163], off
	v_lshl_add_u64 v[162:163], s[4:5], 0, v[136:137]
	s_add_i32 m0, s36, 0x2000
	s_nop 0
	global_load_lds_dwordx4 v[162:163], off
	v_lshl_add_u64 v[162:163], v[220:221], 0, s[86:87]
	s_mov_b32 m0, s43
	s_nop 0
	global_load_lds_dwordx4 v[162:163], off
	v_lshl_add_u64 v[162:163], v[222:223], 0, s[86:87]
	s_mov_b32 m0, s44
	s_nop 0
	global_load_lds_dwordx4 v[162:163], off
	s_waitcnt vmcnt(8)
	s_waitcnt lgkmcnt(0)
	s_barrier
	s_setprio 1
	s_waitcnt lgkmcnt(0)
	v_mfma_f32_16x16x32_bf16 v[88:91], v[128:131], v[178:181], v[88:91]
	v_mfma_f32_16x16x32_bf16 v[52:55], v[142:145], v[178:181], v[52:55]
	v_mfma_f32_16x16x32_bf16 v[76:79], v[128:131], v[186:189], v[76:79]
	v_mfma_f32_16x16x32_bf16 v[44:47], v[142:145], v[186:189], v[44:47]
	v_mfma_f32_16x16x32_bf16 v[68:71], v[128:131], v[194:197], v[68:71]
	v_mfma_f32_16x16x32_bf16 v[36:39], v[142:145], v[194:197], v[36:39]
	v_mfma_f32_16x16x32_bf16 v[64:67], v[128:131], v[202:205], v[64:67]
	v_mfma_f32_16x16x32_bf16 v[32:35], v[142:145], v[202:205], v[32:35]
	s_setprio 0
	s_setprio 1
	v_mfma_f32_16x16x32_bf16 v[88:91], v[132:135], v[182:185], v[88:91]
	v_mfma_f32_16x16x32_bf16 v[52:55], v[146:149], v[182:185], v[52:55]
	v_mfma_f32_16x16x32_bf16 v[76:79], v[132:135], v[190:193], v[76:79]
	v_mfma_f32_16x16x32_bf16 v[44:47], v[146:149], v[190:193], v[44:47]
	v_mfma_f32_16x16x32_bf16 v[68:71], v[132:135], v[198:201], v[68:71]
	v_mfma_f32_16x16x32_bf16 v[36:39], v[146:149], v[198:201], v[36:39]
	v_mfma_f32_16x16x32_bf16 v[64:67], v[132:135], v[206:209], v[64:67]
	v_mfma_f32_16x16x32_bf16 v[32:35], v[146:149], v[206:209], v[32:35]
	s_setprio 0
	s_setprio 1
	v_mfma_f32_16x16x32_bf16 v[28:31], v[150:153], v[178:181], v[28:31]
	v_mfma_f32_16x16x32_bf16 v[12:15], v[158:161], v[178:181], v[12:15]
	v_mfma_f32_16x16x32_bf16 v[24:27], v[150:153], v[186:189], v[24:27]
	v_mfma_f32_16x16x32_bf16 v[8:11], v[158:161], v[186:189], v[8:11]
	v_mfma_f32_16x16x32_bf16 v[20:23], v[150:153], v[194:197], v[20:23]
	v_mfma_f32_16x16x32_bf16 v[4:7], v[158:161], v[194:197], v[4:7]
	v_mfma_f32_16x16x32_bf16 v[16:19], v[150:153], v[202:205], v[16:19]
	v_mfma_f32_16x16x32_bf16 v[0:3], v[158:161], v[202:205], v[0:3]
	s_setprio 0
	s_setprio 1
	v_mfma_f32_16x16x32_bf16 v[28:31], v[154:157], v[182:185], v[28:31]
	v_mfma_f32_16x16x32_bf16 v[12:15], v[174:177], v[182:185], v[12:15]
	v_mfma_f32_16x16x32_bf16 v[24:27], v[154:157], v[190:193], v[24:27]
	v_mfma_f32_16x16x32_bf16 v[8:11], v[174:177], v[190:193], v[8:11]
	v_mfma_f32_16x16x32_bf16 v[20:23], v[154:157], v[198:201], v[20:23]
	v_mfma_f32_16x16x32_bf16 v[4:7], v[174:177], v[198:201], v[4:7]
	v_mfma_f32_16x16x32_bf16 v[16:19], v[154:157], v[206:209], v[16:19]
	v_mfma_f32_16x16x32_bf16 v[0:3], v[174:177], v[206:209], v[0:3]
	s_setprio 0
	s_barrier
	s_add_i32 s48, s48, 2
	s_add_u32 s31, s31, 0x100
	s_addc_u32 s35, s35, 0
	s_cmp_gt_u32 s48, 41
	s_mov_b64 s[4:5], s[16:17]
	s_cbranch_scc0 .LBB0_560
	s_and_b64 vcc, exec, s[24:25]
	s_cbranch_vccz .LBB0_563
	s_barrier

; #define PG8_STAGE(bufoff, gbase, voff) do { _Pragma("unroll") for (int _i = 0; _i < 2; ++_i) \
;         __builtin_amdgcn_global_load_lds((const unsigned*)((const char*)(gbase) + (voff)[_i]), (PG8_LAS unsigned*)(lds + (bufoff) + ldsw + _i * 8192), 16, 0, 0); } while (0)
; #define PG8_LDA(dst, b, h) do { _Pragma("unroll") for (int m = 0; m < 4; ++m) _Pragma("unroll") for (int k = 0; k < 2; ++k) dst[m][k] = *(const PG8_LAS bf16x8*)(lds + PG8_SA(b, h) + aoff + m * 2048 + k * 1024); } while (0)
; #define PG8_LDB(dst, b, h) do { _Pragma("unroll") for (int n = 0; n < 2; ++n) _Pragma("unroll") for (int k = 0; k < 2; ++k) dst[n][k] = *(const PG8_LAS bf16x8*)(lds + PG8_SB(b, h) + boff + n * 2048 + k * 1024); } while (0)
; #define PG8_MMA(ai, bj, At, Bt) do { __builtin_amdgcn_s_setprio(1); _Pragma("unroll") for (int m = 0; m < 4; ++m) _Pragma("unroll") for (int n = 0; n < 2; ++n) _Pragma("unroll") for (int k = 0; k < 2; ++k) \
;         acc[ai][bj][m][n] = __builtin_amdgcn_mfma_f32_16x16x32_bf16(Bt[n][k], At[m][k], acc[ai][bj][m][n], 0, 0, 0); __builtin_amdgcn_s_setprio(0); } while (0)
; #define PG8_WAIT_V(n) asm volatile("s_waitcnt vmcnt(" #n ")" ::: "memory")
; #define PG8_WAIT_L(n) asm volatile("s_waitcnt lgkmcnt(" #n ")" ::: "memory")
; template <class Epi, class Sched, bool ALIGN_EPI, bool SP2, int KC>
; __device__ __forceinline__ void gemm_phase(PG8_LAS unsigned char* lds, const Gemm g, const Sched& S, const Epi& E, const int tid) {
;     ...
;             const bool last = (t == nt - 2);
;             const char* a1 = cA + (size_t)(t + 1) * kstep;
;             const char* a2 = last ? nA : cA + (size_t)(t + 2) * kstep; const char* b2 = last ? nB : cB + (size_t)(t + 2) * kstep;
;             const char* a3 = a2 + kstep; const char* b3 = b2 + kstep;
;             if (last && has_next) S.a_ready(nxt);
;             if constexpr (SP2) {
;             PG8_LDB(B0, 0, 0); PG8_LDB(B1, 0, 1); PG8_SCHED; PG8_LDA(At, 0, 0); PG8_STAGE(PG8_SA(1, 1), a1 + hstep, voffA);
;             PG8_WAIT_V(8); PG8_WAIT_L(0); PG8_BAR; PG8_MMA(0, 0, At, B0); PG8_MMA(0, 1, At, B1); PG8_BAR; PG8_SCHED;
;             PG8_LDA(At, 0, 1); PG8_STAGE(PG8_SB(0, 0), b2, voffB); PG8_STAGE(PG8_SB(0, 1), b2 + hstep, voffB); PG8_STAGE(PG8_SA(0, 0), a2, voffA);
;             PG8_WAIT_V(8); PG8_WAIT_L(0); PG8_BAR; PG8_MMA(1, 0, At, B0); PG8_MMA(1, 1, At, B1); PG8_BAR; PG8_SCHED;
.LBB0_730:
	s_add_u32 s22, s4, 0xfffc0080
	s_addc_u32 s23, s5, -1
	s_add_i32 s41, 0, 0x10000
	s_cmp_eq_u32 s40, 12
	s_cselect_b32 s25, s17, s23
	s_cselect_b32 s24, s36, s22
	s_cselect_b32 s23, s15, s39
	s_cselect_b32 s22, s37, s38
	s_add_i32 s44, 0, 0x14000
	v_add_u32_e32 v140, s41, v223
	v_add_u32_e32 v156, s44, v223
	ds_read_b128 v[128:131], v140
	ds_read_b128 v[132:135], v140 offset:1024
	ds_read_b128 v[136:139], v140 offset:2048
	ds_read_b128 v[140:143], v140 offset:3072
	ds_read_b128 v[144:147], v156
	ds_read_b128 v[148:151], v156 offset:1024
	ds_read_b128 v[152:155], v156 offset:2048
	ds_read_b128 v[156:159], v156 offset:3072
	v_lshl_add_u64 v[214:215], s[4:5], 0, v[182:183]
	s_add_i32 m0, s7, 0xc000
	ds_read_b128 v[160:163], v234
	s_waitcnt vmcnt(0)
	ds_read_b128 v[186:189], v234 offset:1024
	ds_read_b128 v[190:193], v234 offset:2048
	ds_read_b128 v[194:197], v234 offset:3072
	ds_read_b128 v[198:201], v234 offset:4096
	ds_read_b128 v[202:205], v234 offset:5120
	ds_read_b128 v[206:209], v234 offset:6144
	ds_read_b128 v[210:213], v234 offset:7168
	global_load_lds_dwordx4 v[214:215], off
	v_lshl_add_u64 v[214:215], s[4:5], 0, v[184:185]
	s_add_i32 m0, s7, 0xe000
	s_nop 0
	global_load_lds_dwordx4 v[214:215], off
	s_waitcnt vmcnt(8)
	s_waitcnt lgkmcnt(0)
	s_barrier
	s_setprio 1
	s_waitcnt lgkmcnt(0)
	v_mfma_f32_16x16x32_bf16 v[124:127], v[128:131], v[160:163], v[124:127]
	v_mfma_f32_16x16x32_bf16 v[120:123], v[136:139], v[160:163], v[120:123]
	v_mfma_f32_16x16x32_bf16 v[116:119], v[128:131], v[190:193], v[116:119]
	v_mfma_f32_16x16x32_bf16 v[112:115], v[136:139], v[190:193], v[112:115]
	v_mfma_f32_16x16x32_bf16 v[108:111], v[128:131], v[198:201], v[108:111]
	v_mfma_f32_16x16x32_bf16 v[104:107], v[136:139], v[198:201], v[104:107]
	v_mfma_f32_16x16x32_bf16 v[100:103], v[128:131], v[206:209], v[100:103]
	v_mfma_f32_16x16x32_bf16 v[96:99], v[136:139], v[206:209], v[96:99]
	s_setprio 0
	s_setprio 1
	v_mfma_f32_16x16x32_bf16 v[124:127], v[132:135], v[186:189], v[124:127]
	v_mfma_f32_16x16x32_bf16 v[120:123], v[140:143], v[186:189], v[120:123]
	v_mfma_f32_16x16x32_bf16 v[116:119], v[132:135], v[194:197], v[116:119]
	v_mfma_f32_16x16x32_bf16 v[112:115], v[140:143], v[194:197], v[112:115]
	v_mfma_f32_16x16x32_bf16 v[108:111], v[132:135], v[202:205], v[108:111]
	v_mfma_f32_16x16x32_bf16 v[104:107], v[140:143], v[202:205], v[104:107]
	v_mfma_f32_16x16x32_bf16 v[100:103], v[132:135], v[210:213], v[100:103]
	v_mfma_f32_16x16x32_bf16 v[96:99], v[140:143], v[210:213], v[96:99]
	s_setprio 0
	s_setprio 1
	v_mfma_f32_16x16x32_bf16 v[68:71], v[144:147], v[160:163], v[68:71]
	v_mfma_f32_16x16x32_bf16 v[56:59], v[152:155], v[160:163], v[56:59]
	v_mfma_f32_16x16x32_bf16 v[52:55], v[144:147], v[190:193], v[52:55]
	v_mfma_f32_16x16x32_bf16 v[48:51], v[152:155], v[190:193], v[48:51]
	v_mfma_f32_16x16x32_bf16 v[44:47], v[144:147], v[198:201], v[44:47]
	v_mfma_f32_16x16x32_bf16 v[40:43], v[152:155], v[198:201], v[40:43]
	v_mfma_f32_16x16x32_bf16 v[36:39], v[144:147], v[206:209], v[36:39]
	v_mfma_f32_16x16x32_bf16 v[32:35], v[152:155], v[206:209], v[32:35]
	s_setprio 0
	s_setprio 1
	v_mfma_f32_16x16x32_bf16 v[68:71], v[148:151], v[186:189], v[68:71]
	v_mfma_f32_16x16x32_bf16 v[56:59], v[156:159], v[186:189], v[56:59]
	v_mfma_f32_16x16x32_bf16 v[52:55], v[148:151], v[194:197], v[52:55]
	v_mfma_f32_16x16x32_bf16 v[48:51], v[156:159], v[194:197], v[48:51]
	v_mfma_f32_16x16x32_bf16 v[44:47], v[148:151], v[202:205], v[44:47]
	v_mfma_f32_16x16x32_bf16 v[40:43], v[156:159], v[202:205], v[40:43]
	v_mfma_f32_16x16x32_bf16 v[36:39], v[148:151], v[210:213], v[36:39]
	v_mfma_f32_16x16x32_bf16 v[32:35], v[156:159], v[210:213], v[32:35]
	s_setprio 0
	s_barrier
	s_add_i32 s41, s41, s6
	v_lshl_add_u64 v[214:215], s[22:23], 0, v[178:179]
	s_mov_b32 m0, s41
	ds_read_b128 v[160:163], v234 offset:16384
	ds_read_b128 v[186:189], v234 offset:17408
	ds_read_b128 v[190:193], v234 offset:18432
	ds_read_b128 v[194:197], v234 offset:19456
	ds_read_b128 v[198:201], v234 offset:20480
	ds_read_b128 v[202:205], v234 offset:21504
	ds_read_b128 v[206:209], v234 offset:22528
	ds_read_b128 v[210:213], v234 offset:23552
	global_load_lds_dwordx4 v[214:215], off
	s_add_i32 m0, s41, 0x2000
	s_add_u32 s42, s22, 0x40000
	v_lshl_add_u64 v[216:217], s[22:23], 0, v[174:175]
	s_addc_u32 s43, s23, 0
	s_add_i32 s41, s44, s6
	global_load_lds_dwordx4 v[216:217], off
	v_lshl_add_u64 v[218:219], s[42:43], 0, v[178:179]
	s_mov_b32 m0, s41
	v_lshl_add_u64 v[220:221], s[24:25], 0, v[176:177]
	global_load_lds_dwordx4 v[218:219], off
	v_lshl_add_u64 v[218:219], s[42:43], 0, v[174:175]
	s_add_i32 m0, s41, 0x2000
	s_nop 0
	global_load_lds_dwordx4 v[218:219], off
	v_lshl_add_u64 v[218:219], s[24:25], 0, v[180:181]
	s_mov_b32 m0, s7
	s_nop 0
	global_load_lds_dwordx4 v[218:219], off
	s_mov_b32 m0, s26
	s_nop 0
	global_load_lds_dwordx4 v[220:221], off
	s_waitcnt vmcnt(8)
	s_waitcnt lgkmcnt(0)
	s_barrier
; #define PG8_STAGE(bufoff, gbase, voff) do { _Pragma("unroll") for (int _i = 0; _i < 2; ++_i) \
;         __builtin_amdgcn_global_load_lds((const unsigned*)((const char*)(gbase) + (voff)[_i]), (PG8_LAS unsigned*)(lds + (bufoff) + ldsw + _i * 8192), 16, 0, 0); } while (0)
; #define PG8_LDA(dst, b, h) do { _Pragma("unroll") for (int m = 0; m < 4; ++m) _Pragma("unroll") for (int k = 0; k < 2; ++k) dst[m][k] = *(const PG8_LAS bf16x8*)(lds + PG8_SA(b, h) + aoff + m * 2048 + k * 1024); } while (0)
; #define PG8_LDB(dst, b, h) do { _Pragma("unroll") for (int n = 0; n < 2; ++n) _Pragma("unroll") for (int k = 0; k < 2; ++k) dst[n][k] = *(const PG8_LAS bf16x8*)(lds + PG8_SB(b, h) + boff + n * 2048 + k * 1024); } while (0)
; #define PG8_MMA(ai, bj, At, Bt) do { __builtin_amdgcn_s_setprio(1); _Pragma("unroll") for (int m = 0; m < 4; ++m) _Pragma("unroll") for (int n = 0; n < 2; ++n) _Pragma("unroll") for (int k = 0; k < 2; ++k) \
;         acc[ai][bj][m][n] = __builtin_amdgcn_mfma_f32_16x16x32_bf16(Bt[n][k], At[m][k], acc[ai][bj][m][n], 0, 0, 0); __builtin_amdgcn_s_setprio(0); } while (0)
; #define PG8_WAIT_V(n) asm volatile("s_waitcnt vmcnt(" #n ")" ::: "memory")
; #define PG8_WAIT_L(n) asm volatile("s_waitcnt lgkmcnt(" #n ")" ::: "memory")
; #define PG8_BAR __builtin_amdgcn_s_barrier()
; #define PG8_SCHED __builtin_amdgcn_sched_barrier(0)
; template <class Epi, class Sched, bool ALIGN_EPI, bool SP2, int KC>
; __device__ __forceinline__ void gemm_phase(PG8_LAS unsigned char* lds, const Gemm g, const Sched& S, const Epi& E, const int tid) {
;     ...
;             PG8_WAIT_V(8); PG8_WAIT_L(0); PG8_BAR; PG8_MMA(1, 0, At, B0); PG8_MMA(1, 1, At, B1); PG8_BAR; PG8_SCHED;
;             PG8_LDB(B0, 1, 0); PG8_LDB(B1, 1, 1); PG8_SCHED; PG8_LDA(At, 1, 0); PG8_STAGE(PG8_SA(0, 1), a2 + hstep, voffA);
;             PG8_WAIT_V(8); PG8_WAIT_L(0); PG8_BAR; PG8_MMA(0, 0, At, B0); PG8_MMA(0, 1, At, B1); PG8_BAR; PG8_SCHED;
	s_setprio 1
	s_waitcnt lgkmcnt(0)
	v_mfma_f32_16x16x32_bf16 v[92:95], v[128:131], v[160:163], v[92:95]
	v_mfma_f32_16x16x32_bf16 v[88:91], v[136:139], v[160:163], v[88:91]
	v_mfma_f32_16x16x32_bf16 v[84:87], v[128:131], v[190:193], v[84:87]
	v_mfma_f32_16x16x32_bf16 v[80:83], v[136:139], v[190:193], v[80:83]
	v_mfma_f32_16x16x32_bf16 v[76:79], v[128:131], v[198:201], v[76:79]
	v_mfma_f32_16x16x32_bf16 v[72:75], v[136:139], v[198:201], v[72:75]
	v_mfma_f32_16x16x32_bf16 v[64:67], v[128:131], v[206:209], v[64:67]
	v_mfma_f32_16x16x32_bf16 v[60:63], v[136:139], v[206:209], v[60:63]
	s_setprio 0
	s_setprio 1
	v_mfma_f32_16x16x32_bf16 v[92:95], v[132:135], v[186:189], v[92:95]
	v_mfma_f32_16x16x32_bf16 v[88:91], v[140:143], v[186:189], v[88:91]
	v_mfma_f32_16x16x32_bf16 v[84:87], v[132:135], v[194:197], v[84:87]
	v_mfma_f32_16x16x32_bf16 v[80:83], v[140:143], v[194:197], v[80:83]
	v_mfma_f32_16x16x32_bf16 v[76:79], v[132:135], v[202:205], v[76:79]
	v_mfma_f32_16x16x32_bf16 v[72:75], v[140:143], v[202:205], v[72:75]
	v_mfma_f32_16x16x32_bf16 v[64:67], v[132:135], v[210:213], v[64:67]
	v_mfma_f32_16x16x32_bf16 v[60:63], v[140:143], v[210:213], v[60:63]
	s_setprio 0
	s_setprio 1
	v_mfma_f32_16x16x32_bf16 v[28:31], v[144:147], v[160:163], v[28:31]
	v_mfma_f32_16x16x32_bf16 v[24:27], v[152:155], v[160:163], v[24:27]
	v_mfma_f32_16x16x32_bf16 v[20:23], v[144:147], v[190:193], v[20:23]
	v_mfma_f32_16x16x32_bf16 v[16:19], v[152:155], v[190:193], v[16:19]
	v_mfma_f32_16x16x32_bf16 v[12:15], v[144:147], v[198:201], v[12:15]
	v_mfma_f32_16x16x32_bf16 v[8:11], v[152:155], v[198:201], v[8:11]
	v_mfma_f32_16x16x32_bf16 v[4:7], v[144:147], v[206:209], v[4:7]
	v_mfma_f32_16x16x32_bf16 v[0:3], v[152:155], v[206:209], v[0:3]
	s_setprio 0
	s_setprio 1
	v_mfma_f32_16x16x32_bf16 v[28:31], v[148:151], v[186:189], v[28:31]
	v_mfma_f32_16x16x32_bf16 v[24:27], v[156:159], v[186:189], v[24:27]
	v_mfma_f32_16x16x32_bf16 v[20:23], v[148:151], v[194:197], v[20:23]
	v_mfma_f32_16x16x32_bf16 v[16:19], v[156:159], v[194:197], v[16:19]
	v_mfma_f32_16x16x32_bf16 v[12:15], v[148:151], v[202:205], v[12:15]
	v_mfma_f32_16x16x32_bf16 v[8:11], v[156:159], v[202:205], v[8:11]
	v_mfma_f32_16x16x32_bf16 v[4:7], v[148:151], v[210:213], v[4:7]
	v_mfma_f32_16x16x32_bf16 v[0:3], v[156:159], v[210:213], v[0:3]
	s_setprio 0
	s_barrier
	s_add_i32 s41, 0, 0x18000
	s_add_i32 s42, 0, 0x1c000
	v_add_u32_e32 v140, s41, v223
	v_add_u32_e32 v156, s42, v223
	ds_read_b128 v[128:131], v140
	ds_read_b128 v[132:135], v140 offset:1024
	ds_read_b128 v[136:139], v140 offset:2048
	ds_read_b128 v[140:143], v140 offset:3072
	ds_read_b128 v[144:147], v156
	ds_read_b128 v[148:151], v156 offset:1024
	ds_read_b128 v[152:155], v156 offset:2048
	ds_read_b128 v[156:159], v156 offset:3072
	s_add_u32 s24, s24, 0x40000
	s_addc_u32 s25, s25, 0
	s_mov_b32 m0, s27
	v_lshl_add_u64 v[236:237], s[24:25], 0, v[180:181]
	ds_read_b128 v[160:163], v234 offset:32768
	ds_read_b128 v[186:189], v234 offset:33792
	ds_read_b128 v[190:193], v234 offset:34816
	ds_read_b128 v[194:197], v234 offset:35840
	ds_read_b128 v[198:201], v234 offset:36864
	ds_read_b128 v[202:205], v234 offset:37888
	ds_read_b128 v[206:209], v234 offset:38912
	ds_read_b128 v[210:213], v234 offset:39936
	global_load_lds_dwordx4 v[236:237], off
	v_lshl_add_u64 v[236:237], s[24:25], 0, v[176:177]
	s_mov_b32 m0, s28
	s_nop 0
	global_load_lds_dwordx4 v[236:237], off
	s_waitcnt vmcnt(8)
	s_waitcnt lgkmcnt(0)
	s_barrier
	s_setprio 1
	s_waitcnt lgkmcnt(0)
	v_mfma_f32_16x16x32_bf16 v[124:127], v[128:131], v[160:163], v[124:127]
	v_mfma_f32_16x16x32_bf16 v[120:123], v[136:139], v[160:163], v[120:123]
	v_mfma_f32_16x16x32_bf16 v[116:119], v[128:131], v[190:193], v[116:119]
	v_mfma_f32_16x16x32_bf16 v[112:115], v[136:139], v[190:193], v[112:115]
	v_mfma_f32_16x16x32_bf16 v[108:111], v[128:131], v[198:201], v[108:111]
	v_mfma_f32_16x16x32_bf16 v[104:107], v[136:139], v[198:201], v[104:107]
	v_mfma_f32_16x16x32_bf16 v[100:103], v[128:131], v[206:209], v[100:103]
	v_mfma_f32_16x16x32_bf16 v[96:99], v[136:139], v[206:209], v[96:99]
	s_setprio 0
	s_setprio 1
	v_mfma_f32_16x16x32_bf16 v[124:127], v[132:135], v[186:189], v[124:127]
	v_mfma_f32_16x16x32_bf16 v[120:123], v[140:143], v[186:189], v[120:123]
	v_mfma_f32_16x16x32_bf16 v[116:119], v[132:135], v[194:197], v[116:119]
	v_mfma_f32_16x16x32_bf16 v[112:115], v[140:143], v[194:197], v[112:115]
	v_mfma_f32_16x16x32_bf16 v[108:111], v[132:135], v[202:205], v[108:111]
	v_mfma_f32_16x16x32_bf16 v[104:107], v[140:143], v[202:205], v[104:107]
	v_mfma_f32_16x16x32_bf16 v[100:103], v[132:135], v[210:213], v[100:103]
	v_mfma_f32_16x16x32_bf16 v[96:99], v[140:143], v[210:213], v[96:99]
	s_setprio 0
	s_setprio 1
	v_mfma_f32_16x16x32_bf16 v[68:71], v[144:147], v[160:163], v[68:71]
	v_mfma_f32_16x16x32_bf16 v[56:59], v[152:155], v[160:163], v[56:59]
	v_mfma_f32_16x16x32_bf16 v[52:55], v[144:147], v[190:193], v[52:55]
	v_mfma_f32_16x16x32_bf16 v[48:51], v[152:155], v[190:193], v[48:51]
	v_mfma_f32_16x16x32_bf16 v[44:47], v[144:147], v[198:201], v[44:47]
	v_mfma_f32_16x16x32_bf16 v[40:43], v[152:155], v[198:201], v[40:43]
	v_mfma_f32_16x16x32_bf16 v[36:39], v[144:147], v[206:209], v[36:39]
	v_mfma_f32_16x16x32_bf16 v[32:35], v[152:155], v[206:209], v[32:35]
	s_setprio 0
	s_setprio 1
	v_mfma_f32_16x16x32_bf16 v[68:71], v[148:151], v[186:189], v[68:71]
	v_mfma_f32_16x16x32_bf16 v[56:59], v[156:159], v[186:189], v[56:59]
	v_mfma_f32_16x16x32_bf16 v[52:55], v[148:151], v[194:197], v[52:55]
	v_mfma_f32_16x16x32_bf16 v[48:51], v[156:159], v[194:197], v[48:51]
	v_mfma_f32_16x16x32_bf16 v[44:47], v[148:151], v[202:205], v[44:47]
	v_mfma_f32_16x16x32_bf16 v[40:43], v[156:159], v[202:205], v[40:43]
	v_mfma_f32_16x16x32_bf16 v[36:39], v[148:151], v[210:213], v[36:39]
	v_mfma_f32_16x16x32_bf16 v[32:35], v[156:159], v[210:213], v[32:35]
	s_setprio 0
	s_barrier
; #define PG8_STAGE(bufoff, gbase, voff) do { _Pragma("unroll") for (int _i = 0; _i < 2; ++_i) \
;         __builtin_amdgcn_global_load_lds((const unsigned*)((const char*)(gbase) + (voff)[_i]), (PG8_LAS unsigned*)(lds + (bufoff) + ldsw + _i * 8192), 16, 0, 0); } while (0)
; #define PG8_LDA(dst, b, h) do { _Pragma("unroll") for (int m = 0; m < 4; ++m) _Pragma("unroll") for (int k = 0; k < 2; ++k) dst[m][k] = *(const PG8_LAS bf16x8*)(lds + PG8_SA(b, h) + aoff + m * 2048 + k * 1024); } while (0)
; #define PG8_MMA(ai, bj, At, Bt) do { __builtin_amdgcn_s_setprio(1); _Pragma("unroll") for (int m = 0; m < 4; ++m) _Pragma("unroll") for (int n = 0; n < 2; ++n) _Pragma("unroll") for (int k = 0; k < 2; ++k) \
;         acc[ai][bj][m][n] = __builtin_amdgcn_mfma_f32_16x16x32_bf16(Bt[n][k], At[m][k], acc[ai][bj][m][n], 0, 0, 0); __builtin_amdgcn_s_setprio(0); } while (0)
; #define PG8_WAIT_V(n) asm volatile("s_waitcnt vmcnt(" #n ")" ::: "memory")
; #define PG8_WAIT_L(n) asm volatile("s_waitcnt lgkmcnt(" #n ")" ::: "memory")
; #define PG8_BAR __builtin_amdgcn_s_barrier()
; #define PG8_SCHED __builtin_amdgcn_sched_barrier(0)
; template <class Epi, class Sched, bool ALIGN_EPI, bool SP2, int KC>
; __device__ __forceinline__ void gemm_phase(PG8_LAS unsigned char* lds, const Gemm g, const Sched& S, const Epi& E, const int tid) {
;     ...
;             PG8_LDA(At, 1, 1); PG8_STAGE(PG8_SB(1, 0), b3, voffB); PG8_STAGE(PG8_SB(1, 1), b3 + hstep, voffB); PG8_STAGE(PG8_SA(1, 0), a3, voffA);
;             PG8_WAIT_V(8); PG8_WAIT_L(0); PG8_BAR; PG8_MMA(1, 0, At, B0); PG8_MMA(1, 1, At, B1); PG8_BAR; PG8_SCHED;
;     ...
;         if constexpr (ALIGN_EPI) { if (wr == 0) PG8_BAR; }
	s_add_i32 s24, s41, s6
	v_lshl_add_u64 v[214:215], v[214:215], 0, s[86:87]
	s_mov_b32 m0, s24
	ds_read_b128 v[160:163], v234 offset:49152
	ds_read_b128 v[186:189], v234 offset:50176
	ds_read_b128 v[190:193], v234 offset:51200
	ds_read_b128 v[194:197], v234 offset:52224
	ds_read_b128 v[198:201], v234 offset:53248
	ds_read_b128 v[202:205], v234 offset:54272
	ds_read_b128 v[206:209], v234 offset:55296
	ds_read_b128 v[210:213], v234 offset:56320
	global_load_lds_dwordx4 v[214:215], off
	s_add_i32 m0, s24, 0x2000
	s_add_u32 s22, s22, 0x40080
	v_lshl_add_u64 v[214:215], v[216:217], 0, s[86:87]
	s_addc_u32 s23, s23, 0
	s_add_i32 s24, s42, s6
	global_load_lds_dwordx4 v[214:215], off
	v_lshl_add_u64 v[214:215], s[22:23], 0, v[178:179]
	s_mov_b32 m0, s24
	s_nop 0
	global_load_lds_dwordx4 v[214:215], off
	v_lshl_add_u64 v[214:215], s[22:23], 0, v[174:175]
	s_add_i32 m0, s24, 0x2000
	s_nop 0
	global_load_lds_dwordx4 v[214:215], off
	v_lshl_add_u64 v[214:215], v[218:219], 0, s[86:87]
	s_mov_b32 m0, s29
	s_nop 0
	global_load_lds_dwordx4 v[214:215], off
	v_lshl_add_u64 v[214:215], v[220:221], 0, s[86:87]
	s_mov_b32 m0, s30
	s_nop 0
	global_load_lds_dwordx4 v[214:215], off
	s_waitcnt vmcnt(8)
	s_waitcnt lgkmcnt(0)
	s_barrier
	s_setprio 1
	s_waitcnt lgkmcnt(0)
	v_mfma_f32_16x16x32_bf16 v[92:95], v[128:131], v[160:163], v[92:95]
	v_mfma_f32_16x16x32_bf16 v[88:91], v[136:139], v[160:163], v[88:91]
	v_mfma_f32_16x16x32_bf16 v[84:87], v[128:131], v[190:193], v[84:87]
	v_mfma_f32_16x16x32_bf16 v[80:83], v[136:139], v[190:193], v[80:83]
	v_mfma_f32_16x16x32_bf16 v[76:79], v[128:131], v[198:201], v[76:79]
	v_mfma_f32_16x16x32_bf16 v[72:75], v[136:139], v[198:201], v[72:75]
	v_mfma_f32_16x16x32_bf16 v[64:67], v[128:131], v[206:209], v[64:67]
	v_mfma_f32_16x16x32_bf16 v[60:63], v[136:139], v[206:209], v[60:63]
	s_setprio 0
	s_setprio 1
	v_mfma_f32_16x16x32_bf16 v[92:95], v[132:135], v[186:189], v[92:95]
	v_mfma_f32_16x16x32_bf16 v[88:91], v[140:143], v[186:189], v[88:91]
	v_mfma_f32_16x16x32_bf16 v[84:87], v[132:135], v[194:197], v[84:87]
	v_mfma_f32_16x16x32_bf16 v[80:83], v[140:143], v[194:197], v[80:83]
	v_mfma_f32_16x16x32_bf16 v[76:79], v[132:135], v[202:205], v[76:79]
	v_mfma_f32_16x16x32_bf16 v[72:75], v[140:143], v[202:205], v[72:75]
	v_mfma_f32_16x16x32_bf16 v[64:67], v[132:135], v[210:213], v[64:67]
	v_mfma_f32_16x16x32_bf16 v[60:63], v[140:143], v[210:213], v[60:63]
	s_setprio 0
	s_setprio 1
	v_mfma_f32_16x16x32_bf16 v[28:31], v[144:147], v[160:163], v[28:31]
	v_mfma_f32_16x16x32_bf16 v[24:27], v[152:155], v[160:163], v[24:27]
	v_mfma_f32_16x16x32_bf16 v[20:23], v[144:147], v[190:193], v[20:23]
	v_mfma_f32_16x16x32_bf16 v[16:19], v[152:155], v[190:193], v[16:19]
	v_mfma_f32_16x16x32_bf16 v[12:15], v[144:147], v[198:201], v[12:15]
	v_mfma_f32_16x16x32_bf16 v[8:11], v[152:155], v[198:201], v[8:11]
	v_mfma_f32_16x16x32_bf16 v[4:7], v[144:147], v[206:209], v[4:7]
	v_mfma_f32_16x16x32_bf16 v[0:3], v[152:155], v[206:209], v[0:3]
	s_setprio 0
	s_setprio 1
	v_mfma_f32_16x16x32_bf16 v[28:31], v[148:151], v[186:189], v[28:31]
	v_mfma_f32_16x16x32_bf16 v[24:27], v[156:159], v[186:189], v[24:27]
	v_mfma_f32_16x16x32_bf16 v[20:23], v[148:151], v[194:197], v[20:23]
	v_mfma_f32_16x16x32_bf16 v[16:19], v[156:159], v[194:197], v[16:19]
	v_mfma_f32_16x16x32_bf16 v[12:15], v[148:151], v[202:205], v[12:15]
	v_mfma_f32_16x16x32_bf16 v[8:11], v[156:159], v[202:205], v[8:11]
	v_mfma_f32_16x16x32_bf16 v[4:7], v[148:151], v[210:213], v[4:7]
	v_mfma_f32_16x16x32_bf16 v[0:3], v[156:159], v[210:213], v[0:3]
	s_setprio 0
	s_barrier
	s_add_i32 s40, s40, 2
	s_add_u32 s4, s4, 0x100
	s_addc_u32 s5, s5, 0
	s_add_u32 s38, s38, 0x100
	s_addc_u32 s39, s39, 0
	s_cmp_gt_u32 s40, 13
	s_cbranch_scc0 .LBB0_730
	s_and_b64 vcc, exec, s[12:13]
	s_cbranch_vccz .LBB0_733
	s_barrier
